# 4-phase K loop (32 MFMA per barrier interval) in all five GEMM instances + register epilogues for kind 1/10/GLU
# speedup vs baseline: 1.0419x; 1.0186x over previous
; #define WAIT_V(n) asm volatile("s_waitcnt vmcnt(" #n ")" ::: "memory")
; #define BAR __builtin_amdgcn_s_barrier()
; template <int EPI>
; __device__ __forceinline__ void gemm_tile(const GemmArgs& g, int brow, int bcol, int parity, bool first, bool nvalid, int nbrow, int nbcol) {
;     ...
;   if (wr == 1) BAR;
;   if (first) { WAIT_V(4); } else { WAIT_V(0); }
;   BAR;
.LBB0_83:
	s_or_b64 exec, exec, s[18:19]
	s_xor_b64 s[14:15], s[14:15], -1
	s_andn2_b64 vcc, exec, s[14:15]
	s_mov_b64 s[14:15], -1
	s_cbranch_vccnz .LBB0_85
	s_waitcnt vmcnt(2)
	s_mov_b64 s[14:15], 0

; #define STAGE_B(P, br, kt) do { const char* _gb = (const char*)(Bt + ((long)(br) * K + (long)(kt) * BK)); \
;     __builtin_amdgcn_global_load_lds((const unsigned*)(_gb + bofl0), (unsigned*)((char*)(P) + gtid_ * 16), 16, 0, 0); \
;     __builtin_amdgcn_global_load_lds((const unsigned*)(_gb + (long)K * 128 + bofl0), (unsigned*)((char*)(P) + gtid_ * 16 + 8192), 16, 0, 0); } while (0)
; #define LDA(dst, b, h) for (int m = 0; m < 4; ++m) for (int k = 0; k < 2; ++k) \
;     dst[m][k] = *reinterpret_cast<const bf16x8*>((char*)SA(b, h) + lds_byte(wr * 64 + m * 16 + fr, k * 32 + fq * 8))
; #define LDB(dst, b, h) for (int n = 0; n < 2; ++n) for (int k = 0; k < 2; ++k) \
;     dst[n][k] = *reinterpret_cast<const bf16x8*>((char*)SB(b, h) + lds_byte(wc * 32 + n * 16 + fr, k * 32 + fq * 8))
; #define MMA(ai, bj, At_, Bt_) do { __builtin_amdgcn_s_setprio(1); \
;     for (int m = 0; m < 4; ++m) for (int n = 0; n < 2; ++n) for (int k = 0; k < 2; ++k) \
;       acc[ai][bj][m][n] = __builtin_amdgcn_mfma_f32_16x16x32_bf16(At_[m][k], Bt_[n][k], acc[ai][bj][m][n], 0, 0, 0); \
;     __builtin_amdgcn_s_setprio(0); } while (0)
; #define WAIT_V(n) asm volatile("s_waitcnt vmcnt(" #n ")" ::: "memory")
; #define WAIT_L(n) asm volatile("s_waitcnt lgkmcnt(" #n ")" ::: "memory")
; #define BAR __builtin_amdgcn_s_barrier()
; #define SCHED __builtin_amdgcn_sched_barrier(0)
; template <int EPI>
; __device__ __forceinline__ void gemm_tile(const GemmArgs& g, int brow, int bcol, int parity, bool first, bool nvalid, int nbrow, int nbcol) {
;     ...
;   for (int t = 0; t < nt - 2; t += 2) {
;     LDB(B0, 0, 0); SCHED; LDA(At, 0, 0); STAGE_A(SA(1, 1), brow + HALF, t + 1);
;     WAIT_L(8); BAR; WAIT_L(0); MMA(0, 0, At, B0); BAR; SCHED;
;     LDB(B1, 0, 1); STAGE_B(SB(0, 0), bcol, t + 2);
;     BAR; WAIT_L(0); MMA(0, 1, At, B1); BAR; SCHED;
;     LDA(At, 0, 1); STAGE_A(SA(0, 0), brow, t + 2);
;     BAR; WAIT_L(0); MMA(1, 0, At, B0); BAR; SCHED;
;     STAGE_B(SB(0, 1), bcol + HALF, t + 2);
;     WAIT_V(6); BAR; MMA(1, 1, At, B1); BAR; SCHED;
.LBB0_90:
	ds_read_b128 v[164:167], v157
	ds_read_b128 v[168:171], v157 offset:1024
	ds_read_b128 v[172:175], v157 offset:2048
	ds_read_b128 v[176:179], v157 offset:3072
	ds_read_b128 v[180:183], v147
	ds_read_b128 v[184:187], v147 offset:1024
	ds_read_b128 v[188:191], v146
	ds_read_b128 v[192:195], v146 offset:1024
	ds_read_b128 v[196:199], v145
	ds_read_b128 v[202:205], v145 offset:1024
	ds_read_b128 v[206:209], v144
	ds_read_b128 v[216:219], v144 offset:1024
	s_waitcnt lgkmcnt(6)
	ds_read_b128 v[228:231], v154
	ds_read_b128 v[232:235], v154 offset:1024
	ds_read_b128 v[236:239], v154 offset:2048
	ds_read_b128 v[240:243], v154 offset:3072
	v_add_u32_e32 v161, 0xc000, v137
	v_lshl_add_u64 v[210:211], s[0:1], 0, v[130:131]
	v_readfirstlane_b32 s2, v161
	v_add_u32_e32 v162, 0xe000, v137
	v_lshl_add_u64 v[158:159], v[210:211], 0, s[26:27]
	s_mov_b32 m0, s2
	v_readfirstlane_b32 s2, v162
	global_load_lds_dwordx4 v[158:159], off
	v_lshl_add_u64 v[158:159], v[210:211], 0, s[36:37]
	s_mov_b32 m0, s2
	s_nop 0
	global_load_lds_dwordx4 v[158:159], off
	s_waitcnt vmcnt(8)
	s_barrier
	s_waitcnt lgkmcnt(0)
	s_setprio 1
	v_mfma_f32_16x16x32_bf16 v[126:129], v[164:167], v[180:183], v[126:129]
	v_mfma_f32_16x16x32_bf16 v[122:125], v[172:175], v[180:183], v[122:125]
	v_mfma_f32_16x16x32_bf16 v[118:121], v[164:167], v[188:191], v[118:121]
	v_mfma_f32_16x16x32_bf16 v[114:117], v[172:175], v[188:191], v[114:117]
	v_mfma_f32_16x16x32_bf16 v[110:113], v[164:167], v[196:199], v[110:113]
	v_mfma_f32_16x16x32_bf16 v[106:109], v[172:175], v[196:199], v[106:109]
	v_mfma_f32_16x16x32_bf16 v[102:105], v[164:167], v[206:209], v[102:105]
	v_mfma_f32_16x16x32_bf16 v[98:101], v[172:175], v[206:209], v[98:101]
	v_mfma_f32_16x16x32_bf16 v[126:129], v[168:171], v[184:187], v[126:129]
	v_mfma_f32_16x16x32_bf16 v[122:125], v[176:179], v[184:187], v[122:125]
	v_mfma_f32_16x16x32_bf16 v[118:121], v[168:171], v[192:195], v[118:121]
	v_mfma_f32_16x16x32_bf16 v[114:117], v[176:179], v[192:195], v[114:117]
	v_mfma_f32_16x16x32_bf16 v[110:113], v[168:171], v[202:205], v[110:113]
	v_mfma_f32_16x16x32_bf16 v[106:109], v[176:179], v[202:205], v[106:109]
	v_mfma_f32_16x16x32_bf16 v[102:105], v[168:171], v[216:219], v[102:105]
	v_mfma_f32_16x16x32_bf16 v[98:101], v[176:179], v[216:219], v[98:101]
	v_mfma_f32_16x16x32_bf16 v[94:97], v[228:231], v[180:183], v[94:97]
	v_mfma_f32_16x16x32_bf16 v[90:93], v[236:239], v[180:183], v[90:93]
	v_mfma_f32_16x16x32_bf16 v[86:89], v[228:231], v[188:191], v[86:89]
	v_mfma_f32_16x16x32_bf16 v[82:85], v[236:239], v[188:191], v[82:85]
	v_mfma_f32_16x16x32_bf16 v[78:81], v[228:231], v[196:199], v[78:81]
	v_mfma_f32_16x16x32_bf16 v[74:77], v[236:239], v[196:199], v[74:77]
	v_mfma_f32_16x16x32_bf16 v[70:73], v[228:231], v[206:209], v[70:73]
	v_mfma_f32_16x16x32_bf16 v[66:69], v[236:239], v[206:209], v[66:69]
	v_mfma_f32_16x16x32_bf16 v[94:97], v[232:235], v[184:187], v[94:97]
	v_mfma_f32_16x16x32_bf16 v[90:93], v[240:243], v[184:187], v[90:93]
	v_mfma_f32_16x16x32_bf16 v[86:89], v[232:235], v[192:195], v[86:89]
	v_mfma_f32_16x16x32_bf16 v[82:85], v[240:243], v[192:195], v[82:85]
	v_mfma_f32_16x16x32_bf16 v[78:81], v[232:235], v[202:205], v[78:81]
	v_mfma_f32_16x16x32_bf16 v[74:77], v[240:243], v[202:205], v[74:77]
	v_mfma_f32_16x16x32_bf16 v[70:73], v[232:235], v[216:219], v[70:73]
	v_mfma_f32_16x16x32_bf16 v[66:69], v[240:243], v[216:219], v[66:69]
	s_setprio 0
	s_barrier
	ds_read_b128 v[180:183], v147 offset:16384
	ds_read_b128 v[184:187], v147 offset:17408
	ds_read_b128 v[188:191], v146 offset:16384
	ds_read_b128 v[192:195], v146 offset:17408
	ds_read_b128 v[196:199], v145 offset:16384
	ds_read_b128 v[202:205], v145 offset:17408
	ds_read_b128 v[206:209], v144 offset:16384
	ds_read_b128 v[216:219], v144 offset:17408
	v_lshl_add_u64 v[212:213], s[12:13], 0, v[130:131]
	s_mov_b64 s[2:3], 0x900100
	v_add_u32_e32 v158, s14, v142
	v_lshl_add_u64 v[222:223], v[212:213], 0, s[2:3]
	v_readfirstlane_b32 s2, v158
	s_mov_b32 m0, s2
	s_mov_b64 s[2:3], 0x920100
	v_add_u32_e32 v159, 0x2000, v158
	global_load_lds_dwordx4 v[222:223], off
	v_lshl_add_u64 v[222:223], v[212:213], 0, s[2:3]
	v_readfirstlane_b32 s2, v159
	s_mov_b32 m0, s2
	s_nop 0
	global_load_lds_dwordx4 v[222:223], off
	v_readfirstlane_b32 s2, v137
	v_lshl_add_u64 v[222:223], v[210:211], 0, s[40:41]
	s_mov_b32 m0, s2
	v_readfirstlane_b32 s2, v136
	global_load_lds_dwordx4 v[222:223], off
	v_lshl_add_u64 v[222:223], v[210:211], 0, s[44:45]
	s_mov_b32 m0, s2
	s_nop 0
	global_load_lds_dwordx4 v[222:223], off
	s_mov_b64 s[2:3], 0x940100
	v_lshl_add_u64 v[244:245], v[212:213], 0, s[2:3]
	v_readfirstlane_b32 s2, v135
	s_mov_b32 m0, s2
	s_mov_b64 s[2:3], 0x960100
	v_add_u32_e32 v160, 0x2000, v135
	global_load_lds_dwordx4 v[244:245], off
	v_lshl_add_u64 v[244:245], v[212:213], 0, s[2:3]
	v_readfirstlane_b32 s2, v160
	s_mov_b32 m0, s2
	s_nop 0
	global_load_lds_dwordx4 v[244:245], off
	s_waitcnt vmcnt(8)
	s_barrier
; #define STAGE_B(P, br, kt) do { const char* _gb = (const char*)(Bt + ((long)(br) * K + (long)(kt) * BK)); \
;     __builtin_amdgcn_global_load_lds((const unsigned*)(_gb + bofl0), (unsigned*)((char*)(P) + gtid_ * 16), 16, 0, 0); \
;     __builtin_amdgcn_global_load_lds((const unsigned*)(_gb + (long)K * 128 + bofl0), (unsigned*)((char*)(P) + gtid_ * 16 + 8192), 16, 0, 0); } while (0)
; #define LDA(dst, b, h) for (int m = 0; m < 4; ++m) for (int k = 0; k < 2; ++k) \
;     dst[m][k] = *reinterpret_cast<const bf16x8*>((char*)SA(b, h) + lds_byte(wr * 64 + m * 16 + fr, k * 32 + fq * 8))
; #define LDB(dst, b, h) for (int n = 0; n < 2; ++n) for (int k = 0; k < 2; ++k) \
;     dst[n][k] = *reinterpret_cast<const bf16x8*>((char*)SB(b, h) + lds_byte(wc * 32 + n * 16 + fr, k * 32 + fq * 8))
; #define MMA(ai, bj, At_, Bt_) do { __builtin_amdgcn_s_setprio(1); \
;     for (int m = 0; m < 4; ++m) for (int n = 0; n < 2; ++n) for (int k = 0; k < 2; ++k) \
;       acc[ai][bj][m][n] = __builtin_amdgcn_mfma_f32_16x16x32_bf16(At_[m][k], Bt_[n][k], acc[ai][bj][m][n], 0, 0, 0); \
;     __builtin_amdgcn_s_setprio(0); } while (0)
; #define WAIT_V(n) asm volatile("s_waitcnt vmcnt(" #n ")" ::: "memory")
; #define WAIT_L(n) asm volatile("s_waitcnt lgkmcnt(" #n ")" ::: "memory")
; #define BAR __builtin_amdgcn_s_barrier()
; #define SCHED __builtin_amdgcn_sched_barrier(0)
; template <int EPI>
; __device__ __forceinline__ void gemm_tile(const GemmArgs& g, int brow, int bcol, int parity, bool first, bool nvalid, int nbrow, int nbcol) {
;     ...
;     STAGE_B(SB(0, 1), bcol + HALF, t + 2);
;     WAIT_V(6); BAR; MMA(1, 1, At, B1); BAR; SCHED;
;     LDB(B0, 1, 0); SCHED; LDA(At, 1, 0); STAGE_A(SA(0, 1), brow + HALF, t + 2);
;     WAIT_L(8); BAR; WAIT_L(0); MMA(0, 0, At, B0); BAR; SCHED;
;     LDB(B1, 1, 1); STAGE_B(SB(1, 0), bcol, t + 3);
;     BAR; WAIT_L(0); MMA(0, 1, At, B1); BAR; SCHED;
;     LDA(At, 1, 1); STAGE_A(SA(1, 0), brow, t + 3);
;     BAR; WAIT_L(0); MMA(1, 0, At, B0); BAR; SCHED;
	s_waitcnt lgkmcnt(0)
	s_setprio 1
	v_mfma_f32_16x16x32_bf16 v[62:65], v[164:167], v[180:183], v[62:65]
	v_mfma_f32_16x16x32_bf16 v[58:61], v[172:175], v[180:183], v[58:61]
	v_mfma_f32_16x16x32_bf16 v[54:57], v[164:167], v[188:191], v[54:57]
	v_mfma_f32_16x16x32_bf16 v[50:53], v[172:175], v[188:191], v[50:53]
	v_mfma_f32_16x16x32_bf16 v[46:49], v[164:167], v[196:199], v[46:49]
	v_mfma_f32_16x16x32_bf16 v[42:45], v[172:175], v[196:199], v[42:45]
	v_mfma_f32_16x16x32_bf16 v[38:41], v[164:167], v[206:209], v[38:41]
	v_mfma_f32_16x16x32_bf16 v[34:37], v[172:175], v[206:209], v[34:37]
	v_mfma_f32_16x16x32_bf16 v[62:65], v[168:171], v[184:187], v[62:65]
	v_mfma_f32_16x16x32_bf16 v[58:61], v[176:179], v[184:187], v[58:61]
	v_mfma_f32_16x16x32_bf16 v[54:57], v[168:171], v[192:195], v[54:57]
	v_mfma_f32_16x16x32_bf16 v[50:53], v[176:179], v[192:195], v[50:53]
	v_mfma_f32_16x16x32_bf16 v[46:49], v[168:171], v[202:205], v[46:49]
	v_mfma_f32_16x16x32_bf16 v[42:45], v[176:179], v[202:205], v[42:45]
	v_mfma_f32_16x16x32_bf16 v[38:41], v[168:171], v[216:219], v[38:41]
	v_mfma_f32_16x16x32_bf16 v[34:37], v[176:179], v[216:219], v[34:37]
	v_mfma_f32_16x16x32_bf16 v[30:33], v[228:231], v[180:183], v[30:33]
	v_mfma_f32_16x16x32_bf16 v[26:29], v[236:239], v[180:183], v[26:29]
	v_mfma_f32_16x16x32_bf16 v[22:25], v[228:231], v[188:191], v[22:25]
	v_mfma_f32_16x16x32_bf16 v[18:21], v[236:239], v[188:191], v[18:21]
	v_mfma_f32_16x16x32_bf16 v[14:17], v[228:231], v[196:199], v[14:17]
	v_mfma_f32_16x16x32_bf16 v[10:13], v[236:239], v[196:199], v[10:13]
	v_mfma_f32_16x16x32_bf16 v[6:9], v[228:231], v[206:209], v[6:9]
	v_mfma_f32_16x16x32_bf16 v[2:5], v[236:239], v[206:209], v[2:5]
	v_mfma_f32_16x16x32_bf16 v[30:33], v[232:235], v[184:187], v[30:33]
	v_mfma_f32_16x16x32_bf16 v[26:29], v[240:243], v[184:187], v[26:29]
	v_mfma_f32_16x16x32_bf16 v[22:25], v[232:235], v[192:195], v[22:25]
	v_mfma_f32_16x16x32_bf16 v[18:21], v[240:243], v[192:195], v[18:21]
	v_mfma_f32_16x16x32_bf16 v[14:17], v[232:235], v[202:205], v[14:17]
	v_mfma_f32_16x16x32_bf16 v[10:13], v[240:243], v[202:205], v[10:13]
	v_mfma_f32_16x16x32_bf16 v[6:9], v[232:235], v[216:219], v[6:9]
	v_mfma_f32_16x16x32_bf16 v[2:5], v[240:243], v[216:219], v[2:5]
	s_setprio 0
	s_barrier
	ds_read_b128 v[164:167], v149
	ds_read_b128 v[168:171], v149 offset:1024
	ds_read_b128 v[172:175], v149 offset:2048
	ds_read_b128 v[176:179], v149 offset:3072
	ds_read_b128 v[180:183], v147 offset:32768
	ds_read_b128 v[184:187], v147 offset:33792
	ds_read_b128 v[188:191], v146 offset:32768
	ds_read_b128 v[192:195], v146 offset:33792
	ds_read_b128 v[196:199], v145 offset:32768
	ds_read_b128 v[202:205], v145 offset:33792
	ds_read_b128 v[206:209], v144 offset:32768
	ds_read_b128 v[216:219], v144 offset:33792
	s_waitcnt lgkmcnt(6)
	ds_read_b128 v[228:231], v148
	ds_read_b128 v[232:235], v148 offset:1024
	ds_read_b128 v[236:239], v148 offset:2048
	ds_read_b128 v[240:243], v148 offset:3072
	v_readfirstlane_b32 s2, v134
	v_lshl_add_u64 v[222:223], v[210:211], 0, s[46:47]
	s_mov_b32 m0, s2
	v_readfirstlane_b32 s2, v133
	global_load_lds_dwordx4 v[222:223], off
	v_lshl_add_u64 v[222:223], v[210:211], 0, s[48:49]
	s_mov_b32 m0, s2
	s_nop 0
	global_load_lds_dwordx4 v[222:223], off
	s_waitcnt vmcnt(8)
	s_barrier
	s_waitcnt lgkmcnt(0)
	s_setprio 1
	v_mfma_f32_16x16x32_bf16 v[126:129], v[164:167], v[180:183], v[126:129]
	v_mfma_f32_16x16x32_bf16 v[122:125], v[172:175], v[180:183], v[122:125]
	v_mfma_f32_16x16x32_bf16 v[118:121], v[164:167], v[188:191], v[118:121]
	v_mfma_f32_16x16x32_bf16 v[114:117], v[172:175], v[188:191], v[114:117]
	v_mfma_f32_16x16x32_bf16 v[110:113], v[164:167], v[196:199], v[110:113]
	v_mfma_f32_16x16x32_bf16 v[106:109], v[172:175], v[196:199], v[106:109]
	v_mfma_f32_16x16x32_bf16 v[102:105], v[164:167], v[206:209], v[102:105]
	v_mfma_f32_16x16x32_bf16 v[98:101], v[172:175], v[206:209], v[98:101]
	v_mfma_f32_16x16x32_bf16 v[126:129], v[168:171], v[184:187], v[126:129]
	v_mfma_f32_16x16x32_bf16 v[122:125], v[176:179], v[184:187], v[122:125]
	v_mfma_f32_16x16x32_bf16 v[118:121], v[168:171], v[192:195], v[118:121]
	v_mfma_f32_16x16x32_bf16 v[114:117], v[176:179], v[192:195], v[114:117]
	v_mfma_f32_16x16x32_bf16 v[110:113], v[168:171], v[202:205], v[110:113]
	v_mfma_f32_16x16x32_bf16 v[106:109], v[176:179], v[202:205], v[106:109]
	v_mfma_f32_16x16x32_bf16 v[102:105], v[168:171], v[216:219], v[102:105]
	v_mfma_f32_16x16x32_bf16 v[98:101], v[176:179], v[216:219], v[98:101]
	v_mfma_f32_16x16x32_bf16 v[94:97], v[228:231], v[180:183], v[94:97]
	v_mfma_f32_16x16x32_bf16 v[90:93], v[236:239], v[180:183], v[90:93]
	v_mfma_f32_16x16x32_bf16 v[86:89], v[228:231], v[188:191], v[86:89]
	v_mfma_f32_16x16x32_bf16 v[82:85], v[236:239], v[188:191], v[82:85]
	v_mfma_f32_16x16x32_bf16 v[78:81], v[228:231], v[196:199], v[78:81]
	v_mfma_f32_16x16x32_bf16 v[74:77], v[236:239], v[196:199], v[74:77]
	v_mfma_f32_16x16x32_bf16 v[70:73], v[228:231], v[206:209], v[70:73]
	v_mfma_f32_16x16x32_bf16 v[66:69], v[236:239], v[206:209], v[66:69]
	v_mfma_f32_16x16x32_bf16 v[94:97], v[232:235], v[184:187], v[94:97]
	v_mfma_f32_16x16x32_bf16 v[90:93], v[240:243], v[184:187], v[90:93]
	v_mfma_f32_16x16x32_bf16 v[86:89], v[232:235], v[192:195], v[86:89]
	v_mfma_f32_16x16x32_bf16 v[82:85], v[240:243], v[192:195], v[82:85]
	v_mfma_f32_16x16x32_bf16 v[78:81], v[232:235], v[202:205], v[78:81]
	v_mfma_f32_16x16x32_bf16 v[74:77], v[240:243], v[202:205], v[74:77]
	v_mfma_f32_16x16x32_bf16 v[70:73], v[232:235], v[216:219], v[70:73]
	v_mfma_f32_16x16x32_bf16 v[66:69], v[240:243], v[216:219], v[66:69]
	s_setprio 0
	s_barrier
; #define STAGE_B(P, br, kt) do { const char* _gb = (const char*)(Bt + ((long)(br) * K + (long)(kt) * BK)); \
;     __builtin_amdgcn_global_load_lds((const unsigned*)(_gb + bofl0), (unsigned*)((char*)(P) + gtid_ * 16), 16, 0, 0); \
;     __builtin_amdgcn_global_load_lds((const unsigned*)(_gb + (long)K * 128 + bofl0), (unsigned*)((char*)(P) + gtid_ * 16 + 8192), 16, 0, 0); } while (0)
; #define LDA(dst, b, h) for (int m = 0; m < 4; ++m) for (int k = 0; k < 2; ++k) \
;     dst[m][k] = *reinterpret_cast<const bf16x8*>((char*)SA(b, h) + lds_byte(wr * 64 + m * 16 + fr, k * 32 + fq * 8))
; #define LDB(dst, b, h) for (int n = 0; n < 2; ++n) for (int k = 0; k < 2; ++k) \
;     dst[n][k] = *reinterpret_cast<const bf16x8*>((char*)SB(b, h) + lds_byte(wc * 32 + n * 16 + fr, k * 32 + fq * 8))
; #define MMA(ai, bj, At_, Bt_) do { __builtin_amdgcn_s_setprio(1); \
;     for (int m = 0; m < 4; ++m) for (int n = 0; n < 2; ++n) for (int k = 0; k < 2; ++k) \
;       acc[ai][bj][m][n] = __builtin_amdgcn_mfma_f32_16x16x32_bf16(At_[m][k], Bt_[n][k], acc[ai][bj][m][n], 0, 0, 0); \
;     __builtin_amdgcn_s_setprio(0); } while (0)
; #define WAIT_V(n) asm volatile("s_waitcnt vmcnt(" #n ")" ::: "memory")
; #define WAIT_L(n) asm volatile("s_waitcnt lgkmcnt(" #n ")" ::: "memory")
; #define BAR __builtin_amdgcn_s_barrier()
; #define SCHED __builtin_amdgcn_sched_barrier(0)
; template <int EPI>
; __device__ __forceinline__ void gemm_tile(const GemmArgs& g, int brow, int bcol, int parity, bool first, bool nvalid, int nbrow, int nbcol) {
;     ...
;     BAR; WAIT_L(0); MMA(1, 0, At, B0); BAR; SCHED;
;     STAGE_B(SB(1, 1), bcol + HALF, t + 3);
;     WAIT_V(6); BAR; MMA(1, 1, At, B1); BAR; SCHED;
;   }
;   { LDB(B0, 0, 0); LDA(At, 0, 0); STAGE_A(SA(1, 1), brow + HALF, nt - 1);
;     BAR; WAIT_L(0); MMA(0, 0, At, B0); BAR;
	ds_read_b128 v[180:183], v147 offset:49152
	ds_read_b128 v[184:187], v147 offset:50176
	ds_read_b128 v[188:191], v146 offset:49152
	ds_read_b128 v[192:195], v146 offset:50176
	ds_read_b128 v[196:199], v145 offset:49152
	ds_read_b128 v[202:205], v145 offset:50176
	ds_read_b128 v[206:209], v144 offset:49152
	ds_read_b128 v[216:219], v144 offset:50176
	s_mov_b64 s[2:3], 0x900180
	v_lshl_add_u64 v[222:223], v[212:213], 0, s[2:3]
	v_readfirstlane_b32 s2, v150
	s_mov_b32 m0, s2
	s_mov_b64 s[2:3], 0x920180
	global_load_lds_dwordx4 v[222:223], off
	v_lshl_add_u64 v[222:223], v[212:213], 0, s[2:3]
	v_readfirstlane_b32 s2, v151
	s_mov_b32 m0, s2
	s_nop 0
	global_load_lds_dwordx4 v[222:223], off
	v_readfirstlane_b32 s2, v152
	v_lshl_add_u64 v[222:223], v[210:211], 0, s[50:51]
	s_mov_b32 m0, s2
	v_readfirstlane_b32 s2, v153
	global_load_lds_dwordx4 v[222:223], off
	v_lshl_add_u64 v[210:211], v[210:211], 0, s[52:53]
	s_mov_b32 m0, s2
	s_nop 0
	global_load_lds_dwordx4 v[210:211], off
	s_mov_b64 s[2:3], 0x940180
	v_lshl_add_u64 v[244:245], v[212:213], 0, s[2:3]
	v_readfirstlane_b32 s2, v155
	s_mov_b32 m0, s2
	s_mov_b64 s[2:3], 0x960180
	global_load_lds_dwordx4 v[244:245], off
	v_lshl_add_u64 v[244:245], v[212:213], 0, s[2:3]
	v_readfirstlane_b32 s2, v156
	s_mov_b32 m0, s2
	s_nop 0
	global_load_lds_dwordx4 v[244:245], off
	s_waitcnt vmcnt(8)
	s_barrier
	s_waitcnt lgkmcnt(0)
	s_setprio 1
	v_mfma_f32_16x16x32_bf16 v[62:65], v[164:167], v[180:183], v[62:65]
	v_mfma_f32_16x16x32_bf16 v[58:61], v[172:175], v[180:183], v[58:61]
	v_mfma_f32_16x16x32_bf16 v[54:57], v[164:167], v[188:191], v[54:57]
	v_mfma_f32_16x16x32_bf16 v[50:53], v[172:175], v[188:191], v[50:53]
	v_mfma_f32_16x16x32_bf16 v[46:49], v[164:167], v[196:199], v[46:49]
	v_mfma_f32_16x16x32_bf16 v[42:45], v[172:175], v[196:199], v[42:45]
	v_mfma_f32_16x16x32_bf16 v[38:41], v[164:167], v[206:209], v[38:41]
	v_mfma_f32_16x16x32_bf16 v[34:37], v[172:175], v[206:209], v[34:37]
	v_mfma_f32_16x16x32_bf16 v[62:65], v[168:171], v[184:187], v[62:65]
	v_mfma_f32_16x16x32_bf16 v[58:61], v[176:179], v[184:187], v[58:61]
	v_mfma_f32_16x16x32_bf16 v[54:57], v[168:171], v[192:195], v[54:57]
	v_mfma_f32_16x16x32_bf16 v[50:53], v[176:179], v[192:195], v[50:53]
	v_mfma_f32_16x16x32_bf16 v[46:49], v[168:171], v[202:205], v[46:49]
	v_mfma_f32_16x16x32_bf16 v[42:45], v[176:179], v[202:205], v[42:45]
	v_mfma_f32_16x16x32_bf16 v[38:41], v[168:171], v[216:219], v[38:41]
	v_mfma_f32_16x16x32_bf16 v[34:37], v[176:179], v[216:219], v[34:37]
	v_mfma_f32_16x16x32_bf16 v[30:33], v[228:231], v[180:183], v[30:33]
	v_mfma_f32_16x16x32_bf16 v[26:29], v[236:239], v[180:183], v[26:29]
	v_mfma_f32_16x16x32_bf16 v[22:25], v[228:231], v[188:191], v[22:25]
	v_mfma_f32_16x16x32_bf16 v[18:21], v[236:239], v[188:191], v[18:21]
	v_mfma_f32_16x16x32_bf16 v[14:17], v[228:231], v[196:199], v[14:17]
	v_mfma_f32_16x16x32_bf16 v[10:13], v[236:239], v[196:199], v[10:13]
	v_mfma_f32_16x16x32_bf16 v[6:9], v[228:231], v[206:209], v[6:9]
	v_mfma_f32_16x16x32_bf16 v[2:5], v[236:239], v[206:209], v[2:5]
	v_mfma_f32_16x16x32_bf16 v[30:33], v[232:235], v[184:187], v[30:33]
	v_mfma_f32_16x16x32_bf16 v[26:29], v[240:243], v[184:187], v[26:29]
	v_mfma_f32_16x16x32_bf16 v[22:25], v[232:235], v[192:195], v[22:25]
	v_mfma_f32_16x16x32_bf16 v[18:21], v[240:243], v[192:195], v[18:21]
	v_mfma_f32_16x16x32_bf16 v[14:17], v[232:235], v[202:205], v[14:17]
	v_mfma_f32_16x16x32_bf16 v[10:13], v[240:243], v[202:205], v[10:13]
	v_mfma_f32_16x16x32_bf16 v[6:9], v[232:235], v[216:219], v[6:9]
	v_mfma_f32_16x16x32_bf16 v[2:5], v[240:243], v[216:219], v[2:5]
	s_setprio 0
	s_barrier
	s_add_i32 s15, s15, 2
	s_add_u32 s0, s0, 0x100
	s_addc_u32 s1, s1, 0
	s_add_u32 s12, s12, 0x100
	s_addc_u32 s13, s13, 0
	s_cmp_lt_u32 s15, 12
	s_cbranch_scc1 .LBB0_90
	s_or_b32 s0, s38, 0x80
	s_ashr_i32 s1, s0, 31
	s_lshl_b64 s[0:1], s[0:1], 11
	s_add_u32 s0, s80, s0
	s_addc_u32 s1, s81, s1
	v_lshl_add_u64 v[130:131], s[0:1], 0, v[0:1]
	s_mov_b64 s[0:1], 0x780
	ds_read_b128 v[150:153], v157
	ds_read_b128 v[164:167], v157 offset:1024
	ds_read_b128 v[168:171], v157 offset:2048
	ds_read_b128 v[172:175], v157 offset:3072
	ds_read_b128 v[176:179], v147
	ds_read_b128 v[180:183], v147 offset:1024
	ds_read_b128 v[184:187], v146
	ds_read_b128 v[188:191], v146 offset:1024
	ds_read_b128 v[192:195], v145
	ds_read_b128 v[196:199], v145 offset:1024
	ds_read_b128 v[202:205], v144
	ds_read_b128 v[206:209], v144 offset:1024
	v_lshl_add_u64 v[156:157], v[130:131], 0, s[0:1]
	v_readfirstlane_b32 s0, v161
	s_mov_b32 m0, s0
	s_mov_b64 s[0:1], 0x20780
	v_lshl_add_u64 v[130:131], v[130:131], 0, s[0:1]
	v_readfirstlane_b32 s0, v162
	global_load_lds_dwordx4 v[156:157], off
	s_mov_b32 m0, s0
	s_nop 0
	global_load_lds_dwordx4 v[130:131], off
	s_waitcnt vmcnt(8)
	s_barrier
	s_waitcnt lgkmcnt(0)
	s_setprio 1
	s_waitcnt lgkmcnt(0)
	v_mfma_f32_16x16x32_bf16 v[126:129], v[150:153], v[176:179], v[126:129]
	v_mfma_f32_16x16x32_bf16 v[118:121], v[150:153], v[184:187], v[118:121]
	v_mfma_f32_16x16x32_bf16 v[110:113], v[150:153], v[192:195], v[110:113]
	v_mfma_f32_16x16x32_bf16 v[102:105], v[150:153], v[202:205], v[102:105]
	v_mfma_f32_16x16x32_bf16 v[126:129], v[164:167], v[180:183], v[126:129]
	v_mfma_f32_16x16x32_bf16 v[122:125], v[168:171], v[176:179], v[122:125]
	v_mfma_f32_16x16x32_bf16 v[118:121], v[164:167], v[188:191], v[118:121]
	v_mfma_f32_16x16x32_bf16 v[114:117], v[168:171], v[184:187], v[114:117]
	v_mfma_f32_16x16x32_bf16 v[110:113], v[164:167], v[196:199], v[110:113]
	v_mfma_f32_16x16x32_bf16 v[106:109], v[168:171], v[192:195], v[106:109]
	v_mfma_f32_16x16x32_bf16 v[102:105], v[164:167], v[206:209], v[102:105]
	v_mfma_f32_16x16x32_bf16 v[98:101], v[168:171], v[202:205], v[98:101]
	v_mfma_f32_16x16x32_bf16 v[216:219], v[172:175], v[180:183], v[122:125]
	v_mfma_f32_16x16x32_bf16 v[228:231], v[172:175], v[188:191], v[114:117]
	v_mfma_f32_16x16x32_bf16 v[232:235], v[172:175], v[196:199], v[106:109]
	v_mfma_f32_16x16x32_bf16 v[236:239], v[172:175], v[206:209], v[98:101]
	s_setprio 0
	s_barrier
; #define LDA(dst, b, h) for (int m = 0; m < 4; ++m) for (int k = 0; k < 2; ++k) \
;     dst[m][k] = *reinterpret_cast<const bf16x8*>((char*)SA(b, h) + lds_byte(wr * 64 + m * 16 + fr, k * 32 + fq * 8))
; #define LDB(dst, b, h) for (int n = 0; n < 2; ++n) for (int k = 0; k < 2; ++k) \
;     dst[n][k] = *reinterpret_cast<const bf16x8*>((char*)SB(b, h) + lds_byte(wc * 32 + n * 16 + fr, k * 32 + fq * 8))
; #define MMA(ai, bj, At_, Bt_) do { __builtin_amdgcn_s_setprio(1); \
;     for (int m = 0; m < 4; ++m) for (int n = 0; n < 2; ++n) for (int k = 0; k < 2; ++k) \
;       acc[ai][bj][m][n] = __builtin_amdgcn_mfma_f32_16x16x32_bf16(At_[m][k], Bt_[n][k], acc[ai][bj][m][n], 0, 0, 0); \
;     __builtin_amdgcn_s_setprio(0); } while (0)
; #define WAIT_V(n) asm volatile("s_waitcnt vmcnt(" #n ")" ::: "memory")
; #define WAIT_L(n) asm volatile("s_waitcnt lgkmcnt(" #n ")" ::: "memory")
; #define BAR __builtin_amdgcn_s_barrier()
; #define SCHED __builtin_amdgcn_sched_barrier(0)
; template <int EPI>
; __device__ __forceinline__ void gemm_tile(const GemmArgs& g, int brow, int bcol, int parity, bool first, bool nvalid, int nbrow, int nbcol) {
;     ...
;   { LDB(B0, 0, 0); LDA(At, 0, 0); STAGE_A(SA(1, 1), brow + HALF, nt - 1);
;     BAR; WAIT_L(0); MMA(0, 0, At, B0); BAR;
;     LDB(B1, 0, 1); BAR; WAIT_L(0); MMA(0, 1, At, B1); BAR; SCHED;
;     LDA(At, 0, 1); WAIT_V(4); BAR; WAIT_L(0); MMA(1, 0, At, B0); MMA(1, 1, At, B1); BAR; }
;   { LDB(B0, 1, 0); LDA(At, 1, 0); WAIT_V(2); BAR; WAIT_L(0); MMA(0, 0, At, B0); BAR;
	s_nop 1
	ds_read_b128 v[98:101], v154
	ds_read_b128 v[106:109], v154 offset:1024
	ds_read_b128 v[114:117], v154 offset:2048
	ds_read_b128 v[122:125], v154 offset:3072
	s_barrier
	s_waitcnt lgkmcnt(0)
	s_setprio 1
	s_waitcnt lgkmcnt(0)
	v_mfma_f32_16x16x32_bf16 v[94:97], v[98:101], v[176:179], v[94:97]
	v_mfma_f32_16x16x32_bf16 v[86:89], v[98:101], v[184:187], v[86:89]
	v_mfma_f32_16x16x32_bf16 v[78:81], v[98:101], v[192:195], v[78:81]
	v_mfma_f32_16x16x32_bf16 v[70:73], v[98:101], v[202:205], v[70:73]
	v_mfma_f32_16x16x32_bf16 v[94:97], v[106:109], v[180:183], v[94:97]
	v_mfma_f32_16x16x32_bf16 v[90:93], v[114:117], v[176:179], v[90:93]
	v_mfma_f32_16x16x32_bf16 v[86:89], v[106:109], v[188:191], v[86:89]
	v_mfma_f32_16x16x32_bf16 v[82:85], v[114:117], v[184:187], v[82:85]
	v_mfma_f32_16x16x32_bf16 v[78:81], v[106:109], v[196:199], v[78:81]
	v_mfma_f32_16x16x32_bf16 v[74:77], v[114:117], v[192:195], v[74:77]
	v_mfma_f32_16x16x32_bf16 v[70:73], v[106:109], v[206:209], v[70:73]
	v_mfma_f32_16x16x32_bf16 v[66:69], v[114:117], v[202:205], v[66:69]
	v_mfma_f32_16x16x32_bf16 v[154:157], v[122:125], v[180:183], v[90:93]
	v_mfma_f32_16x16x32_bf16 v[176:179], v[122:125], v[188:191], v[82:85]
	v_mfma_f32_16x16x32_bf16 v[180:183], v[122:125], v[196:199], v[74:77]
	v_mfma_f32_16x16x32_bf16 v[184:187], v[122:125], v[206:209], v[66:69]
	s_setprio 0
	s_barrier
	s_nop 1
	ds_read_b128 v[66:69], v147 offset:16384
	ds_read_b128 v[74:77], v147 offset:17408
	ds_read_b128 v[82:85], v146 offset:16384
	ds_read_b128 v[90:93], v146 offset:17408
	ds_read_b128 v[188:191], v145 offset:16384
	ds_read_b128 v[192:195], v145 offset:17408
	ds_read_b128 v[196:199], v144 offset:16384
	ds_read_b128 v[202:205], v144 offset:17408
	s_waitcnt vmcnt(4)
	s_barrier
	s_waitcnt lgkmcnt(0)
	s_setprio 1
	s_waitcnt lgkmcnt(0)
	v_mfma_f32_16x16x32_bf16 v[62:65], v[150:153], v[66:69], v[62:65]
	v_mfma_f32_16x16x32_bf16 v[54:57], v[150:153], v[82:85], v[54:57]
	v_mfma_f32_16x16x32_bf16 v[46:49], v[150:153], v[188:191], v[46:49]
	v_mfma_f32_16x16x32_bf16 v[38:41], v[150:153], v[196:199], v[38:41]
	v_mfma_f32_16x16x32_bf16 v[62:65], v[164:167], v[74:77], v[62:65]
	v_mfma_f32_16x16x32_bf16 v[58:61], v[168:171], v[66:69], v[58:61]
	v_mfma_f32_16x16x32_bf16 v[54:57], v[164:167], v[90:93], v[54:57]
	v_mfma_f32_16x16x32_bf16 v[50:53], v[168:171], v[82:85], v[50:53]
	v_mfma_f32_16x16x32_bf16 v[46:49], v[164:167], v[192:195], v[46:49]
	v_mfma_f32_16x16x32_bf16 v[42:45], v[168:171], v[188:191], v[42:45]
	v_mfma_f32_16x16x32_bf16 v[38:41], v[164:167], v[202:205], v[38:41]
	v_mfma_f32_16x16x32_bf16 v[34:37], v[168:171], v[196:199], v[34:37]
	v_mfma_f32_16x16x32_bf16 v[206:209], v[172:175], v[74:77], v[58:61]
	v_mfma_f32_16x16x32_bf16 v[240:243], v[172:175], v[90:93], v[50:53]
	v_mfma_f32_16x16x32_bf16 v[244:247], v[172:175], v[192:195], v[42:45]
	v_mfma_f32_16x16x32_bf16 v[150:153], v[172:175], v[202:205], v[34:37]
	s_setprio 0
	s_setprio 1
	v_mfma_f32_16x16x32_bf16 v[30:33], v[98:101], v[66:69], v[30:33]
	v_mfma_f32_16x16x32_bf16 v[22:25], v[98:101], v[82:85], v[22:25]
	v_mfma_f32_16x16x32_bf16 v[14:17], v[98:101], v[188:191], v[14:17]
	v_mfma_f32_16x16x32_bf16 v[6:9], v[98:101], v[196:199], v[6:9]
	v_mfma_f32_16x16x32_bf16 v[30:33], v[106:109], v[74:77], v[30:33]
	v_mfma_f32_16x16x32_bf16 v[26:29], v[114:117], v[66:69], v[26:29]
	v_mfma_f32_16x16x32_bf16 v[22:25], v[106:109], v[90:93], v[22:25]
	v_mfma_f32_16x16x32_bf16 v[18:21], v[114:117], v[82:85], v[18:21]
	v_mfma_f32_16x16x32_bf16 v[14:17], v[106:109], v[192:195], v[14:17]
	v_mfma_f32_16x16x32_bf16 v[10:13], v[114:117], v[188:191], v[10:13]
	v_mfma_f32_16x16x32_bf16 v[6:9], v[106:109], v[202:205], v[6:9]
	v_mfma_f32_16x16x32_bf16 v[2:5], v[114:117], v[196:199], v[2:5]
	v_mfma_f32_16x16x32_bf16 v[162:165], v[122:125], v[74:77], v[26:29]
	v_mfma_f32_16x16x32_bf16 v[166:169], v[122:125], v[90:93], v[18:21]
	v_mfma_f32_16x16x32_bf16 v[170:173], v[122:125], v[192:195], v[10:13]
	v_mfma_f32_16x16x32_bf16 v[188:191], v[122:125], v[202:205], v[2:5]
	s_setprio 0
	s_barrier
	s_nop 1
	ds_read_b128 v[2:5], v149
	ds_read_b128 v[10:13], v149 offset:1024
	ds_read_b128 v[18:21], v149 offset:2048
	ds_read_b128 v[26:29], v149 offset:3072
	ds_read_b128 v[34:37], v147 offset:32768
	ds_read_b128 v[42:45], v147 offset:33792
	ds_read_b128 v[50:53], v146 offset:32768
	ds_read_b128 v[58:61], v146 offset:33792
	ds_read_b128 v[66:69], v145 offset:32768
	ds_read_b128 v[192:195], v145 offset:33792
	ds_read_b128 v[196:199], v144 offset:32768
	ds_read_b128 v[202:205], v144 offset:33792
	s_waitcnt vmcnt(2)
	s_barrier
; #define LDA(dst, b, h) for (int m = 0; m < 4; ++m) for (int k = 0; k < 2; ++k) \
;     dst[m][k] = *reinterpret_cast<const bf16x8*>((char*)SA(b, h) + lds_byte(wr * 64 + m * 16 + fr, k * 32 + fq * 8))
; #define LDB(dst, b, h) for (int n = 0; n < 2; ++n) for (int k = 0; k < 2; ++k) \
;     dst[n][k] = *reinterpret_cast<const bf16x8*>((char*)SB(b, h) + lds_byte(wc * 32 + n * 16 + fr, k * 32 + fq * 8))
; #define MMA(ai, bj, At_, Bt_) do { __builtin_amdgcn_s_setprio(1); \
;     for (int m = 0; m < 4; ++m) for (int n = 0; n < 2; ++n) for (int k = 0; k < 2; ++k) \
;       acc[ai][bj][m][n] = __builtin_amdgcn_mfma_f32_16x16x32_bf16(At_[m][k], Bt_[n][k], acc[ai][bj][m][n], 0, 0, 0); \
;     __builtin_amdgcn_s_setprio(0); } while (0)
; #define WAIT_V(n) asm volatile("s_waitcnt vmcnt(" #n ")" ::: "memory")
; #define WAIT_L(n) asm volatile("s_waitcnt lgkmcnt(" #n ")" ::: "memory")
; #define BAR __builtin_amdgcn_s_barrier()
; #define SCHED __builtin_amdgcn_sched_barrier(0)
; template <int EPI>
; __device__ __forceinline__ void gemm_tile(const GemmArgs& g, int brow, int bcol, int parity, bool first, bool nvalid, int nbrow, int nbcol) {
;     ...
;     LDA(At, 0, 1); WAIT_V(4); BAR; WAIT_L(0); MMA(1, 0, At, B0); MMA(1, 1, At, B1); BAR; }
;   { LDB(B0, 1, 0); LDA(At, 1, 0); WAIT_V(2); BAR; WAIT_L(0); MMA(0, 0, At, B0); BAR;
;     LDB(B1, 1, 1); WAIT_V(0); BAR; WAIT_L(0); MMA(0, 1, At, B1); BAR; SCHED;
;     LDA(At, 1, 1); BAR; WAIT_L(0); MMA(1, 0, At, B0); MMA(1, 1, At, B1); BAR; }
;   if (wr == 0) BAR;
	s_waitcnt lgkmcnt(0)
	s_setprio 1
	s_waitcnt lgkmcnt(0)
	v_mfma_f32_16x16x32_bf16 v[74:77], v[2:5], v[34:37], v[126:129]
	v_mfma_f32_16x16x32_bf16 v[122:125], v[10:13], v[42:45], v[74:77]
	v_mfma_f32_16x16x32_bf16 v[74:77], v[18:21], v[34:37], v[216:219]
	v_mfma_f32_16x16x32_bf16 v[126:129], v[26:29], v[42:45], v[74:77]
	v_mfma_f32_16x16x32_bf16 v[74:77], v[2:5], v[50:53], v[118:121]
	v_mfma_f32_16x16x32_bf16 v[114:117], v[10:13], v[58:61], v[74:77]
	v_mfma_f32_16x16x32_bf16 v[74:77], v[18:21], v[50:53], v[228:231]
	v_mfma_f32_16x16x32_bf16 v[118:121], v[26:29], v[58:61], v[74:77]
	v_mfma_f32_16x16x32_bf16 v[74:77], v[2:5], v[66:69], v[110:113]
	v_mfma_f32_16x16x32_bf16 v[106:109], v[10:13], v[192:195], v[74:77]
	v_mfma_f32_16x16x32_bf16 v[74:77], v[18:21], v[66:69], v[232:235]
	v_mfma_f32_16x16x32_bf16 v[110:113], v[26:29], v[192:195], v[74:77]
	v_mfma_f32_16x16x32_bf16 v[74:77], v[2:5], v[196:199], v[102:105]
	v_mfma_f32_16x16x32_bf16 v[98:101], v[10:13], v[202:205], v[74:77]
	v_mfma_f32_16x16x32_bf16 v[74:77], v[18:21], v[196:199], v[236:239]
	v_mfma_f32_16x16x32_bf16 v[102:105], v[26:29], v[202:205], v[74:77]
	s_setprio 0
	s_barrier
	ds_read_b128 v[216:219], v148
	ds_read_b128 v[228:231], v148 offset:1024
	ds_read_b128 v[232:235], v148 offset:2048
	ds_read_b128 v[236:239], v148 offset:3072
	s_waitcnt vmcnt(0)
	s_barrier
	s_waitcnt lgkmcnt(0)
	s_setprio 1
	s_waitcnt lgkmcnt(0)
	v_mfma_f32_16x16x32_bf16 v[74:77], v[216:219], v[34:37], v[94:97]
	v_mfma_f32_16x16x32_bf16 v[34:37], v[232:235], v[34:37], v[154:157]
	v_mfma_f32_16x16x32_bf16 v[94:97], v[236:239], v[42:45], v[34:37]
	v_mfma_f32_16x16x32_bf16 v[34:37], v[216:219], v[50:53], v[86:89]
	v_mfma_f32_16x16x32_bf16 v[82:85], v[228:231], v[58:61], v[34:37]
	v_mfma_f32_16x16x32_bf16 v[34:37], v[232:235], v[50:53], v[176:179]
	v_mfma_f32_16x16x32_bf16 v[86:89], v[236:239], v[58:61], v[34:37]
	v_mfma_f32_16x16x32_bf16 v[34:37], v[216:219], v[66:69], v[78:81]
	v_mfma_f32_16x16x32_bf16 v[90:93], v[228:231], v[42:45], v[74:77]
	v_mfma_f32_16x16x32_bf16 v[74:77], v[228:231], v[192:195], v[34:37]
	v_mfma_f32_16x16x32_bf16 v[34:37], v[232:235], v[66:69], v[180:183]
	v_mfma_f32_16x16x32_bf16 v[78:81], v[236:239], v[192:195], v[34:37]
	v_mfma_f32_16x16x32_bf16 v[34:37], v[216:219], v[196:199], v[70:73]
	v_mfma_f32_16x16x32_bf16 v[66:69], v[228:231], v[202:205], v[34:37]
	v_mfma_f32_16x16x32_bf16 v[34:37], v[232:235], v[196:199], v[184:187]
	v_mfma_f32_16x16x32_bf16 v[70:73], v[236:239], v[202:205], v[34:37]
	s_setprio 0
	s_barrier
	ds_read_b128 v[154:157], v147 offset:49152
	ds_read_b128 v[174:177], v147 offset:50176
	ds_read_b128 v[178:181], v146 offset:49152
	ds_read_b128 v[146:149], v146 offset:50176
	ds_read_b128 v[182:185], v145 offset:49152
	ds_read_b128 v[192:195], v145 offset:50176
	ds_read_b128 v[196:199], v144 offset:49152
	ds_read_b128 v[202:205], v144 offset:50176
	s_barrier
	s_waitcnt lgkmcnt(0)
	s_setprio 1
	s_waitcnt lgkmcnt(0)
	v_mfma_f32_16x16x32_bf16 v[34:37], v[2:5], v[154:157], v[62:65]
	v_mfma_f32_16x16x32_bf16 v[58:61], v[10:13], v[174:177], v[34:37]
	v_mfma_f32_16x16x32_bf16 v[34:37], v[18:21], v[154:157], v[206:209]
	v_mfma_f32_16x16x32_bf16 v[62:65], v[26:29], v[174:177], v[34:37]
	v_mfma_f32_16x16x32_bf16 v[34:37], v[2:5], v[178:181], v[54:57]
	v_mfma_f32_16x16x32_bf16 v[50:53], v[10:13], v[146:149], v[34:37]
	v_mfma_f32_16x16x32_bf16 v[34:37], v[18:21], v[178:181], v[240:243]
	v_mfma_f32_16x16x32_bf16 v[54:57], v[26:29], v[146:149], v[34:37]
	v_mfma_f32_16x16x32_bf16 v[34:37], v[2:5], v[182:185], v[46:49]
	v_mfma_f32_16x16x32_bf16 v[42:45], v[10:13], v[192:195], v[34:37]
	v_mfma_f32_16x16x32_bf16 v[34:37], v[18:21], v[182:185], v[244:247]
	v_mfma_f32_16x16x32_bf16 v[2:5], v[2:5], v[196:199], v[38:41]
	v_mfma_f32_16x16x32_bf16 v[46:49], v[26:29], v[192:195], v[34:37]
	v_mfma_f32_16x16x32_bf16 v[34:37], v[10:13], v[202:205], v[2:5]
	v_mfma_f32_16x16x32_bf16 v[2:5], v[18:21], v[196:199], v[150:153]
	v_mfma_f32_16x16x32_bf16 v[38:41], v[26:29], v[202:205], v[2:5]
	s_setprio 0
	s_setprio 1
	v_mfma_f32_16x16x32_bf16 v[2:5], v[216:219], v[154:157], v[30:33]
	v_mfma_f32_16x16x32_bf16 v[26:29], v[228:231], v[174:177], v[2:5]
	v_mfma_f32_16x16x32_bf16 v[2:5], v[232:235], v[154:157], v[162:165]
	v_mfma_f32_16x16x32_bf16 v[30:33], v[236:239], v[174:177], v[2:5]
	v_mfma_f32_16x16x32_bf16 v[2:5], v[216:219], v[178:181], v[22:25]
	v_mfma_f32_16x16x32_bf16 v[18:21], v[228:231], v[146:149], v[2:5]
	v_mfma_f32_16x16x32_bf16 v[2:5], v[232:235], v[178:181], v[166:169]
	v_mfma_f32_16x16x32_bf16 v[22:25], v[236:239], v[146:149], v[2:5]
	v_mfma_f32_16x16x32_bf16 v[2:5], v[216:219], v[182:185], v[14:17]
	v_mfma_f32_16x16x32_bf16 v[10:13], v[228:231], v[192:195], v[2:5]
	v_mfma_f32_16x16x32_bf16 v[2:5], v[232:235], v[182:185], v[170:173]
	v_mfma_f32_16x16x32_bf16 v[14:17], v[236:239], v[192:195], v[2:5]
	v_mfma_f32_16x16x32_bf16 v[2:5], v[216:219], v[196:199], v[6:9]
	v_mfma_f32_16x16x32_bf16 v[6:9], v[232:235], v[196:199], v[188:191]
	v_mfma_f32_16x16x32_bf16 v[2:5], v[228:231], v[202:205], v[2:5]
	v_mfma_f32_16x16x32_bf16 v[6:9], v[236:239], v[202:205], v[6:9]
	s_setprio 0
	s_movk_i32 s0, 0x100
	v_cmp_gt_u32_e32 vcc, s0, v138
	s_barrier
	s_and_saveexec_b64 s[0:1], vcc
	s_cbranch_execz .LBB0_93
	s_barrier

; #define WAIT_V(n) asm volatile("s_waitcnt vmcnt(" #n ")" ::: "memory")
; #define BAR __builtin_amdgcn_s_barrier()
; template <int EPI>
; __device__ __forceinline__ void gemm_tile(const GemmArgs& g, int brow, int bcol, int parity, bool first, bool nvalid, int nbrow, int nbcol) {
;     ...
;   if (wr == 1) BAR;
;   if (first) { WAIT_V(4); } else { WAIT_V(0); }
;   BAR;
.LBB0_126:
	s_or_b64 exec, exec, s[14:15]
	s_xor_b64 s[12:13], s[12:13], -1
	s_andn2_b64 vcc, exec, s[12:13]
	s_mov_b64 s[12:13], -1
	s_cbranch_vccnz .LBB0_128
	s_waitcnt vmcnt(2)
	s_mov_b64 s[12:13], 0

; #define STAGE_B(P, br, kt) do { const char* _gb = (const char*)(Bt + ((long)(br) * K + (long)(kt) * BK)); \
;     __builtin_amdgcn_global_load_lds((const unsigned*)(_gb + bofl0), (unsigned*)((char*)(P) + gtid_ * 16), 16, 0, 0); \
;     __builtin_amdgcn_global_load_lds((const unsigned*)(_gb + (long)K * 128 + bofl0), (unsigned*)((char*)(P) + gtid_ * 16 + 8192), 16, 0, 0); } while (0)
; #define LDA(dst, b, h) for (int m = 0; m < 4; ++m) for (int k = 0; k < 2; ++k) \
;     dst[m][k] = *reinterpret_cast<const bf16x8*>((char*)SA(b, h) + lds_byte(wr * 64 + m * 16 + fr, k * 32 + fq * 8))
; #define LDB(dst, b, h) for (int n = 0; n < 2; ++n) for (int k = 0; k < 2; ++k) \
;     dst[n][k] = *reinterpret_cast<const bf16x8*>((char*)SB(b, h) + lds_byte(wc * 32 + n * 16 + fr, k * 32 + fq * 8))
; #define MMA(ai, bj, At_, Bt_) do { __builtin_amdgcn_s_setprio(1); \
;     for (int m = 0; m < 4; ++m) for (int n = 0; n < 2; ++n) for (int k = 0; k < 2; ++k) \
;       acc[ai][bj][m][n] = __builtin_amdgcn_mfma_f32_16x16x32_bf16(At_[m][k], Bt_[n][k], acc[ai][bj][m][n], 0, 0, 0); \
;     __builtin_amdgcn_s_setprio(0); } while (0)
; #define WAIT_V(n) asm volatile("s_waitcnt vmcnt(" #n ")" ::: "memory")
; #define WAIT_L(n) asm volatile("s_waitcnt lgkmcnt(" #n ")" ::: "memory")
; #define BAR __builtin_amdgcn_s_barrier()
; #define SCHED __builtin_amdgcn_sched_barrier(0)
; template <int EPI>
; __device__ __forceinline__ void gemm_tile(const GemmArgs& g, int brow, int bcol, int parity, bool first, bool nvalid, int nbrow, int nbcol) {
;     ...
;   for (int t = 0; t < nt - 2; t += 2) {
;     LDB(B0, 0, 0); SCHED; LDA(At, 0, 0); STAGE_A(SA(1, 1), brow + HALF, t + 1);
;     WAIT_L(8); BAR; WAIT_L(0); MMA(0, 0, At, B0); BAR; SCHED;
;     LDB(B1, 0, 1); STAGE_B(SB(0, 0), bcol, t + 2);
;     BAR; WAIT_L(0); MMA(0, 1, At, B1); BAR; SCHED;
;     LDA(At, 0, 1); STAGE_A(SA(0, 0), brow, t + 2);
;     BAR; WAIT_L(0); MMA(1, 0, At, B0); BAR; SCHED;
;     STAGE_B(SB(0, 1), bcol + HALF, t + 2);
;     WAIT_V(6); BAR; MMA(1, 1, At, B1); BAR; SCHED;
.LBB0_133:
	ds_read_b128 v[164:167], v157
	ds_read_b128 v[168:171], v157 offset:1024
	ds_read_b128 v[172:175], v157 offset:2048
	ds_read_b128 v[176:179], v157 offset:3072
	ds_read_b128 v[180:183], v146
	ds_read_b128 v[184:187], v146 offset:1024
	ds_read_b128 v[188:191], v145
	ds_read_b128 v[192:195], v145 offset:1024
	ds_read_b128 v[196:199], v144
	ds_read_b128 v[202:205], v144 offset:1024
	ds_read_b128 v[206:209], v143
	ds_read_b128 v[216:219], v143 offset:1024
	s_waitcnt lgkmcnt(6)
	ds_read_b128 v[222:225], v154
	ds_read_b128 v[228:231], v154 offset:1024
	ds_read_b128 v[232:235], v154 offset:2048
	ds_read_b128 v[236:239], v154 offset:3072
	v_add_u32_e32 v161, 0xc000, v137
	v_lshl_add_u64 v[210:211], s[12:13], 0, v[130:131]
	v_readfirstlane_b32 s2, v161
	v_add_u32_e32 v162, 0xe000, v137
	v_lshl_add_u64 v[158:159], v[210:211], 0, s[24:25]
	s_mov_b32 m0, s2
	v_readfirstlane_b32 s2, v162
	global_load_lds_dwordx4 v[158:159], off
	v_lshl_add_u64 v[158:159], v[210:211], 0, s[34:35]
	s_mov_b32 m0, s2
	s_nop 0
	global_load_lds_dwordx4 v[158:159], off
	s_waitcnt vmcnt(8)
	s_barrier
	s_waitcnt lgkmcnt(0)
	s_setprio 1
	v_mfma_f32_16x16x32_bf16 v[126:129], v[180:183], v[164:167], v[126:129]
	v_mfma_f32_16x16x32_bf16 v[122:125], v[180:183], v[172:175], v[122:125]
	v_mfma_f32_16x16x32_bf16 v[118:121], v[188:191], v[164:167], v[118:121]
	v_mfma_f32_16x16x32_bf16 v[114:117], v[188:191], v[172:175], v[114:117]
	v_mfma_f32_16x16x32_bf16 v[110:113], v[196:199], v[164:167], v[110:113]
	v_mfma_f32_16x16x32_bf16 v[106:109], v[196:199], v[172:175], v[106:109]
	v_mfma_f32_16x16x32_bf16 v[102:105], v[206:209], v[164:167], v[102:105]
	v_mfma_f32_16x16x32_bf16 v[98:101], v[206:209], v[172:175], v[98:101]
	v_mfma_f32_16x16x32_bf16 v[126:129], v[184:187], v[168:171], v[126:129]
	v_mfma_f32_16x16x32_bf16 v[122:125], v[184:187], v[176:179], v[122:125]
	v_mfma_f32_16x16x32_bf16 v[118:121], v[192:195], v[168:171], v[118:121]
	v_mfma_f32_16x16x32_bf16 v[114:117], v[192:195], v[176:179], v[114:117]
	v_mfma_f32_16x16x32_bf16 v[110:113], v[202:205], v[168:171], v[110:113]
	v_mfma_f32_16x16x32_bf16 v[106:109], v[202:205], v[176:179], v[106:109]
	v_mfma_f32_16x16x32_bf16 v[102:105], v[216:219], v[168:171], v[102:105]
	v_mfma_f32_16x16x32_bf16 v[98:101], v[216:219], v[176:179], v[98:101]
	v_mfma_f32_16x16x32_bf16 v[94:97], v[180:183], v[222:225], v[94:97]
	v_mfma_f32_16x16x32_bf16 v[90:93], v[180:183], v[232:235], v[90:93]
	v_mfma_f32_16x16x32_bf16 v[86:89], v[188:191], v[222:225], v[86:89]
	v_mfma_f32_16x16x32_bf16 v[82:85], v[188:191], v[232:235], v[82:85]
	v_mfma_f32_16x16x32_bf16 v[78:81], v[196:199], v[222:225], v[78:81]
	v_mfma_f32_16x16x32_bf16 v[74:77], v[196:199], v[232:235], v[74:77]
	v_mfma_f32_16x16x32_bf16 v[70:73], v[206:209], v[222:225], v[70:73]
	v_mfma_f32_16x16x32_bf16 v[66:69], v[206:209], v[232:235], v[66:69]
	v_mfma_f32_16x16x32_bf16 v[94:97], v[184:187], v[228:231], v[94:97]
	v_mfma_f32_16x16x32_bf16 v[90:93], v[184:187], v[236:239], v[90:93]
	v_mfma_f32_16x16x32_bf16 v[86:89], v[192:195], v[228:231], v[86:89]
	v_mfma_f32_16x16x32_bf16 v[82:85], v[192:195], v[236:239], v[82:85]
	v_mfma_f32_16x16x32_bf16 v[78:81], v[202:205], v[228:231], v[78:81]
	v_mfma_f32_16x16x32_bf16 v[74:77], v[202:205], v[236:239], v[74:77]
	v_mfma_f32_16x16x32_bf16 v[70:73], v[216:219], v[228:231], v[70:73]
	v_mfma_f32_16x16x32_bf16 v[66:69], v[216:219], v[236:239], v[66:69]
	s_setprio 0
	s_barrier
	ds_read_b128 v[180:183], v146 offset:16384
	ds_read_b128 v[184:187], v146 offset:17408
	ds_read_b128 v[188:191], v145 offset:16384
	ds_read_b128 v[192:195], v145 offset:17408
	ds_read_b128 v[196:199], v144 offset:16384
	ds_read_b128 v[202:205], v144 offset:17408
	ds_read_b128 v[206:209], v143 offset:16384
	ds_read_b128 v[216:219], v143 offset:17408
	v_add_u32_e32 v158, s15, v141
	v_lshl_add_u64 v[212:213], s[0:1], 0, v[130:131]
	v_readfirstlane_b32 s2, v158
	v_add_u32_e32 v159, 0x2000, v158
	v_lshl_add_u64 v[240:241], v[212:213], 0, s[78:79]
	s_mov_b32 m0, s2
	v_readfirstlane_b32 s2, v159
	global_load_lds_dwordx4 v[240:241], off
	v_lshl_add_u64 v[240:241], v[212:213], 0, s[52:53]
	s_mov_b32 m0, s2
	s_nop 0
	global_load_lds_dwordx4 v[240:241], off
	v_readfirstlane_b32 s2, v137
	v_lshl_add_u64 v[240:241], v[210:211], 0, s[36:37]
	s_mov_b32 m0, s2
	v_readfirstlane_b32 s2, v136
	global_load_lds_dwordx4 v[240:241], off
	v_lshl_add_u64 v[240:241], v[210:211], 0, s[42:43]
	s_mov_b32 m0, s2
	s_nop 0
	global_load_lds_dwordx4 v[240:241], off
	v_readfirstlane_b32 s2, v135
	v_add_u32_e32 v160, 0x2000, v135
	v_lshl_add_u64 v[244:245], v[212:213], 0, s[56:57]
	s_mov_b32 m0, s2
	v_readfirstlane_b32 s2, v160
	global_load_lds_dwordx4 v[244:245], off
	v_lshl_add_u64 v[244:245], v[212:213], 0, s[66:67]
	s_mov_b32 m0, s2
	s_nop 0
	global_load_lds_dwordx4 v[244:245], off
	s_waitcnt vmcnt(8)
	s_barrier
; #define STAGE_B(P, br, kt) do { const char* _gb = (const char*)(Bt + ((long)(br) * K + (long)(kt) * BK)); \
;     __builtin_amdgcn_global_load_lds((const unsigned*)(_gb + bofl0), (unsigned*)((char*)(P) + gtid_ * 16), 16, 0, 0); \
;     __builtin_amdgcn_global_load_lds((const unsigned*)(_gb + (long)K * 128 + bofl0), (unsigned*)((char*)(P) + gtid_ * 16 + 8192), 16, 0, 0); } while (0)
; #define LDA(dst, b, h) for (int m = 0; m < 4; ++m) for (int k = 0; k < 2; ++k) \
;     dst[m][k] = *reinterpret_cast<const bf16x8*>((char*)SA(b, h) + lds_byte(wr * 64 + m * 16 + fr, k * 32 + fq * 8))
; #define LDB(dst, b, h) for (int n = 0; n < 2; ++n) for (int k = 0; k < 2; ++k) \
;     dst[n][k] = *reinterpret_cast<const bf16x8*>((char*)SB(b, h) + lds_byte(wc * 32 + n * 16 + fr, k * 32 + fq * 8))
; #define MMA(ai, bj, At_, Bt_) do { __builtin_amdgcn_s_setprio(1); \
;     for (int m = 0; m < 4; ++m) for (int n = 0; n < 2; ++n) for (int k = 0; k < 2; ++k) \
;       acc[ai][bj][m][n] = __builtin_amdgcn_mfma_f32_16x16x32_bf16(At_[m][k], Bt_[n][k], acc[ai][bj][m][n], 0, 0, 0); \
;     __builtin_amdgcn_s_setprio(0); } while (0)
; #define WAIT_V(n) asm volatile("s_waitcnt vmcnt(" #n ")" ::: "memory")
; #define WAIT_L(n) asm volatile("s_waitcnt lgkmcnt(" #n ")" ::: "memory")
; #define BAR __builtin_amdgcn_s_barrier()
; #define SCHED __builtin_amdgcn_sched_barrier(0)
; template <int EPI>
; __device__ __forceinline__ void gemm_tile(const GemmArgs& g, int brow, int bcol, int parity, bool first, bool nvalid, int nbrow, int nbcol) {
;     ...
;     STAGE_B(SB(0, 1), bcol + HALF, t + 2);
;     WAIT_V(6); BAR; MMA(1, 1, At, B1); BAR; SCHED;
;     LDB(B0, 1, 0); SCHED; LDA(At, 1, 0); STAGE_A(SA(0, 1), brow + HALF, t + 2);
;     WAIT_L(8); BAR; WAIT_L(0); MMA(0, 0, At, B0); BAR; SCHED;
;     LDB(B1, 1, 1); STAGE_B(SB(1, 0), bcol, t + 3);
;     BAR; WAIT_L(0); MMA(0, 1, At, B1); BAR; SCHED;
;     LDA(At, 1, 1); STAGE_A(SA(1, 0), brow, t + 3);
;     BAR; WAIT_L(0); MMA(1, 0, At, B0); BAR; SCHED;
	s_waitcnt lgkmcnt(0)
	s_setprio 1
	v_mfma_f32_16x16x32_bf16 v[62:65], v[180:183], v[164:167], v[62:65]
	v_mfma_f32_16x16x32_bf16 v[58:61], v[180:183], v[172:175], v[58:61]
	v_mfma_f32_16x16x32_bf16 v[54:57], v[188:191], v[164:167], v[54:57]
	v_mfma_f32_16x16x32_bf16 v[50:53], v[188:191], v[172:175], v[50:53]
	v_mfma_f32_16x16x32_bf16 v[46:49], v[196:199], v[164:167], v[46:49]
	v_mfma_f32_16x16x32_bf16 v[42:45], v[196:199], v[172:175], v[42:45]
	v_mfma_f32_16x16x32_bf16 v[38:41], v[206:209], v[164:167], v[38:41]
	v_mfma_f32_16x16x32_bf16 v[34:37], v[206:209], v[172:175], v[34:37]
	v_mfma_f32_16x16x32_bf16 v[62:65], v[184:187], v[168:171], v[62:65]
	v_mfma_f32_16x16x32_bf16 v[58:61], v[184:187], v[176:179], v[58:61]
	v_mfma_f32_16x16x32_bf16 v[54:57], v[192:195], v[168:171], v[54:57]
	v_mfma_f32_16x16x32_bf16 v[50:53], v[192:195], v[176:179], v[50:53]
	v_mfma_f32_16x16x32_bf16 v[46:49], v[202:205], v[168:171], v[46:49]
	v_mfma_f32_16x16x32_bf16 v[42:45], v[202:205], v[176:179], v[42:45]
	v_mfma_f32_16x16x32_bf16 v[38:41], v[216:219], v[168:171], v[38:41]
	v_mfma_f32_16x16x32_bf16 v[34:37], v[216:219], v[176:179], v[34:37]
	v_mfma_f32_16x16x32_bf16 v[30:33], v[180:183], v[222:225], v[30:33]
	v_mfma_f32_16x16x32_bf16 v[26:29], v[180:183], v[232:235], v[26:29]
	v_mfma_f32_16x16x32_bf16 v[22:25], v[188:191], v[222:225], v[22:25]
	v_mfma_f32_16x16x32_bf16 v[18:21], v[188:191], v[232:235], v[18:21]
	v_mfma_f32_16x16x32_bf16 v[14:17], v[196:199], v[222:225], v[14:17]
	v_mfma_f32_16x16x32_bf16 v[10:13], v[196:199], v[232:235], v[10:13]
	v_mfma_f32_16x16x32_bf16 v[6:9], v[206:209], v[222:225], v[6:9]
	v_mfma_f32_16x16x32_bf16 v[2:5], v[206:209], v[232:235], v[2:5]
	v_mfma_f32_16x16x32_bf16 v[30:33], v[184:187], v[228:231], v[30:33]
	v_mfma_f32_16x16x32_bf16 v[26:29], v[184:187], v[236:239], v[26:29]
	v_mfma_f32_16x16x32_bf16 v[22:25], v[192:195], v[228:231], v[22:25]
	v_mfma_f32_16x16x32_bf16 v[18:21], v[192:195], v[236:239], v[18:21]
	v_mfma_f32_16x16x32_bf16 v[14:17], v[202:205], v[228:231], v[14:17]
	v_mfma_f32_16x16x32_bf16 v[10:13], v[202:205], v[236:239], v[10:13]
	v_mfma_f32_16x16x32_bf16 v[6:9], v[216:219], v[228:231], v[6:9]
	v_mfma_f32_16x16x32_bf16 v[2:5], v[216:219], v[236:239], v[2:5]
	s_setprio 0
	s_barrier
	ds_read_b128 v[164:167], v148
	ds_read_b128 v[168:171], v148 offset:1024
	ds_read_b128 v[172:175], v148 offset:2048
	ds_read_b128 v[176:179], v148 offset:3072
	ds_read_b128 v[180:183], v146 offset:32768
	ds_read_b128 v[184:187], v146 offset:33792
	ds_read_b128 v[188:191], v145 offset:32768
	ds_read_b128 v[192:195], v145 offset:33792
	ds_read_b128 v[196:199], v144 offset:32768
	ds_read_b128 v[202:205], v144 offset:33792
	ds_read_b128 v[206:209], v143 offset:32768
	ds_read_b128 v[216:219], v143 offset:33792
	s_waitcnt lgkmcnt(6)
	ds_read_b128 v[222:225], v147
	ds_read_b128 v[228:231], v147 offset:1024
	ds_read_b128 v[232:235], v147 offset:2048
	ds_read_b128 v[236:239], v147 offset:3072
	v_readfirstlane_b32 s2, v134
	v_lshl_add_u64 v[246:247], v[210:211], 0, s[44:45]
	s_mov_b32 m0, s2
	v_readfirstlane_b32 s2, v133
	global_load_lds_dwordx4 v[246:247], off
	v_lshl_add_u64 v[246:247], v[210:211], 0, s[46:47]
	s_mov_b32 m0, s2
	s_nop 0
	global_load_lds_dwordx4 v[246:247], off
	s_waitcnt vmcnt(8)
	s_barrier
	s_waitcnt lgkmcnt(0)
	s_setprio 1
	v_mfma_f32_16x16x32_bf16 v[126:129], v[180:183], v[164:167], v[126:129]
	v_mfma_f32_16x16x32_bf16 v[122:125], v[180:183], v[172:175], v[122:125]
	v_mfma_f32_16x16x32_bf16 v[118:121], v[188:191], v[164:167], v[118:121]
	v_mfma_f32_16x16x32_bf16 v[114:117], v[188:191], v[172:175], v[114:117]
	v_mfma_f32_16x16x32_bf16 v[110:113], v[196:199], v[164:167], v[110:113]
	v_mfma_f32_16x16x32_bf16 v[106:109], v[196:199], v[172:175], v[106:109]
	v_mfma_f32_16x16x32_bf16 v[102:105], v[206:209], v[164:167], v[102:105]
	v_mfma_f32_16x16x32_bf16 v[98:101], v[206:209], v[172:175], v[98:101]
	v_mfma_f32_16x16x32_bf16 v[126:129], v[184:187], v[168:171], v[126:129]
	v_mfma_f32_16x16x32_bf16 v[122:125], v[184:187], v[176:179], v[122:125]
	v_mfma_f32_16x16x32_bf16 v[118:121], v[192:195], v[168:171], v[118:121]
	v_mfma_f32_16x16x32_bf16 v[114:117], v[192:195], v[176:179], v[114:117]
	v_mfma_f32_16x16x32_bf16 v[110:113], v[202:205], v[168:171], v[110:113]
	v_mfma_f32_16x16x32_bf16 v[106:109], v[202:205], v[176:179], v[106:109]
	v_mfma_f32_16x16x32_bf16 v[102:105], v[216:219], v[168:171], v[102:105]
	v_mfma_f32_16x16x32_bf16 v[98:101], v[216:219], v[176:179], v[98:101]
	v_mfma_f32_16x16x32_bf16 v[94:97], v[180:183], v[222:225], v[94:97]
	v_mfma_f32_16x16x32_bf16 v[90:93], v[180:183], v[232:235], v[90:93]
	v_mfma_f32_16x16x32_bf16 v[86:89], v[188:191], v[222:225], v[86:89]
	v_mfma_f32_16x16x32_bf16 v[82:85], v[188:191], v[232:235], v[82:85]
	v_mfma_f32_16x16x32_bf16 v[78:81], v[196:199], v[222:225], v[78:81]
	v_mfma_f32_16x16x32_bf16 v[74:77], v[196:199], v[232:235], v[74:77]
	v_mfma_f32_16x16x32_bf16 v[70:73], v[206:209], v[222:225], v[70:73]
	v_mfma_f32_16x16x32_bf16 v[66:69], v[206:209], v[232:235], v[66:69]
	v_mfma_f32_16x16x32_bf16 v[94:97], v[184:187], v[228:231], v[94:97]
	v_mfma_f32_16x16x32_bf16 v[90:93], v[184:187], v[236:239], v[90:93]
	v_mfma_f32_16x16x32_bf16 v[86:89], v[192:195], v[228:231], v[86:89]
	v_mfma_f32_16x16x32_bf16 v[82:85], v[192:195], v[236:239], v[82:85]
	v_mfma_f32_16x16x32_bf16 v[78:81], v[202:205], v[228:231], v[78:81]
	v_mfma_f32_16x16x32_bf16 v[74:77], v[202:205], v[236:239], v[74:77]
	v_mfma_f32_16x16x32_bf16 v[70:73], v[216:219], v[228:231], v[70:73]
	v_mfma_f32_16x16x32_bf16 v[66:69], v[216:219], v[236:239], v[66:69]
	s_setprio 0
	s_barrier
; #define STAGE_B(P, br, kt) do { const char* _gb = (const char*)(Bt + ((long)(br) * K + (long)(kt) * BK)); \
;     __builtin_amdgcn_global_load_lds((const unsigned*)(_gb + bofl0), (unsigned*)((char*)(P) + gtid_ * 16), 16, 0, 0); \
;     __builtin_amdgcn_global_load_lds((const unsigned*)(_gb + (long)K * 128 + bofl0), (unsigned*)((char*)(P) + gtid_ * 16 + 8192), 16, 0, 0); } while (0)
; #define LDA(dst, b, h) for (int m = 0; m < 4; ++m) for (int k = 0; k < 2; ++k) \
;     dst[m][k] = *reinterpret_cast<const bf16x8*>((char*)SA(b, h) + lds_byte(wr * 64 + m * 16 + fr, k * 32 + fq * 8))
; #define LDB(dst, b, h) for (int n = 0; n < 2; ++n) for (int k = 0; k < 2; ++k) \
;     dst[n][k] = *reinterpret_cast<const bf16x8*>((char*)SB(b, h) + lds_byte(wc * 32 + n * 16 + fr, k * 32 + fq * 8))
; #define MMA(ai, bj, At_, Bt_) do { __builtin_amdgcn_s_setprio(1); \
;     for (int m = 0; m < 4; ++m) for (int n = 0; n < 2; ++n) for (int k = 0; k < 2; ++k) \
;       acc[ai][bj][m][n] = __builtin_amdgcn_mfma_f32_16x16x32_bf16(At_[m][k], Bt_[n][k], acc[ai][bj][m][n], 0, 0, 0); \
;     __builtin_amdgcn_s_setprio(0); } while (0)
; #define WAIT_V(n) asm volatile("s_waitcnt vmcnt(" #n ")" ::: "memory")
; #define WAIT_L(n) asm volatile("s_waitcnt lgkmcnt(" #n ")" ::: "memory")
; #define BAR __builtin_amdgcn_s_barrier()
; #define SCHED __builtin_amdgcn_sched_barrier(0)
; template <int EPI>
; __device__ __forceinline__ void gemm_tile(const GemmArgs& g, int brow, int bcol, int parity, bool first, bool nvalid, int nbrow, int nbcol) {
;     ...
;     BAR; WAIT_L(0); MMA(1, 0, At, B0); BAR; SCHED;
;     STAGE_B(SB(1, 1), bcol + HALF, t + 3);
;     WAIT_V(6); BAR; MMA(1, 1, At, B1); BAR; SCHED;
;   }
;   { LDB(B0, 0, 0); LDA(At, 0, 0); STAGE_A(SA(1, 1), brow + HALF, nt - 1);
;     BAR; WAIT_L(0); MMA(0, 0, At, B0); BAR;
	ds_read_b128 v[180:183], v146 offset:49152
	ds_read_b128 v[184:187], v146 offset:50176
	ds_read_b128 v[188:191], v145 offset:49152
	ds_read_b128 v[192:195], v145 offset:50176
	ds_read_b128 v[196:199], v144 offset:49152
	ds_read_b128 v[202:205], v144 offset:50176
	ds_read_b128 v[206:209], v143 offset:49152
	ds_read_b128 v[216:219], v143 offset:50176
	v_readfirstlane_b32 s2, v149
	v_lshl_add_u64 v[240:241], v[212:213], 0, s[58:59]
	s_mov_b32 m0, s2
	v_readfirstlane_b32 s2, v151
	global_load_lds_dwordx4 v[240:241], off
	v_lshl_add_u64 v[240:241], v[212:213], 0, s[76:77]
	s_mov_b32 m0, s2
	s_nop 0
	global_load_lds_dwordx4 v[240:241], off
	v_readfirstlane_b32 s2, v152
	v_lshl_add_u64 v[240:241], v[210:211], 0, s[48:49]
	s_mov_b32 m0, s2
	v_readfirstlane_b32 s2, v153
	global_load_lds_dwordx4 v[240:241], off
	v_lshl_add_u64 v[210:211], v[210:211], 0, s[50:51]
	s_mov_b32 m0, s2
	s_nop 0
	global_load_lds_dwordx4 v[210:211], off
	v_readfirstlane_b32 s2, v155
	v_lshl_add_u64 v[244:245], v[212:213], 0, s[96:97]
	s_mov_b32 m0, s2
	v_readfirstlane_b32 s2, v156
	global_load_lds_dwordx4 v[244:245], off
	v_lshl_add_u64 v[244:245], v[212:213], 0, s[60:61]
	s_mov_b32 m0, s2
	s_nop 0
	global_load_lds_dwordx4 v[244:245], off
	s_waitcnt vmcnt(8)
	s_barrier
	s_waitcnt lgkmcnt(0)
	s_setprio 1
	v_mfma_f32_16x16x32_bf16 v[62:65], v[180:183], v[164:167], v[62:65]
	v_mfma_f32_16x16x32_bf16 v[58:61], v[180:183], v[172:175], v[58:61]
	v_mfma_f32_16x16x32_bf16 v[54:57], v[188:191], v[164:167], v[54:57]
	v_mfma_f32_16x16x32_bf16 v[50:53], v[188:191], v[172:175], v[50:53]
	v_mfma_f32_16x16x32_bf16 v[46:49], v[196:199], v[164:167], v[46:49]
	v_mfma_f32_16x16x32_bf16 v[42:45], v[196:199], v[172:175], v[42:45]
	v_mfma_f32_16x16x32_bf16 v[38:41], v[206:209], v[164:167], v[38:41]
	v_mfma_f32_16x16x32_bf16 v[34:37], v[206:209], v[172:175], v[34:37]
	v_mfma_f32_16x16x32_bf16 v[62:65], v[184:187], v[168:171], v[62:65]
	v_mfma_f32_16x16x32_bf16 v[58:61], v[184:187], v[176:179], v[58:61]
	v_mfma_f32_16x16x32_bf16 v[54:57], v[192:195], v[168:171], v[54:57]
	v_mfma_f32_16x16x32_bf16 v[50:53], v[192:195], v[176:179], v[50:53]
	v_mfma_f32_16x16x32_bf16 v[46:49], v[202:205], v[168:171], v[46:49]
	v_mfma_f32_16x16x32_bf16 v[42:45], v[202:205], v[176:179], v[42:45]
	v_mfma_f32_16x16x32_bf16 v[38:41], v[216:219], v[168:171], v[38:41]
	v_mfma_f32_16x16x32_bf16 v[34:37], v[216:219], v[176:179], v[34:37]
	v_mfma_f32_16x16x32_bf16 v[30:33], v[180:183], v[222:225], v[30:33]
	v_mfma_f32_16x16x32_bf16 v[26:29], v[180:183], v[232:235], v[26:29]
	v_mfma_f32_16x16x32_bf16 v[22:25], v[188:191], v[222:225], v[22:25]
	v_mfma_f32_16x16x32_bf16 v[18:21], v[188:191], v[232:235], v[18:21]
	v_mfma_f32_16x16x32_bf16 v[14:17], v[196:199], v[222:225], v[14:17]
	v_mfma_f32_16x16x32_bf16 v[10:13], v[196:199], v[232:235], v[10:13]
	v_mfma_f32_16x16x32_bf16 v[6:9], v[206:209], v[222:225], v[6:9]
	v_mfma_f32_16x16x32_bf16 v[2:5], v[206:209], v[232:235], v[2:5]
	v_mfma_f32_16x16x32_bf16 v[30:33], v[184:187], v[228:231], v[30:33]
	v_mfma_f32_16x16x32_bf16 v[26:29], v[184:187], v[236:239], v[26:29]
	v_mfma_f32_16x16x32_bf16 v[22:25], v[192:195], v[228:231], v[22:25]
	v_mfma_f32_16x16x32_bf16 v[18:21], v[192:195], v[236:239], v[18:21]
	v_mfma_f32_16x16x32_bf16 v[14:17], v[202:205], v[228:231], v[14:17]
	v_mfma_f32_16x16x32_bf16 v[10:13], v[202:205], v[236:239], v[10:13]
	v_mfma_f32_16x16x32_bf16 v[6:9], v[216:219], v[228:231], v[6:9]
	v_mfma_f32_16x16x32_bf16 v[2:5], v[216:219], v[236:239], v[2:5]
	s_setprio 0
	s_barrier
	s_add_i32 s22, s22, 2
	s_add_u32 s12, s12, 0x100
	s_addc_u32 s13, s13, 0
	s_add_u32 s0, s0, 0x100
	s_addc_u32 s1, s1, 0
	s_cmp_lt_u32 s22, 12
	s_cbranch_scc1 .LBB0_133
	s_or_b32 s0, s40, 0x80
	s_ashr_i32 s1, s0, 31
	s_lshl_b64 s[0:1], s[0:1], 11
	s_add_u32 s0, s80, s0
	s_addc_u32 s1, s81, s1
	v_lshl_add_u64 v[130:131], s[0:1], 0, v[0:1]
	s_mov_b64 s[0:1], 0x780
	v_lshl_add_u64 v[152:153], v[130:131], 0, s[0:1]
	v_readfirstlane_b32 s0, v161
	s_mov_b32 m0, s0
	s_mov_b64 s[0:1], 0x20780
	v_lshl_add_u64 v[130:131], v[130:131], 0, s[0:1]
	v_readfirstlane_b32 s0, v162
	ds_read_b128 v[164:167], v157
	ds_read_b128 v[168:171], v157 offset:1024
	ds_read_b128 v[172:175], v157 offset:2048
	ds_read_b128 v[176:179], v157 offset:3072
	ds_read_b128 v[180:183], v146
	ds_read_b128 v[184:187], v146 offset:1024
	ds_read_b128 v[188:191], v145
	ds_read_b128 v[192:195], v145 offset:1024
	ds_read_b128 v[196:199], v144
	ds_read_b128 v[202:205], v144 offset:1024
	ds_read_b128 v[206:209], v143
	ds_read_b128 v[216:219], v143 offset:1024
	global_load_lds_dwordx4 v[152:153], off
	s_mov_b32 m0, s0
	s_nop 0
	global_load_lds_dwordx4 v[130:131], off
	s_waitcnt vmcnt(8)
	s_barrier
	s_waitcnt lgkmcnt(0)
	s_setprio 1
	s_waitcnt lgkmcnt(0)
	v_mfma_f32_16x16x32_bf16 v[126:129], v[180:183], v[164:167], v[126:129]
	v_mfma_f32_16x16x32_bf16 v[122:125], v[180:183], v[172:175], v[122:125]
	v_mfma_f32_16x16x32_bf16 v[110:113], v[196:199], v[164:167], v[110:113]
	v_mfma_f32_16x16x32_bf16 v[106:109], v[196:199], v[172:175], v[106:109]
	v_mfma_f32_16x16x32_bf16 v[126:129], v[184:187], v[168:171], v[126:129]
	v_mfma_f32_16x16x32_bf16 v[122:125], v[184:187], v[176:179], v[122:125]
	v_mfma_f32_16x16x32_bf16 v[118:121], v[188:191], v[164:167], v[118:121]
	v_mfma_f32_16x16x32_bf16 v[114:117], v[188:191], v[172:175], v[114:117]
	v_mfma_f32_16x16x32_bf16 v[110:113], v[202:205], v[168:171], v[110:113]
	v_mfma_f32_16x16x32_bf16 v[106:109], v[202:205], v[176:179], v[106:109]
	v_mfma_f32_16x16x32_bf16 v[102:105], v[206:209], v[164:167], v[102:105]
	v_mfma_f32_16x16x32_bf16 v[98:101], v[206:209], v[172:175], v[98:101]
	v_mfma_f32_16x16x32_bf16 v[222:225], v[192:195], v[168:171], v[118:121]
	v_mfma_f32_16x16x32_bf16 v[228:231], v[192:195], v[176:179], v[114:117]
	v_mfma_f32_16x16x32_bf16 v[232:235], v[216:219], v[168:171], v[102:105]
	v_mfma_f32_16x16x32_bf16 v[236:239], v[216:219], v[176:179], v[98:101]
	s_setprio 0
	s_barrier
; #define LDA(dst, b, h) for (int m = 0; m < 4; ++m) for (int k = 0; k < 2; ++k) \
;     dst[m][k] = *reinterpret_cast<const bf16x8*>((char*)SA(b, h) + lds_byte(wr * 64 + m * 16 + fr, k * 32 + fq * 8))
; #define LDB(dst, b, h) for (int n = 0; n < 2; ++n) for (int k = 0; k < 2; ++k) \
;     dst[n][k] = *reinterpret_cast<const bf16x8*>((char*)SB(b, h) + lds_byte(wc * 32 + n * 16 + fr, k * 32 + fq * 8))
; #define MMA(ai, bj, At_, Bt_) do { __builtin_amdgcn_s_setprio(1); \
;     for (int m = 0; m < 4; ++m) for (int n = 0; n < 2; ++n) for (int k = 0; k < 2; ++k) \
;       acc[ai][bj][m][n] = __builtin_amdgcn_mfma_f32_16x16x32_bf16(At_[m][k], Bt_[n][k], acc[ai][bj][m][n], 0, 0, 0); \
;     __builtin_amdgcn_s_setprio(0); } while (0)
; #define WAIT_V(n) asm volatile("s_waitcnt vmcnt(" #n ")" ::: "memory")
; #define WAIT_L(n) asm volatile("s_waitcnt lgkmcnt(" #n ")" ::: "memory")
; #define BAR __builtin_amdgcn_s_barrier()
; #define SCHED __builtin_amdgcn_sched_barrier(0)
; template <int EPI>
; __device__ __forceinline__ void gemm_tile(const GemmArgs& g, int brow, int bcol, int parity, bool first, bool nvalid, int nbrow, int nbcol) {
;     ...
;   { LDB(B0, 0, 0); LDA(At, 0, 0); STAGE_A(SA(1, 1), brow + HALF, nt - 1);
;     BAR; WAIT_L(0); MMA(0, 0, At, B0); BAR;
;     LDB(B1, 0, 1); BAR; WAIT_L(0); MMA(0, 1, At, B1); BAR; SCHED;
;     LDA(At, 0, 1); WAIT_V(4); BAR; WAIT_L(0); MMA(1, 0, At, B0); MMA(1, 1, At, B1); BAR; }
;   { LDB(B0, 1, 0); LDA(At, 1, 0); WAIT_V(2); BAR; WAIT_L(0); MMA(0, 0, At, B0); BAR;
	s_nop 1
	ds_read_b128 v[98:101], v154
	ds_read_b128 v[102:105], v154 offset:1024
	ds_read_b128 v[114:117], v154 offset:2048
	ds_read_b128 v[118:121], v154 offset:3072
	s_barrier
	s_waitcnt lgkmcnt(0)
	s_setprio 1
	s_waitcnt lgkmcnt(0)
	v_mfma_f32_16x16x32_bf16 v[94:97], v[180:183], v[98:101], v[94:97]
	v_mfma_f32_16x16x32_bf16 v[90:93], v[180:183], v[114:117], v[90:93]
	v_mfma_f32_16x16x32_bf16 v[78:81], v[196:199], v[98:101], v[78:81]
	v_mfma_f32_16x16x32_bf16 v[74:77], v[196:199], v[114:117], v[74:77]
	v_mfma_f32_16x16x32_bf16 v[94:97], v[184:187], v[102:105], v[94:97]
	v_mfma_f32_16x16x32_bf16 v[90:93], v[184:187], v[118:121], v[90:93]
	v_mfma_f32_16x16x32_bf16 v[86:89], v[188:191], v[98:101], v[86:89]
	v_mfma_f32_16x16x32_bf16 v[82:85], v[188:191], v[114:117], v[82:85]
	v_mfma_f32_16x16x32_bf16 v[78:81], v[202:205], v[102:105], v[78:81]
	v_mfma_f32_16x16x32_bf16 v[74:77], v[202:205], v[118:121], v[74:77]
	v_mfma_f32_16x16x32_bf16 v[70:73], v[206:209], v[98:101], v[70:73]
	v_mfma_f32_16x16x32_bf16 v[66:69], v[206:209], v[114:117], v[66:69]
	v_mfma_f32_16x16x32_bf16 v[152:155], v[192:195], v[102:105], v[86:89]
	v_mfma_f32_16x16x32_bf16 v[180:183], v[192:195], v[118:121], v[82:85]
	v_mfma_f32_16x16x32_bf16 v[184:187], v[216:219], v[102:105], v[70:73]
	v_mfma_f32_16x16x32_bf16 v[188:191], v[216:219], v[118:121], v[66:69]
	s_setprio 0
	s_barrier
	s_nop 1
	ds_read_b128 v[66:69], v146 offset:16384
	ds_read_b128 v[70:73], v146 offset:17408
	ds_read_b128 v[82:85], v145 offset:16384
	ds_read_b128 v[86:89], v145 offset:17408
	ds_read_b128 v[192:195], v144 offset:16384
	ds_read_b128 v[196:199], v144 offset:17408
	ds_read_b128 v[202:205], v143 offset:16384
	ds_read_b128 v[206:209], v143 offset:17408
	s_waitcnt vmcnt(4)
	s_barrier
	s_waitcnt lgkmcnt(0)
	s_setprio 1
	s_waitcnt lgkmcnt(0)
	v_mfma_f32_16x16x32_bf16 v[62:65], v[66:69], v[164:167], v[62:65]
	v_mfma_f32_16x16x32_bf16 v[58:61], v[66:69], v[172:175], v[58:61]
	v_mfma_f32_16x16x32_bf16 v[46:49], v[192:195], v[164:167], v[46:49]
	v_mfma_f32_16x16x32_bf16 v[42:45], v[192:195], v[172:175], v[42:45]
	v_mfma_f32_16x16x32_bf16 v[62:65], v[70:73], v[168:171], v[62:65]
	v_mfma_f32_16x16x32_bf16 v[58:61], v[70:73], v[176:179], v[58:61]
	v_mfma_f32_16x16x32_bf16 v[54:57], v[82:85], v[164:167], v[54:57]
	v_mfma_f32_16x16x32_bf16 v[50:53], v[82:85], v[172:175], v[50:53]
	v_mfma_f32_16x16x32_bf16 v[46:49], v[196:199], v[168:171], v[46:49]
	v_mfma_f32_16x16x32_bf16 v[42:45], v[196:199], v[176:179], v[42:45]
	v_mfma_f32_16x16x32_bf16 v[38:41], v[202:205], v[164:167], v[38:41]
	v_mfma_f32_16x16x32_bf16 v[34:37], v[202:205], v[172:175], v[34:37]
	v_mfma_f32_16x16x32_bf16 v[216:219], v[86:89], v[168:171], v[54:57]
	v_mfma_f32_16x16x32_bf16 v[240:243], v[86:89], v[176:179], v[50:53]
	v_mfma_f32_16x16x32_bf16 v[162:165], v[206:209], v[168:171], v[38:41]
	v_mfma_f32_16x16x32_bf16 v[166:169], v[206:209], v[176:179], v[34:37]
	s_setprio 0
	s_setprio 1
	v_mfma_f32_16x16x32_bf16 v[30:33], v[66:69], v[98:101], v[30:33]
	v_mfma_f32_16x16x32_bf16 v[26:29], v[66:69], v[114:117], v[26:29]
	v_mfma_f32_16x16x32_bf16 v[14:17], v[192:195], v[98:101], v[14:17]
	v_mfma_f32_16x16x32_bf16 v[10:13], v[192:195], v[114:117], v[10:13]
	v_mfma_f32_16x16x32_bf16 v[30:33], v[70:73], v[102:105], v[30:33]
	v_mfma_f32_16x16x32_bf16 v[26:29], v[70:73], v[118:121], v[26:29]
	v_mfma_f32_16x16x32_bf16 v[22:25], v[82:85], v[98:101], v[22:25]
	v_mfma_f32_16x16x32_bf16 v[18:21], v[82:85], v[114:117], v[18:21]
	v_mfma_f32_16x16x32_bf16 v[14:17], v[196:199], v[102:105], v[14:17]
	v_mfma_f32_16x16x32_bf16 v[10:13], v[196:199], v[118:121], v[10:13]
	v_mfma_f32_16x16x32_bf16 v[6:9], v[202:205], v[98:101], v[6:9]
	v_mfma_f32_16x16x32_bf16 v[2:5], v[202:205], v[114:117], v[2:5]
	v_mfma_f32_16x16x32_bf16 v[170:173], v[86:89], v[102:105], v[22:25]
	v_mfma_f32_16x16x32_bf16 v[174:177], v[86:89], v[118:121], v[18:21]
	v_mfma_f32_16x16x32_bf16 v[192:195], v[206:209], v[102:105], v[6:9]
	v_mfma_f32_16x16x32_bf16 v[196:199], v[206:209], v[118:121], v[2:5]
	s_setprio 0
	s_barrier
	s_nop 1
	ds_read_b128 v[2:5], v148
	ds_read_b128 v[6:9], v148 offset:1024
	ds_read_b128 v[202:205], v148 offset:2048
	ds_read_b128 v[206:209], v148 offset:3072
	ds_read_b128 v[18:21], v146 offset:32768
	ds_read_b128 v[22:25], v146 offset:33792
	ds_read_b128 v[34:37], v145 offset:32768
	ds_read_b128 v[38:41], v145 offset:33792
	ds_read_b128 v[50:53], v144 offset:32768
	ds_read_b128 v[54:57], v144 offset:33792
	ds_read_b128 v[244:247], v143 offset:32768
	ds_read_b128 v[248:251], v143 offset:33792
	s_waitcnt vmcnt(2)
	s_barrier
; #define LDA(dst, b, h) for (int m = 0; m < 4; ++m) for (int k = 0; k < 2; ++k) \
;     dst[m][k] = *reinterpret_cast<const bf16x8*>((char*)SA(b, h) + lds_byte(wr * 64 + m * 16 + fr, k * 32 + fq * 8))
; #define LDB(dst, b, h) for (int n = 0; n < 2; ++n) for (int k = 0; k < 2; ++k) \
;     dst[n][k] = *reinterpret_cast<const bf16x8*>((char*)SB(b, h) + lds_byte(wc * 32 + n * 16 + fr, k * 32 + fq * 8))
; #define MMA(ai, bj, At_, Bt_) do { __builtin_amdgcn_s_setprio(1); \
;     for (int m = 0; m < 4; ++m) for (int n = 0; n < 2; ++n) for (int k = 0; k < 2; ++k) \
;       acc[ai][bj][m][n] = __builtin_amdgcn_mfma_f32_16x16x32_bf16(At_[m][k], Bt_[n][k], acc[ai][bj][m][n], 0, 0, 0); \
;     __builtin_amdgcn_s_setprio(0); } while (0)
; #define WAIT_V(n) asm volatile("s_waitcnt vmcnt(" #n ")" ::: "memory")
; #define WAIT_L(n) asm volatile("s_waitcnt lgkmcnt(" #n ")" ::: "memory")
; #define BAR __builtin_amdgcn_s_barrier()
; #define SCHED __builtin_amdgcn_sched_barrier(0)
; template <int EPI>
; __device__ __forceinline__ void gemm_tile(const GemmArgs& g, int brow, int bcol, int parity, bool first, bool nvalid, int nbrow, int nbcol) {
;     ...
;     LDA(At, 0, 1); WAIT_V(4); BAR; WAIT_L(0); MMA(1, 0, At, B0); MMA(1, 1, At, B1); BAR; }
;   { LDB(B0, 1, 0); LDA(At, 1, 0); WAIT_V(2); BAR; WAIT_L(0); MMA(0, 0, At, B0); BAR;
;     LDB(B1, 1, 1); WAIT_V(0); BAR; WAIT_L(0); MMA(0, 1, At, B1); BAR; SCHED;
;     LDA(At, 1, 1); BAR; WAIT_L(0); MMA(1, 0, At, B0); MMA(1, 1, At, B1); BAR; }
;   if (wr == 0) BAR;
	s_waitcnt lgkmcnt(0)
	s_setprio 1
	s_waitcnt lgkmcnt(0)
	v_mfma_f32_16x16x32_bf16 v[66:69], v[18:21], v[2:5], v[126:129]
	v_mfma_f32_16x16x32_bf16 v[114:117], v[22:25], v[6:9], v[66:69]
	v_mfma_f32_16x16x32_bf16 v[66:69], v[18:21], v[202:205], v[122:125]
	v_mfma_f32_16x16x32_bf16 v[118:121], v[22:25], v[206:209], v[66:69]
	v_mfma_f32_16x16x32_bf16 v[66:69], v[34:37], v[2:5], v[222:225]
	v_mfma_f32_16x16x32_bf16 v[98:101], v[38:41], v[6:9], v[66:69]
	v_mfma_f32_16x16x32_bf16 v[66:69], v[34:37], v[202:205], v[228:231]
	v_mfma_f32_16x16x32_bf16 v[102:105], v[38:41], v[206:209], v[66:69]
	v_mfma_f32_16x16x32_bf16 v[66:69], v[50:53], v[2:5], v[110:113]
	v_mfma_f32_16x16x32_bf16 v[82:85], v[54:57], v[6:9], v[66:69]
	v_mfma_f32_16x16x32_bf16 v[66:69], v[50:53], v[202:205], v[106:109]
	v_mfma_f32_16x16x32_bf16 v[86:89], v[54:57], v[206:209], v[66:69]
	v_mfma_f32_16x16x32_bf16 v[66:69], v[244:247], v[2:5], v[232:235]
	v_mfma_f32_16x16x32_bf16 v[70:73], v[244:247], v[202:205], v[236:239]
	v_mfma_f32_16x16x32_bf16 v[66:69], v[248:251], v[6:9], v[66:69]
	v_mfma_f32_16x16x32_bf16 v[70:73], v[248:251], v[206:209], v[70:73]
	s_setprio 0
	s_barrier
	ds_read_b128 v[222:225], v147
	ds_read_b128 v[228:231], v147 offset:1024
	ds_read_b128 v[232:235], v147 offset:2048
	ds_read_b128 v[236:239], v147 offset:3072
	s_waitcnt vmcnt(0)
	s_barrier
	s_waitcnt lgkmcnt(0)
	s_setprio 1
	s_waitcnt lgkmcnt(0)
	v_mfma_f32_16x16x32_bf16 v[94:97], v[18:21], v[222:225], v[94:97]
	v_mfma_f32_16x16x32_bf16 v[18:21], v[18:21], v[232:235], v[90:93]
	v_mfma_f32_16x16x32_bf16 v[122:125], v[22:25], v[236:239], v[18:21]
	v_mfma_f32_16x16x32_bf16 v[18:21], v[34:37], v[222:225], v[152:155]
	v_mfma_f32_16x16x32_bf16 v[110:113], v[38:41], v[228:231], v[18:21]
	v_mfma_f32_16x16x32_bf16 v[18:21], v[34:37], v[232:235], v[180:183]
	v_mfma_f32_16x16x32_bf16 v[106:109], v[38:41], v[236:239], v[18:21]
	v_mfma_f32_16x16x32_bf16 v[18:21], v[50:53], v[222:225], v[78:81]
	v_mfma_f32_16x16x32_bf16 v[126:129], v[22:25], v[228:231], v[94:97]
	v_mfma_f32_16x16x32_bf16 v[94:97], v[54:57], v[228:231], v[18:21]
	v_mfma_f32_16x16x32_bf16 v[18:21], v[50:53], v[232:235], v[74:77]
	v_mfma_f32_16x16x32_bf16 v[90:93], v[54:57], v[236:239], v[18:21]
	v_mfma_f32_16x16x32_bf16 v[18:21], v[244:247], v[222:225], v[184:187]
	v_mfma_f32_16x16x32_bf16 v[78:81], v[248:251], v[228:231], v[18:21]
	v_mfma_f32_16x16x32_bf16 v[18:21], v[244:247], v[232:235], v[188:191]
	v_mfma_f32_16x16x32_bf16 v[74:77], v[248:251], v[236:239], v[18:21]
	s_setprio 0
	s_barrier
	ds_read_b128 v[152:155], v146 offset:49152
	ds_read_b128 v[146:149], v146 offset:50176
	ds_read_b128 v[178:181], v145 offset:49152
	ds_read_b128 v[182:185], v145 offset:50176
	ds_read_b128 v[186:189], v144 offset:49152
	ds_read_b128 v[244:247], v144 offset:50176
	ds_read_b128 v[248:251], v143 offset:49152
	ds_read_b128 v[210:213], v143 offset:50176
	s_barrier
	s_waitcnt lgkmcnt(0)
	s_setprio 1
	s_waitcnt lgkmcnt(0)
	v_mfma_f32_16x16x32_bf16 v[18:21], v[152:155], v[2:5], v[62:65]
	v_mfma_f32_16x16x32_bf16 v[50:53], v[146:149], v[6:9], v[18:21]
	v_mfma_f32_16x16x32_bf16 v[18:21], v[152:155], v[202:205], v[58:61]
	v_mfma_f32_16x16x32_bf16 v[54:57], v[146:149], v[206:209], v[18:21]
	v_mfma_f32_16x16x32_bf16 v[18:21], v[178:181], v[2:5], v[216:219]
	v_mfma_f32_16x16x32_bf16 v[34:37], v[182:185], v[6:9], v[18:21]
	v_mfma_f32_16x16x32_bf16 v[18:21], v[178:181], v[202:205], v[240:243]
	v_mfma_f32_16x16x32_bf16 v[38:41], v[182:185], v[206:209], v[18:21]
	v_mfma_f32_16x16x32_bf16 v[18:21], v[186:189], v[2:5], v[46:49]
	v_mfma_f32_16x16x32_bf16 v[2:5], v[248:251], v[2:5], v[162:165]
	v_mfma_f32_16x16x32_bf16 v[18:21], v[244:247], v[6:9], v[18:21]
	v_mfma_f32_16x16x32_bf16 v[22:25], v[186:189], v[202:205], v[42:45]
	v_mfma_f32_16x16x32_bf16 v[2:5], v[210:213], v[6:9], v[2:5]
	v_mfma_f32_16x16x32_bf16 v[6:9], v[248:251], v[202:205], v[166:169]
	v_mfma_f32_16x16x32_bf16 v[22:25], v[244:247], v[206:209], v[22:25]
	v_mfma_f32_16x16x32_bf16 v[6:9], v[210:213], v[206:209], v[6:9]
	s_setprio 0
	s_setprio 1
	v_mfma_f32_16x16x32_bf16 v[26:29], v[152:155], v[232:235], v[26:29]
	v_mfma_f32_16x16x32_bf16 v[58:61], v[146:149], v[236:239], v[26:29]
	v_mfma_f32_16x16x32_bf16 v[26:29], v[178:181], v[222:225], v[170:173]
	v_mfma_f32_16x16x32_bf16 v[46:49], v[182:185], v[228:231], v[26:29]
	v_mfma_f32_16x16x32_bf16 v[26:29], v[178:181], v[232:235], v[174:177]
	v_mfma_f32_16x16x32_bf16 v[10:13], v[186:189], v[232:235], v[10:13]
	v_mfma_f32_16x16x32_bf16 v[30:33], v[152:155], v[222:225], v[30:33]
	v_mfma_f32_16x16x32_bf16 v[42:45], v[182:185], v[236:239], v[26:29]
	v_mfma_f32_16x16x32_bf16 v[14:17], v[186:189], v[222:225], v[14:17]
	v_mfma_f32_16x16x32_bf16 v[26:29], v[244:247], v[236:239], v[10:13]
	v_mfma_f32_16x16x32_bf16 v[10:13], v[248:251], v[222:225], v[192:195]
	v_mfma_f32_16x16x32_bf16 v[62:65], v[146:149], v[228:231], v[30:33]
	v_mfma_f32_16x16x32_bf16 v[30:33], v[244:247], v[228:231], v[14:17]
	v_mfma_f32_16x16x32_bf16 v[14:17], v[210:213], v[228:231], v[10:13]
	v_mfma_f32_16x16x32_bf16 v[10:13], v[248:251], v[232:235], v[196:199]
	v_mfma_f32_16x16x32_bf16 v[10:13], v[210:213], v[236:239], v[10:13]
	s_setprio 0
	s_movk_i32 s0, 0x100
	v_cmp_gt_u32_e32 vcc, s0, v138
	s_barrier
	s_and_saveexec_b64 s[0:1], vcc
	s_cbranch_execz .LBB0_136
	s_barrier

; #define STAGE_B(P, br, kt) do { const char* _gb = (const char*)(Bt + ((long)(br) * K + (long)(kt) * BK)); \
;     __builtin_amdgcn_global_load_lds((const unsigned*)(_gb + bofl0), (unsigned*)((char*)(P) + gtid_ * 16), 16, 0, 0); \
;     __builtin_amdgcn_global_load_lds((const unsigned*)(_gb + (long)K * 128 + bofl0), (unsigned*)((char*)(P) + gtid_ * 16 + 8192), 16, 0, 0); } while (0)
; #define LDA(dst, b, h) for (int m = 0; m < 4; ++m) for (int k = 0; k < 2; ++k) \
;     dst[m][k] = *reinterpret_cast<const bf16x8*>((char*)SA(b, h) + lds_byte(wr * 64 + m * 16 + fr, k * 32 + fq * 8))
; #define LDB(dst, b, h) for (int n = 0; n < 2; ++n) for (int k = 0; k < 2; ++k) \
;     dst[n][k] = *reinterpret_cast<const bf16x8*>((char*)SB(b, h) + lds_byte(wc * 32 + n * 16 + fr, k * 32 + fq * 8))
; #define MMA(ai, bj, At_, Bt_) do { __builtin_amdgcn_s_setprio(1); \
;     for (int m = 0; m < 4; ++m) for (int n = 0; n < 2; ++n) for (int k = 0; k < 2; ++k) \
;       acc[ai][bj][m][n] = __builtin_amdgcn_mfma_f32_16x16x32_bf16(At_[m][k], Bt_[n][k], acc[ai][bj][m][n], 0, 0, 0); \
;     __builtin_amdgcn_s_setprio(0); } while (0)
; #define WAIT_V(n) asm volatile("s_waitcnt vmcnt(" #n ")" ::: "memory")
; #define WAIT_L(n) asm volatile("s_waitcnt lgkmcnt(" #n ")" ::: "memory")
; #define BAR __builtin_amdgcn_s_barrier()
; #define SCHED __builtin_amdgcn_sched_barrier(0)
; template <int EPI>
; __device__ __forceinline__ void gemm_tile(const GemmArgs& g, int brow, int bcol, int parity, bool first, bool nvalid, int nbrow, int nbcol) {
;     ...
;   for (int t = 0; t < nt - 2; t += 2) {
;     LDB(B0, 0, 0); SCHED; LDA(At, 0, 0); STAGE_A(SA(1, 1), brow + HALF, t + 1);
;     WAIT_L(8); BAR; WAIT_L(0); MMA(0, 0, At, B0); BAR; SCHED;
;     LDB(B1, 0, 1); STAGE_B(SB(0, 0), bcol, t + 2);
;     BAR; WAIT_L(0); MMA(0, 1, At, B1); BAR; SCHED;
;     LDA(At, 0, 1); STAGE_A(SA(0, 0), brow, t + 2);
;     BAR; WAIT_L(0); MMA(1, 0, At, B0); BAR; SCHED;
;     STAGE_B(SB(0, 1), bcol + HALF, t + 2);
;     WAIT_V(6); BAR; MMA(1, 1, At, B1); BAR; SCHED;
.LBB0_166:
	ds_read_b128 v[164:167], v157
	ds_read_b128 v[168:171], v157 offset:1024
	ds_read_b128 v[172:175], v157 offset:2048
	ds_read_b128 v[176:179], v157 offset:3072
	ds_read_b128 v[180:183], v147
	ds_read_b128 v[184:187], v147 offset:1024
	ds_read_b128 v[188:191], v146
	ds_read_b128 v[192:195], v146 offset:1024
	ds_read_b128 v[196:199], v145
	ds_read_b128 v[202:205], v145 offset:1024
	ds_read_b128 v[206:209], v144
	ds_read_b128 v[216:219], v144 offset:1024
	s_waitcnt lgkmcnt(6)
	ds_read_b128 v[222:225], v154
	ds_read_b128 v[228:231], v154 offset:1024
	ds_read_b128 v[232:235], v154 offset:2048
	ds_read_b128 v[236:239], v154 offset:3072
	v_add_u32_e32 v161, 0xc000, v137
	v_lshl_add_u64 v[210:211], s[0:1], 0, v[130:131]
	v_readfirstlane_b32 s2, v161
	v_add_u32_e32 v162, 0xe000, v137
	v_lshl_add_u64 v[158:159], v[210:211], 0, s[26:27]
	s_mov_b32 m0, s2
	v_readfirstlane_b32 s2, v162
	global_load_lds_dwordx4 v[158:159], off
	v_lshl_add_u64 v[158:159], v[210:211], 0, s[42:43]
	s_mov_b32 m0, s2
	s_nop 0
	global_load_lds_dwordx4 v[158:159], off
	s_waitcnt vmcnt(8)
	s_barrier
	s_waitcnt lgkmcnt(0)
	s_setprio 1
	v_mfma_f32_16x16x32_bf16 v[126:129], v[164:167], v[180:183], v[126:129]
	v_mfma_f32_16x16x32_bf16 v[122:125], v[172:175], v[180:183], v[122:125]
	v_mfma_f32_16x16x32_bf16 v[118:121], v[164:167], v[188:191], v[118:121]
	v_mfma_f32_16x16x32_bf16 v[114:117], v[172:175], v[188:191], v[114:117]
	v_mfma_f32_16x16x32_bf16 v[110:113], v[164:167], v[196:199], v[110:113]
	v_mfma_f32_16x16x32_bf16 v[106:109], v[172:175], v[196:199], v[106:109]
	v_mfma_f32_16x16x32_bf16 v[102:105], v[164:167], v[206:209], v[102:105]
	v_mfma_f32_16x16x32_bf16 v[98:101], v[172:175], v[206:209], v[98:101]
	v_mfma_f32_16x16x32_bf16 v[126:129], v[168:171], v[184:187], v[126:129]
	v_mfma_f32_16x16x32_bf16 v[122:125], v[176:179], v[184:187], v[122:125]
	v_mfma_f32_16x16x32_bf16 v[118:121], v[168:171], v[192:195], v[118:121]
	v_mfma_f32_16x16x32_bf16 v[114:117], v[176:179], v[192:195], v[114:117]
	v_mfma_f32_16x16x32_bf16 v[110:113], v[168:171], v[202:205], v[110:113]
	v_mfma_f32_16x16x32_bf16 v[106:109], v[176:179], v[202:205], v[106:109]
	v_mfma_f32_16x16x32_bf16 v[102:105], v[168:171], v[216:219], v[102:105]
	v_mfma_f32_16x16x32_bf16 v[98:101], v[176:179], v[216:219], v[98:101]
	v_mfma_f32_16x16x32_bf16 v[94:97], v[222:225], v[180:183], v[94:97]
	v_mfma_f32_16x16x32_bf16 v[90:93], v[232:235], v[180:183], v[90:93]
	v_mfma_f32_16x16x32_bf16 v[86:89], v[222:225], v[188:191], v[86:89]
	v_mfma_f32_16x16x32_bf16 v[82:85], v[232:235], v[188:191], v[82:85]
	v_mfma_f32_16x16x32_bf16 v[78:81], v[222:225], v[196:199], v[78:81]
	v_mfma_f32_16x16x32_bf16 v[74:77], v[232:235], v[196:199], v[74:77]
	v_mfma_f32_16x16x32_bf16 v[70:73], v[222:225], v[206:209], v[70:73]
	v_mfma_f32_16x16x32_bf16 v[66:69], v[232:235], v[206:209], v[66:69]
	v_mfma_f32_16x16x32_bf16 v[94:97], v[228:231], v[184:187], v[94:97]
	v_mfma_f32_16x16x32_bf16 v[90:93], v[236:239], v[184:187], v[90:93]
	v_mfma_f32_16x16x32_bf16 v[86:89], v[228:231], v[192:195], v[86:89]
	v_mfma_f32_16x16x32_bf16 v[82:85], v[236:239], v[192:195], v[82:85]
	v_mfma_f32_16x16x32_bf16 v[78:81], v[228:231], v[202:205], v[78:81]
	v_mfma_f32_16x16x32_bf16 v[74:77], v[236:239], v[202:205], v[74:77]
	v_mfma_f32_16x16x32_bf16 v[70:73], v[228:231], v[216:219], v[70:73]
	v_mfma_f32_16x16x32_bf16 v[66:69], v[236:239], v[216:219], v[66:69]
	s_setprio 0
	s_barrier
	ds_read_b128 v[180:183], v147 offset:16384
	ds_read_b128 v[184:187], v147 offset:17408
	ds_read_b128 v[188:191], v146 offset:16384
	ds_read_b128 v[192:195], v146 offset:17408
	ds_read_b128 v[196:199], v145 offset:16384
	ds_read_b128 v[202:205], v145 offset:17408
	ds_read_b128 v[206:209], v144 offset:16384
	ds_read_b128 v[216:219], v144 offset:17408
	v_add_u32_e32 v158, s15, v142
	v_lshl_add_u64 v[212:213], s[12:13], 0, v[130:131]
	v_readfirstlane_b32 s2, v158
	v_add_u32_e32 v159, 0x2000, v158
	v_lshl_add_u64 v[240:241], v[212:213], 0, s[78:79]
	s_mov_b32 m0, s2
	v_readfirstlane_b32 s2, v159
	global_load_lds_dwordx4 v[240:241], off
	v_lshl_add_u64 v[240:241], v[212:213], 0, s[66:67]
	s_mov_b32 m0, s2
	s_nop 0
	global_load_lds_dwordx4 v[240:241], off
	v_readfirstlane_b32 s2, v137
	v_lshl_add_u64 v[240:241], v[210:211], 0, s[44:45]
	s_mov_b32 m0, s2
	v_readfirstlane_b32 s2, v136
	global_load_lds_dwordx4 v[240:241], off
	v_lshl_add_u64 v[240:241], v[210:211], 0, s[46:47]
	s_mov_b32 m0, s2
	s_nop 0
	global_load_lds_dwordx4 v[240:241], off
	v_readfirstlane_b32 s2, v135
	v_add_u32_e32 v160, 0x2000, v135
	v_lshl_add_u64 v[244:245], v[212:213], 0, s[76:77]
	s_mov_b32 m0, s2
	v_readfirstlane_b32 s2, v160
	global_load_lds_dwordx4 v[244:245], off
	v_lshl_add_u64 v[244:245], v[212:213], 0, s[96:97]
	s_mov_b32 m0, s2
	s_nop 0
	global_load_lds_dwordx4 v[244:245], off
	s_waitcnt vmcnt(8)
	s_barrier
; #define STAGE_B(P, br, kt) do { const char* _gb = (const char*)(Bt + ((long)(br) * K + (long)(kt) * BK)); \
;     __builtin_amdgcn_global_load_lds((const unsigned*)(_gb + bofl0), (unsigned*)((char*)(P) + gtid_ * 16), 16, 0, 0); \
;     __builtin_amdgcn_global_load_lds((const unsigned*)(_gb + (long)K * 128 + bofl0), (unsigned*)((char*)(P) + gtid_ * 16 + 8192), 16, 0, 0); } while (0)
; #define LDA(dst, b, h) for (int m = 0; m < 4; ++m) for (int k = 0; k < 2; ++k) \
;     dst[m][k] = *reinterpret_cast<const bf16x8*>((char*)SA(b, h) + lds_byte(wr * 64 + m * 16 + fr, k * 32 + fq * 8))
; #define LDB(dst, b, h) for (int n = 0; n < 2; ++n) for (int k = 0; k < 2; ++k) \
;     dst[n][k] = *reinterpret_cast<const bf16x8*>((char*)SB(b, h) + lds_byte(wc * 32 + n * 16 + fr, k * 32 + fq * 8))
; #define MMA(ai, bj, At_, Bt_) do { __builtin_amdgcn_s_setprio(1); \
;     for (int m = 0; m < 4; ++m) for (int n = 0; n < 2; ++n) for (int k = 0; k < 2; ++k) \
;       acc[ai][bj][m][n] = __builtin_amdgcn_mfma_f32_16x16x32_bf16(At_[m][k], Bt_[n][k], acc[ai][bj][m][n], 0, 0, 0); \
;     __builtin_amdgcn_s_setprio(0); } while (0)
; #define WAIT_V(n) asm volatile("s_waitcnt vmcnt(" #n ")" ::: "memory")
; #define WAIT_L(n) asm volatile("s_waitcnt lgkmcnt(" #n ")" ::: "memory")
; template <int EPI>
; __device__ __forceinline__ void gemm_tile(const GemmArgs& g, int brow, int bcol, int parity, bool first, bool nvalid, int nbrow, int nbcol) {
;     ...
;   for (int t = 0; t < nt - 2; t += 2) {
;     LDB(B0, 0, 0); SCHED; LDA(At, 0, 0); STAGE_A(SA(1, 1), brow + HALF, t + 1);
;     WAIT_L(8); BAR; WAIT_L(0); MMA(0, 0, At, B0); BAR; SCHED;
;     LDB(B1, 0, 1); STAGE_B(SB(0, 0), bcol, t + 2);
;     BAR; WAIT_L(0); MMA(0, 1, At, B1); BAR; SCHED;
;     LDA(At, 0, 1); STAGE_A(SA(0, 0), brow, t + 2);
;     BAR; WAIT_L(0); MMA(1, 0, At, B0); BAR; SCHED;
;     STAGE_B(SB(0, 1), bcol + HALF, t + 2);
;     WAIT_V(6); BAR; MMA(1, 1, At, B1); BAR; SCHED;
;     LDB(B0, 1, 0); SCHED; LDA(At, 1, 0); STAGE_A(SA(0, 1), brow + HALF, t + 2);
;     WAIT_L(8); BAR; WAIT_L(0); MMA(0, 0, At, B0); BAR; SCHED;
;     LDB(B1, 1, 1); STAGE_B(SB(1, 0), bcol, t + 3);
;     BAR; WAIT_L(0); MMA(0, 1, At, B1); BAR; SCHED;
;     LDA(At, 1, 1); STAGE_A(SA(1, 0), brow, t + 3);
;     BAR; WAIT_L(0); MMA(1, 0, At, B0); BAR; SCHED;
;     STAGE_B(SB(1, 1), bcol + HALF, t + 3);
;     WAIT_V(6); BAR; MMA(1, 1, At, B1); BAR; SCHED;
;   }
	s_waitcnt lgkmcnt(0)
	s_setprio 1
	v_mfma_f32_16x16x32_bf16 v[62:65], v[164:167], v[180:183], v[62:65]
	v_mfma_f32_16x16x32_bf16 v[58:61], v[172:175], v[180:183], v[58:61]
	v_mfma_f32_16x16x32_bf16 v[54:57], v[164:167], v[188:191], v[54:57]
	v_mfma_f32_16x16x32_bf16 v[50:53], v[172:175], v[188:191], v[50:53]
	v_mfma_f32_16x16x32_bf16 v[46:49], v[164:167], v[196:199], v[46:49]
	v_mfma_f32_16x16x32_bf16 v[42:45], v[172:175], v[196:199], v[42:45]
	v_mfma_f32_16x16x32_bf16 v[38:41], v[164:167], v[206:209], v[38:41]
	v_mfma_f32_16x16x32_bf16 v[34:37], v[172:175], v[206:209], v[34:37]
	v_mfma_f32_16x16x32_bf16 v[62:65], v[168:171], v[184:187], v[62:65]
	v_mfma_f32_16x16x32_bf16 v[58:61], v[176:179], v[184:187], v[58:61]
	v_mfma_f32_16x16x32_bf16 v[54:57], v[168:171], v[192:195], v[54:57]
	v_mfma_f32_16x16x32_bf16 v[50:53], v[176:179], v[192:195], v[50:53]
	v_mfma_f32_16x16x32_bf16 v[46:49], v[168:171], v[202:205], v[46:49]
	v_mfma_f32_16x16x32_bf16 v[42:45], v[176:179], v[202:205], v[42:45]
	v_mfma_f32_16x16x32_bf16 v[38:41], v[168:171], v[216:219], v[38:41]
	v_mfma_f32_16x16x32_bf16 v[34:37], v[176:179], v[216:219], v[34:37]
	v_mfma_f32_16x16x32_bf16 v[30:33], v[222:225], v[180:183], v[30:33]
	v_mfma_f32_16x16x32_bf16 v[26:29], v[232:235], v[180:183], v[26:29]
	v_mfma_f32_16x16x32_bf16 v[22:25], v[222:225], v[188:191], v[22:25]
	v_mfma_f32_16x16x32_bf16 v[18:21], v[232:235], v[188:191], v[18:21]
	v_mfma_f32_16x16x32_bf16 v[14:17], v[222:225], v[196:199], v[14:17]
	v_mfma_f32_16x16x32_bf16 v[10:13], v[232:235], v[196:199], v[10:13]
	v_mfma_f32_16x16x32_bf16 v[6:9], v[222:225], v[206:209], v[6:9]
	v_mfma_f32_16x16x32_bf16 v[2:5], v[232:235], v[206:209], v[2:5]
	v_mfma_f32_16x16x32_bf16 v[30:33], v[228:231], v[184:187], v[30:33]
	v_mfma_f32_16x16x32_bf16 v[26:29], v[236:239], v[184:187], v[26:29]
	v_mfma_f32_16x16x32_bf16 v[22:25], v[228:231], v[192:195], v[22:25]
	v_mfma_f32_16x16x32_bf16 v[18:21], v[236:239], v[192:195], v[18:21]
	v_mfma_f32_16x16x32_bf16 v[14:17], v[228:231], v[202:205], v[14:17]
	v_mfma_f32_16x16x32_bf16 v[10:13], v[236:239], v[202:205], v[10:13]
	v_mfma_f32_16x16x32_bf16 v[6:9], v[228:231], v[216:219], v[6:9]
	v_mfma_f32_16x16x32_bf16 v[2:5], v[236:239], v[216:219], v[2:5]
	s_setprio 0
	s_barrier
	ds_read_b128 v[164:167], v149
	ds_read_b128 v[168:171], v149 offset:1024
	ds_read_b128 v[172:175], v149 offset:2048
	ds_read_b128 v[176:179], v149 offset:3072
	ds_read_b128 v[180:183], v147 offset:32768
	ds_read_b128 v[184:187], v147 offset:33792
	ds_read_b128 v[188:191], v146 offset:32768
	ds_read_b128 v[192:195], v146 offset:33792
	ds_read_b128 v[196:199], v145 offset:32768
	ds_read_b128 v[202:205], v145 offset:33792
	ds_read_b128 v[206:209], v144 offset:32768
	ds_read_b128 v[216:219], v144 offset:33792
	s_waitcnt lgkmcnt(6)
	ds_read_b128 v[222:225], v148
	ds_read_b128 v[228:231], v148 offset:1024
	ds_read_b128 v[232:235], v148 offset:2048
	ds_read_b128 v[236:239], v148 offset:3072
	v_readfirstlane_b32 s2, v134
	v_lshl_add_u64 v[246:247], v[210:211], 0, s[48:49]
	s_mov_b32 m0, s2
	v_readfirstlane_b32 s2, v133
	global_load_lds_dwordx4 v[246:247], off
	v_lshl_add_u64 v[246:247], v[210:211], 0, s[50:51]
	s_mov_b32 m0, s2
	s_nop 0
	global_load_lds_dwordx4 v[246:247], off
	s_waitcnt vmcnt(8)
	s_barrier
	s_waitcnt lgkmcnt(0)
	s_setprio 1
	v_mfma_f32_16x16x32_bf16 v[126:129], v[164:167], v[180:183], v[126:129]
	v_mfma_f32_16x16x32_bf16 v[122:125], v[172:175], v[180:183], v[122:125]
	v_mfma_f32_16x16x32_bf16 v[118:121], v[164:167], v[188:191], v[118:121]
	v_mfma_f32_16x16x32_bf16 v[114:117], v[172:175], v[188:191], v[114:117]
	v_mfma_f32_16x16x32_bf16 v[110:113], v[164:167], v[196:199], v[110:113]
	v_mfma_f32_16x16x32_bf16 v[106:109], v[172:175], v[196:199], v[106:109]
	v_mfma_f32_16x16x32_bf16 v[102:105], v[164:167], v[206:209], v[102:105]
	v_mfma_f32_16x16x32_bf16 v[98:101], v[172:175], v[206:209], v[98:101]
	v_mfma_f32_16x16x32_bf16 v[126:129], v[168:171], v[184:187], v[126:129]
	v_mfma_f32_16x16x32_bf16 v[122:125], v[176:179], v[184:187], v[122:125]
	v_mfma_f32_16x16x32_bf16 v[118:121], v[168:171], v[192:195], v[118:121]
	v_mfma_f32_16x16x32_bf16 v[114:117], v[176:179], v[192:195], v[114:117]
	v_mfma_f32_16x16x32_bf16 v[110:113], v[168:171], v[202:205], v[110:113]
	v_mfma_f32_16x16x32_bf16 v[106:109], v[176:179], v[202:205], v[106:109]
	v_mfma_f32_16x16x32_bf16 v[102:105], v[168:171], v[216:219], v[102:105]
	v_mfma_f32_16x16x32_bf16 v[98:101], v[176:179], v[216:219], v[98:101]
	v_mfma_f32_16x16x32_bf16 v[94:97], v[222:225], v[180:183], v[94:97]
	v_mfma_f32_16x16x32_bf16 v[90:93], v[232:235], v[180:183], v[90:93]
	v_mfma_f32_16x16x32_bf16 v[86:89], v[222:225], v[188:191], v[86:89]
	v_mfma_f32_16x16x32_bf16 v[82:85], v[232:235], v[188:191], v[82:85]
	v_mfma_f32_16x16x32_bf16 v[78:81], v[222:225], v[196:199], v[78:81]
	v_mfma_f32_16x16x32_bf16 v[74:77], v[232:235], v[196:199], v[74:77]
	v_mfma_f32_16x16x32_bf16 v[70:73], v[222:225], v[206:209], v[70:73]
	v_mfma_f32_16x16x32_bf16 v[66:69], v[232:235], v[206:209], v[66:69]
	v_mfma_f32_16x16x32_bf16 v[94:97], v[228:231], v[184:187], v[94:97]
	v_mfma_f32_16x16x32_bf16 v[90:93], v[236:239], v[184:187], v[90:93]
	v_mfma_f32_16x16x32_bf16 v[86:89], v[228:231], v[192:195], v[86:89]
	v_mfma_f32_16x16x32_bf16 v[82:85], v[236:239], v[192:195], v[82:85]
	v_mfma_f32_16x16x32_bf16 v[78:81], v[228:231], v[202:205], v[78:81]
	v_mfma_f32_16x16x32_bf16 v[74:77], v[236:239], v[202:205], v[74:77]
	v_mfma_f32_16x16x32_bf16 v[70:73], v[228:231], v[216:219], v[70:73]
	v_mfma_f32_16x16x32_bf16 v[66:69], v[236:239], v[216:219], v[66:69]
	s_setprio 0
	s_barrier
; #define STAGE_B(P, br, kt) do { const char* _gb = (const char*)(Bt + ((long)(br) * K + (long)(kt) * BK)); \
;     __builtin_amdgcn_global_load_lds((const unsigned*)(_gb + bofl0), (unsigned*)((char*)(P) + gtid_ * 16), 16, 0, 0); \
;     __builtin_amdgcn_global_load_lds((const unsigned*)(_gb + (long)K * 128 + bofl0), (unsigned*)((char*)(P) + gtid_ * 16 + 8192), 16, 0, 0); } while (0)
; #define LDA(dst, b, h) for (int m = 0; m < 4; ++m) for (int k = 0; k < 2; ++k) \
;     dst[m][k] = *reinterpret_cast<const bf16x8*>((char*)SA(b, h) + lds_byte(wr * 64 + m * 16 + fr, k * 32 + fq * 8))
; #define LDB(dst, b, h) for (int n = 0; n < 2; ++n) for (int k = 0; k < 2; ++k) \
;     dst[n][k] = *reinterpret_cast<const bf16x8*>((char*)SB(b, h) + lds_byte(wc * 32 + n * 16 + fr, k * 32 + fq * 8))
; #define MMA(ai, bj, At_, Bt_) do { __builtin_amdgcn_s_setprio(1); \
;     for (int m = 0; m < 4; ++m) for (int n = 0; n < 2; ++n) for (int k = 0; k < 2; ++k) \
;       acc[ai][bj][m][n] = __builtin_amdgcn_mfma_f32_16x16x32_bf16(At_[m][k], Bt_[n][k], acc[ai][bj][m][n], 0, 0, 0); \
;     __builtin_amdgcn_s_setprio(0); } while (0)
; template <int EPI>
; __device__ __forceinline__ void gemm_tile(const GemmArgs& g, int brow, int bcol, int parity, bool first, bool nvalid, int nbrow, int nbcol) {
;     ...
;   for (int t = 0; t < nt - 2; t += 2) {
;     LDB(B0, 0, 0); SCHED; LDA(At, 0, 0); STAGE_A(SA(1, 1), brow + HALF, t + 1);
;     WAIT_L(8); BAR; WAIT_L(0); MMA(0, 0, At, B0); BAR; SCHED;
;     LDB(B1, 0, 1); STAGE_B(SB(0, 0), bcol, t + 2);
;     BAR; WAIT_L(0); MMA(0, 1, At, B1); BAR; SCHED;
;     LDA(At, 0, 1); STAGE_A(SA(0, 0), brow, t + 2);
;     BAR; WAIT_L(0); MMA(1, 0, At, B0); BAR; SCHED;
;     STAGE_B(SB(0, 1), bcol + HALF, t + 2);
;     WAIT_V(6); BAR; MMA(1, 1, At, B1); BAR; SCHED;
;     LDB(B0, 1, 0); SCHED; LDA(At, 1, 0); STAGE_A(SA(0, 1), brow + HALF, t + 2);
;     WAIT_L(8); BAR; WAIT_L(0); MMA(0, 0, At, B0); BAR; SCHED;
;     LDB(B1, 1, 1); STAGE_B(SB(1, 0), bcol, t + 3);
;     BAR; WAIT_L(0); MMA(0, 1, At, B1); BAR; SCHED;
;     LDA(At, 1, 1); STAGE_A(SA(1, 0), brow, t + 3);
;     BAR; WAIT_L(0); MMA(1, 0, At, B0); BAR; SCHED;
;     STAGE_B(SB(1, 1), bcol + HALF, t + 3);
;     WAIT_V(6); BAR; MMA(1, 1, At, B1); BAR; SCHED;
;   }
;   { LDB(B0, 0, 0); LDA(At, 0, 0); STAGE_A(SA(1, 1), brow + HALF, nt - 1);
;     BAR; WAIT_L(0); MMA(0, 0, At, B0); BAR;
	ds_read_b128 v[180:183], v147 offset:49152
	ds_read_b128 v[184:187], v147 offset:50176
	ds_read_b128 v[188:191], v146 offset:49152
	ds_read_b128 v[192:195], v146 offset:50176
	ds_read_b128 v[196:199], v145 offset:49152
	ds_read_b128 v[202:205], v145 offset:50176
	ds_read_b128 v[206:209], v144 offset:49152
	ds_read_b128 v[216:219], v144 offset:50176
	v_readfirstlane_b32 s2, v150
	v_lshl_add_u64 v[240:241], v[212:213], 0, s[58:59]
	s_mov_b32 m0, s2
	v_readfirstlane_b32 s2, v151
	global_load_lds_dwordx4 v[240:241], off
	v_lshl_add_u64 v[240:241], v[212:213], 0, vcc
	s_mov_b32 m0, s2
	s_nop 0
	global_load_lds_dwordx4 v[240:241], off
	v_readfirstlane_b32 s2, v152
	v_lshl_add_u64 v[240:241], v[210:211], 0, s[52:53]
	s_mov_b32 m0, s2
	v_readfirstlane_b32 s2, v153
	global_load_lds_dwordx4 v[240:241], off
	v_lshl_add_u64 v[210:211], v[210:211], 0, s[56:57]
	s_mov_b32 m0, s2
	s_nop 0
	global_load_lds_dwordx4 v[210:211], off
	v_readfirstlane_b32 s2, v155
	v_lshl_add_u64 v[244:245], v[212:213], 0, s[60:61]
	s_mov_b32 m0, s2
	v_readfirstlane_b32 s2, v156
	global_load_lds_dwordx4 v[244:245], off
	v_lshl_add_u64 v[244:245], v[212:213], 0, s[94:95]
	s_mov_b32 m0, s2
	s_nop 0
	global_load_lds_dwordx4 v[244:245], off
	s_waitcnt vmcnt(8)
	s_barrier
	s_waitcnt lgkmcnt(0)
	s_setprio 1
	v_mfma_f32_16x16x32_bf16 v[62:65], v[164:167], v[180:183], v[62:65]
	v_mfma_f32_16x16x32_bf16 v[58:61], v[172:175], v[180:183], v[58:61]
	v_mfma_f32_16x16x32_bf16 v[54:57], v[164:167], v[188:191], v[54:57]
	v_mfma_f32_16x16x32_bf16 v[50:53], v[172:175], v[188:191], v[50:53]
	v_mfma_f32_16x16x32_bf16 v[46:49], v[164:167], v[196:199], v[46:49]
	v_mfma_f32_16x16x32_bf16 v[42:45], v[172:175], v[196:199], v[42:45]
	v_mfma_f32_16x16x32_bf16 v[38:41], v[164:167], v[206:209], v[38:41]
	v_mfma_f32_16x16x32_bf16 v[34:37], v[172:175], v[206:209], v[34:37]
	v_mfma_f32_16x16x32_bf16 v[62:65], v[168:171], v[184:187], v[62:65]
	v_mfma_f32_16x16x32_bf16 v[58:61], v[176:179], v[184:187], v[58:61]
	v_mfma_f32_16x16x32_bf16 v[54:57], v[168:171], v[192:195], v[54:57]
	v_mfma_f32_16x16x32_bf16 v[50:53], v[176:179], v[192:195], v[50:53]
	v_mfma_f32_16x16x32_bf16 v[46:49], v[168:171], v[202:205], v[46:49]
	v_mfma_f32_16x16x32_bf16 v[42:45], v[176:179], v[202:205], v[42:45]
	v_mfma_f32_16x16x32_bf16 v[38:41], v[168:171], v[216:219], v[38:41]
	v_mfma_f32_16x16x32_bf16 v[34:37], v[176:179], v[216:219], v[34:37]
	v_mfma_f32_16x16x32_bf16 v[30:33], v[222:225], v[180:183], v[30:33]
	v_mfma_f32_16x16x32_bf16 v[26:29], v[232:235], v[180:183], v[26:29]
	v_mfma_f32_16x16x32_bf16 v[22:25], v[222:225], v[188:191], v[22:25]
	v_mfma_f32_16x16x32_bf16 v[18:21], v[232:235], v[188:191], v[18:21]
	v_mfma_f32_16x16x32_bf16 v[14:17], v[222:225], v[196:199], v[14:17]
	v_mfma_f32_16x16x32_bf16 v[10:13], v[232:235], v[196:199], v[10:13]
	v_mfma_f32_16x16x32_bf16 v[6:9], v[222:225], v[206:209], v[6:9]
	v_mfma_f32_16x16x32_bf16 v[2:5], v[232:235], v[206:209], v[2:5]
	v_mfma_f32_16x16x32_bf16 v[30:33], v[228:231], v[184:187], v[30:33]
	v_mfma_f32_16x16x32_bf16 v[26:29], v[236:239], v[184:187], v[26:29]
	v_mfma_f32_16x16x32_bf16 v[22:25], v[228:231], v[192:195], v[22:25]
	v_mfma_f32_16x16x32_bf16 v[18:21], v[236:239], v[192:195], v[18:21]
	v_mfma_f32_16x16x32_bf16 v[14:17], v[228:231], v[202:205], v[14:17]
	v_mfma_f32_16x16x32_bf16 v[10:13], v[236:239], v[202:205], v[10:13]
	v_mfma_f32_16x16x32_bf16 v[6:9], v[228:231], v[216:219], v[6:9]
	v_mfma_f32_16x16x32_bf16 v[2:5], v[236:239], v[216:219], v[2:5]
	s_setprio 0
	s_barrier
	s_add_i32 s25, s25, 2
	s_add_u32 s0, s0, 0x100
	s_addc_u32 s1, s1, 0
	s_add_u32 s12, s12, 0x100
	s_addc_u32 s13, s13, 0
	s_cmp_lt_u32 s25, 12
	s_cbranch_scc1 .LBB0_166
	s_or_b32 s0, s38, 0x80
	s_ashr_i32 s1, s0, 31
	s_lshl_b64 s[0:1], s[0:1], 11
	s_add_u32 s0, s80, s0
	s_addc_u32 s1, s81, s1
	v_lshl_add_u64 v[130:131], s[0:1], 0, v[0:1]
	s_mov_b64 s[0:1], 0x780
	ds_read_b128 v[150:153], v157
	ds_read_b128 v[164:167], v157 offset:1024
	ds_read_b128 v[168:171], v157 offset:2048
	ds_read_b128 v[172:175], v157 offset:3072
	ds_read_b128 v[176:179], v147
	ds_read_b128 v[180:183], v147 offset:1024
	ds_read_b128 v[184:187], v146
	ds_read_b128 v[188:191], v146 offset:1024
	ds_read_b128 v[192:195], v145
	ds_read_b128 v[196:199], v145 offset:1024
	ds_read_b128 v[202:205], v144
	ds_read_b128 v[206:209], v144 offset:1024
	v_lshl_add_u64 v[156:157], v[130:131], 0, s[0:1]
	v_readfirstlane_b32 s0, v161
	s_mov_b32 m0, s0
	s_mov_b64 s[0:1], 0x20780
	v_lshl_add_u64 v[130:131], v[130:131], 0, s[0:1]
	v_readfirstlane_b32 s0, v162
	global_load_lds_dwordx4 v[156:157], off
	s_mov_b32 m0, s0
	s_nop 0
	global_load_lds_dwordx4 v[130:131], off
	s_waitcnt vmcnt(8)
	s_barrier
	s_waitcnt lgkmcnt(0)
	s_setprio 1
	s_waitcnt lgkmcnt(0)
	v_mfma_f32_16x16x32_bf16 v[126:129], v[150:153], v[176:179], v[126:129]
	v_mfma_f32_16x16x32_bf16 v[118:121], v[150:153], v[184:187], v[118:121]
	v_mfma_f32_16x16x32_bf16 v[110:113], v[150:153], v[192:195], v[110:113]
	v_mfma_f32_16x16x32_bf16 v[102:105], v[150:153], v[202:205], v[102:105]
	v_mfma_f32_16x16x32_bf16 v[126:129], v[164:167], v[180:183], v[126:129]
	v_mfma_f32_16x16x32_bf16 v[122:125], v[168:171], v[176:179], v[122:125]
	v_mfma_f32_16x16x32_bf16 v[118:121], v[164:167], v[188:191], v[118:121]
	v_mfma_f32_16x16x32_bf16 v[114:117], v[168:171], v[184:187], v[114:117]
	v_mfma_f32_16x16x32_bf16 v[110:113], v[164:167], v[196:199], v[110:113]
	v_mfma_f32_16x16x32_bf16 v[106:109], v[168:171], v[192:195], v[106:109]
	v_mfma_f32_16x16x32_bf16 v[102:105], v[164:167], v[206:209], v[102:105]
	v_mfma_f32_16x16x32_bf16 v[98:101], v[168:171], v[202:205], v[98:101]
	v_mfma_f32_16x16x32_bf16 v[216:219], v[172:175], v[180:183], v[122:125]
	v_mfma_f32_16x16x32_bf16 v[222:225], v[172:175], v[188:191], v[114:117]
	v_mfma_f32_16x16x32_bf16 v[228:231], v[172:175], v[196:199], v[106:109]
	v_mfma_f32_16x16x32_bf16 v[232:235], v[172:175], v[206:209], v[98:101]
	s_setprio 0
	s_barrier
; #define LDA(dst, b, h) for (int m = 0; m < 4; ++m) for (int k = 0; k < 2; ++k) \
;     dst[m][k] = *reinterpret_cast<const bf16x8*>((char*)SA(b, h) + lds_byte(wr * 64 + m * 16 + fr, k * 32 + fq * 8))
; #define LDB(dst, b, h) for (int n = 0; n < 2; ++n) for (int k = 0; k < 2; ++k) \
;     dst[n][k] = *reinterpret_cast<const bf16x8*>((char*)SB(b, h) + lds_byte(wc * 32 + n * 16 + fr, k * 32 + fq * 8))
; #define MMA(ai, bj, At_, Bt_) do { __builtin_amdgcn_s_setprio(1); \
;     for (int m = 0; m < 4; ++m) for (int n = 0; n < 2; ++n) for (int k = 0; k < 2; ++k) \
;       acc[ai][bj][m][n] = __builtin_amdgcn_mfma_f32_16x16x32_bf16(At_[m][k], Bt_[n][k], acc[ai][bj][m][n], 0, 0, 0); \
;     __builtin_amdgcn_s_setprio(0); } while (0)
; #define WAIT_V(n) asm volatile("s_waitcnt vmcnt(" #n ")" ::: "memory")
; #define WAIT_L(n) asm volatile("s_waitcnt lgkmcnt(" #n ")" ::: "memory")
; #define BAR __builtin_amdgcn_s_barrier()
; #define SCHED __builtin_amdgcn_sched_barrier(0)
; template <int EPI>
; __device__ __forceinline__ void gemm_tile(const GemmArgs& g, int brow, int bcol, int parity, bool first, bool nvalid, int nbrow, int nbcol) {
;     ...
;   { LDB(B0, 0, 0); LDA(At, 0, 0); STAGE_A(SA(1, 1), brow + HALF, nt - 1);
;     BAR; WAIT_L(0); MMA(0, 0, At, B0); BAR;
;     LDB(B1, 0, 1); BAR; WAIT_L(0); MMA(0, 1, At, B1); BAR; SCHED;
;     LDA(At, 0, 1); WAIT_V(4); BAR; WAIT_L(0); MMA(1, 0, At, B0); MMA(1, 1, At, B1); BAR; }
;   { LDB(B0, 1, 0); LDA(At, 1, 0); WAIT_V(2); BAR; WAIT_L(0); MMA(0, 0, At, B0); BAR;
	s_nop 1
	ds_read_b128 v[98:101], v154
	ds_read_b128 v[106:109], v154 offset:1024
	ds_read_b128 v[114:117], v154 offset:2048
	ds_read_b128 v[122:125], v154 offset:3072
	s_barrier
	s_waitcnt lgkmcnt(0)
	s_setprio 1
	s_waitcnt lgkmcnt(0)
	v_mfma_f32_16x16x32_bf16 v[94:97], v[98:101], v[176:179], v[94:97]
	v_mfma_f32_16x16x32_bf16 v[86:89], v[98:101], v[184:187], v[86:89]
	v_mfma_f32_16x16x32_bf16 v[78:81], v[98:101], v[192:195], v[78:81]
	v_mfma_f32_16x16x32_bf16 v[74:77], v[114:117], v[192:195], v[74:77]
	v_mfma_f32_16x16x32_bf16 v[94:97], v[106:109], v[180:183], v[94:97]
	v_mfma_f32_16x16x32_bf16 v[90:93], v[114:117], v[176:179], v[90:93]
	v_mfma_f32_16x16x32_bf16 v[86:89], v[106:109], v[188:191], v[86:89]
	v_mfma_f32_16x16x32_bf16 v[82:85], v[114:117], v[184:187], v[82:85]
	v_mfma_f32_16x16x32_bf16 v[78:81], v[106:109], v[196:199], v[78:81]
	v_mfma_f32_16x16x32_bf16 v[74:77], v[122:125], v[196:199], v[74:77]
	v_mfma_f32_16x16x32_bf16 v[70:73], v[98:101], v[202:205], v[70:73]
	v_mfma_f32_16x16x32_bf16 v[66:69], v[114:117], v[202:205], v[66:69]
	v_mfma_f32_16x16x32_bf16 v[154:157], v[122:125], v[180:183], v[90:93]
	v_mfma_f32_16x16x32_bf16 v[176:179], v[122:125], v[188:191], v[82:85]
	v_mfma_f32_16x16x32_bf16 v[180:183], v[106:109], v[206:209], v[70:73]
	v_mfma_f32_16x16x32_bf16 v[184:187], v[122:125], v[206:209], v[66:69]
	s_setprio 0
	s_barrier
	s_nop 1
	ds_read_b128 v[66:69], v147 offset:16384
	ds_read_b128 v[70:73], v147 offset:17408
	ds_read_b128 v[82:85], v146 offset:16384
	ds_read_b128 v[90:93], v146 offset:17408
	ds_read_b128 v[188:191], v145 offset:16384
	ds_read_b128 v[192:195], v145 offset:17408
	ds_read_b128 v[196:199], v144 offset:16384
	ds_read_b128 v[202:205], v144 offset:17408
	s_waitcnt vmcnt(4)
	s_barrier
	s_waitcnt lgkmcnt(0)
	s_setprio 1
	s_waitcnt lgkmcnt(0)
	v_mfma_f32_16x16x32_bf16 v[62:65], v[150:153], v[66:69], v[62:65]
	v_mfma_f32_16x16x32_bf16 v[54:57], v[150:153], v[82:85], v[54:57]
	v_mfma_f32_16x16x32_bf16 v[46:49], v[150:153], v[188:191], v[46:49]
	v_mfma_f32_16x16x32_bf16 v[38:41], v[150:153], v[196:199], v[38:41]
	v_mfma_f32_16x16x32_bf16 v[62:65], v[164:167], v[70:73], v[62:65]
	v_mfma_f32_16x16x32_bf16 v[58:61], v[168:171], v[66:69], v[58:61]
	v_mfma_f32_16x16x32_bf16 v[54:57], v[164:167], v[90:93], v[54:57]
	v_mfma_f32_16x16x32_bf16 v[50:53], v[168:171], v[82:85], v[50:53]
	v_mfma_f32_16x16x32_bf16 v[46:49], v[164:167], v[192:195], v[46:49]
	v_mfma_f32_16x16x32_bf16 v[42:45], v[168:171], v[188:191], v[42:45]
	v_mfma_f32_16x16x32_bf16 v[38:41], v[164:167], v[202:205], v[38:41]
	v_mfma_f32_16x16x32_bf16 v[34:37], v[168:171], v[196:199], v[34:37]
	v_mfma_f32_16x16x32_bf16 v[206:209], v[172:175], v[70:73], v[58:61]
	v_mfma_f32_16x16x32_bf16 v[236:239], v[172:175], v[90:93], v[50:53]
	v_mfma_f32_16x16x32_bf16 v[240:243], v[172:175], v[192:195], v[42:45]
	v_mfma_f32_16x16x32_bf16 v[150:153], v[172:175], v[202:205], v[34:37]
	s_setprio 0
	s_setprio 1
	v_mfma_f32_16x16x32_bf16 v[30:33], v[98:101], v[66:69], v[30:33]
	v_mfma_f32_16x16x32_bf16 v[22:25], v[98:101], v[82:85], v[22:25]
	v_mfma_f32_16x16x32_bf16 v[14:17], v[98:101], v[188:191], v[14:17]
	v_mfma_f32_16x16x32_bf16 v[10:13], v[114:117], v[188:191], v[10:13]
	v_mfma_f32_16x16x32_bf16 v[30:33], v[106:109], v[70:73], v[30:33]
	v_mfma_f32_16x16x32_bf16 v[26:29], v[114:117], v[66:69], v[26:29]
	v_mfma_f32_16x16x32_bf16 v[22:25], v[106:109], v[90:93], v[22:25]
	v_mfma_f32_16x16x32_bf16 v[18:21], v[114:117], v[82:85], v[18:21]
	v_mfma_f32_16x16x32_bf16 v[14:17], v[106:109], v[192:195], v[14:17]
	v_mfma_f32_16x16x32_bf16 v[10:13], v[122:125], v[192:195], v[10:13]
	v_mfma_f32_16x16x32_bf16 v[6:9], v[98:101], v[196:199], v[6:9]
	v_mfma_f32_16x16x32_bf16 v[2:5], v[114:117], v[196:199], v[2:5]
	v_mfma_f32_16x16x32_bf16 v[162:165], v[122:125], v[70:73], v[26:29]
	v_mfma_f32_16x16x32_bf16 v[166:169], v[122:125], v[90:93], v[18:21]
	v_mfma_f32_16x16x32_bf16 v[170:173], v[106:109], v[202:205], v[6:9]
	v_mfma_f32_16x16x32_bf16 v[188:191], v[122:125], v[202:205], v[2:5]
	s_setprio 0
	s_barrier
	s_nop 1
	ds_read_b128 v[2:5], v149
	ds_read_b128 v[6:9], v149 offset:1024
	ds_read_b128 v[192:195], v149 offset:2048
	ds_read_b128 v[196:199], v149 offset:3072
	ds_read_b128 v[18:21], v147 offset:32768
	ds_read_b128 v[26:29], v147 offset:33792
	ds_read_b128 v[34:37], v146 offset:32768
	ds_read_b128 v[42:45], v146 offset:33792
	ds_read_b128 v[50:53], v145 offset:32768
	ds_read_b128 v[58:61], v145 offset:33792
	ds_read_b128 v[202:205], v144 offset:32768
	ds_read_b128 v[244:247], v144 offset:33792
	s_waitcnt vmcnt(2)
	s_barrier
; #define LDA(dst, b, h) for (int m = 0; m < 4; ++m) for (int k = 0; k < 2; ++k) \
;     dst[m][k] = *reinterpret_cast<const bf16x8*>((char*)SA(b, h) + lds_byte(wr * 64 + m * 16 + fr, k * 32 + fq * 8))
; #define LDB(dst, b, h) for (int n = 0; n < 2; ++n) for (int k = 0; k < 2; ++k) \
;     dst[n][k] = *reinterpret_cast<const bf16x8*>((char*)SB(b, h) + lds_byte(wc * 32 + n * 16 + fr, k * 32 + fq * 8))
; #define MMA(ai, bj, At_, Bt_) do { __builtin_amdgcn_s_setprio(1); \
;     for (int m = 0; m < 4; ++m) for (int n = 0; n < 2; ++n) for (int k = 0; k < 2; ++k) \
;       acc[ai][bj][m][n] = __builtin_amdgcn_mfma_f32_16x16x32_bf16(At_[m][k], Bt_[n][k], acc[ai][bj][m][n], 0, 0, 0); \
;     __builtin_amdgcn_s_setprio(0); } while (0)
; #define WAIT_V(n) asm volatile("s_waitcnt vmcnt(" #n ")" ::: "memory")
; #define WAIT_L(n) asm volatile("s_waitcnt lgkmcnt(" #n ")" ::: "memory")
; #define BAR __builtin_amdgcn_s_barrier()
; #define SCHED __builtin_amdgcn_sched_barrier(0)
; template <int EPI>
; __device__ __forceinline__ void gemm_tile(const GemmArgs& g, int brow, int bcol, int parity, bool first, bool nvalid, int nbrow, int nbcol) {
;     ...
;     LDA(At, 0, 1); WAIT_V(4); BAR; WAIT_L(0); MMA(1, 0, At, B0); MMA(1, 1, At, B1); BAR; }
;   { LDB(B0, 1, 0); LDA(At, 1, 0); WAIT_V(2); BAR; WAIT_L(0); MMA(0, 0, At, B0); BAR;
;     LDB(B1, 1, 1); WAIT_V(0); BAR; WAIT_L(0); MMA(0, 1, At, B1); BAR; SCHED;
;     LDA(At, 1, 1); BAR; WAIT_L(0); MMA(1, 0, At, B0); MMA(1, 1, At, B1); BAR; }
;   if (wr == 0) BAR;
	s_waitcnt lgkmcnt(0)
	s_setprio 1
	s_waitcnt lgkmcnt(0)
	v_mfma_f32_16x16x32_bf16 v[66:69], v[2:5], v[18:21], v[126:129]
	v_mfma_f32_16x16x32_bf16 v[122:125], v[6:9], v[26:29], v[66:69]
	v_mfma_f32_16x16x32_bf16 v[66:69], v[192:195], v[18:21], v[216:219]
	v_mfma_f32_16x16x32_bf16 v[114:117], v[196:199], v[26:29], v[66:69]
	v_mfma_f32_16x16x32_bf16 v[66:69], v[2:5], v[34:37], v[118:121]
	v_mfma_f32_16x16x32_bf16 v[106:109], v[6:9], v[42:45], v[66:69]
	v_mfma_f32_16x16x32_bf16 v[66:69], v[192:195], v[34:37], v[222:225]
	v_mfma_f32_16x16x32_bf16 v[98:101], v[196:199], v[42:45], v[66:69]
	v_mfma_f32_16x16x32_bf16 v[66:69], v[2:5], v[50:53], v[110:113]
	v_mfma_f32_16x16x32_bf16 v[90:93], v[6:9], v[58:61], v[66:69]
	v_mfma_f32_16x16x32_bf16 v[66:69], v[192:195], v[50:53], v[228:231]
	v_mfma_f32_16x16x32_bf16 v[82:85], v[196:199], v[58:61], v[66:69]
	v_mfma_f32_16x16x32_bf16 v[66:69], v[2:5], v[202:205], v[102:105]
	v_mfma_f32_16x16x32_bf16 v[70:73], v[6:9], v[244:247], v[66:69]
	v_mfma_f32_16x16x32_bf16 v[66:69], v[192:195], v[202:205], v[232:235]
	v_mfma_f32_16x16x32_bf16 v[66:69], v[196:199], v[244:247], v[66:69]
	s_setprio 0
	s_barrier
	ds_read_b128 v[216:219], v148
	ds_read_b128 v[222:225], v148 offset:1024
	ds_read_b128 v[228:231], v148 offset:2048
	ds_read_b128 v[232:235], v148 offset:3072
	s_waitcnt vmcnt(0)
	s_barrier
	s_waitcnt lgkmcnt(0)
	s_setprio 1
	s_waitcnt lgkmcnt(0)
	v_mfma_f32_16x16x32_bf16 v[94:97], v[216:219], v[18:21], v[94:97]
	v_mfma_f32_16x16x32_bf16 v[18:21], v[228:231], v[18:21], v[154:157]
	v_mfma_f32_16x16x32_bf16 v[118:121], v[232:235], v[26:29], v[18:21]
	v_mfma_f32_16x16x32_bf16 v[18:21], v[216:219], v[34:37], v[86:89]
	v_mfma_f32_16x16x32_bf16 v[110:113], v[222:225], v[42:45], v[18:21]
	v_mfma_f32_16x16x32_bf16 v[18:21], v[228:231], v[34:37], v[176:179]
	v_mfma_f32_16x16x32_bf16 v[102:105], v[232:235], v[42:45], v[18:21]
	v_mfma_f32_16x16x32_bf16 v[18:21], v[216:219], v[50:53], v[78:81]
	v_mfma_f32_16x16x32_bf16 v[126:129], v[222:225], v[26:29], v[94:97]
	v_mfma_f32_16x16x32_bf16 v[94:97], v[222:225], v[58:61], v[18:21]
	v_mfma_f32_16x16x32_bf16 v[18:21], v[228:231], v[50:53], v[74:77]
	v_mfma_f32_16x16x32_bf16 v[86:89], v[232:235], v[58:61], v[18:21]
	v_mfma_f32_16x16x32_bf16 v[18:21], v[216:219], v[202:205], v[180:183]
	v_mfma_f32_16x16x32_bf16 v[78:81], v[222:225], v[244:247], v[18:21]
	v_mfma_f32_16x16x32_bf16 v[18:21], v[228:231], v[202:205], v[184:187]
	v_mfma_f32_16x16x32_bf16 v[74:77], v[232:235], v[244:247], v[18:21]
	s_setprio 0
	s_barrier
	ds_read_b128 v[154:157], v147 offset:49152
	ds_read_b128 v[174:177], v147 offset:50176
	ds_read_b128 v[178:181], v146 offset:49152
	ds_read_b128 v[146:149], v146 offset:50176
	ds_read_b128 v[182:185], v145 offset:49152
	ds_read_b128 v[202:205], v145 offset:50176
	ds_read_b128 v[244:247], v144 offset:49152
	ds_read_b128 v[248:251], v144 offset:50176
	s_barrier
	s_waitcnt lgkmcnt(0)
	s_setprio 1
	s_waitcnt lgkmcnt(0)
	v_mfma_f32_16x16x32_bf16 v[18:21], v[2:5], v[154:157], v[62:65]
	v_mfma_f32_16x16x32_bf16 v[58:61], v[6:9], v[174:177], v[18:21]
	v_mfma_f32_16x16x32_bf16 v[18:21], v[192:195], v[154:157], v[206:209]
	v_mfma_f32_16x16x32_bf16 v[50:53], v[196:199], v[174:177], v[18:21]
	v_mfma_f32_16x16x32_bf16 v[18:21], v[2:5], v[178:181], v[54:57]
	v_mfma_f32_16x16x32_bf16 v[42:45], v[6:9], v[146:149], v[18:21]
	v_mfma_f32_16x16x32_bf16 v[18:21], v[192:195], v[178:181], v[236:239]
	v_mfma_f32_16x16x32_bf16 v[34:37], v[196:199], v[146:149], v[18:21]
	v_mfma_f32_16x16x32_bf16 v[18:21], v[2:5], v[182:185], v[46:49]
	v_mfma_f32_16x16x32_bf16 v[2:5], v[2:5], v[244:247], v[38:41]
	v_mfma_f32_16x16x32_bf16 v[26:29], v[6:9], v[202:205], v[18:21]
	v_mfma_f32_16x16x32_bf16 v[18:21], v[192:195], v[182:185], v[240:243]
	v_mfma_f32_16x16x32_bf16 v[6:9], v[6:9], v[248:251], v[2:5]
	v_mfma_f32_16x16x32_bf16 v[2:5], v[192:195], v[244:247], v[150:153]
	v_mfma_f32_16x16x32_bf16 v[18:21], v[196:199], v[202:205], v[18:21]
	v_mfma_f32_16x16x32_bf16 v[2:5], v[196:199], v[248:251], v[2:5]
	s_setprio 0
	s_setprio 1
	v_mfma_f32_16x16x32_bf16 v[22:25], v[216:219], v[178:181], v[22:25]
	v_mfma_f32_16x16x32_bf16 v[30:33], v[216:219], v[154:157], v[30:33]
	v_mfma_f32_16x16x32_bf16 v[46:49], v[222:225], v[146:149], v[22:25]
	v_mfma_f32_16x16x32_bf16 v[22:25], v[228:231], v[178:181], v[166:169]
	v_mfma_f32_16x16x32_bf16 v[10:13], v[228:231], v[182:185], v[10:13]
	v_mfma_f32_16x16x32_bf16 v[62:65], v[222:225], v[174:177], v[30:33]
	v_mfma_f32_16x16x32_bf16 v[30:33], v[228:231], v[154:157], v[162:165]
	v_mfma_f32_16x16x32_bf16 v[38:41], v[232:235], v[146:149], v[22:25]
	v_mfma_f32_16x16x32_bf16 v[14:17], v[216:219], v[182:185], v[14:17]
	v_mfma_f32_16x16x32_bf16 v[22:25], v[232:235], v[202:205], v[10:13]
	v_mfma_f32_16x16x32_bf16 v[10:13], v[216:219], v[244:247], v[170:173]
	v_mfma_f32_16x16x32_bf16 v[54:57], v[232:235], v[174:177], v[30:33]
	v_mfma_f32_16x16x32_bf16 v[30:33], v[222:225], v[202:205], v[14:17]
	v_mfma_f32_16x16x32_bf16 v[14:17], v[222:225], v[248:251], v[10:13]
	v_mfma_f32_16x16x32_bf16 v[10:13], v[228:231], v[244:247], v[188:191]
	v_mfma_f32_16x16x32_bf16 v[10:13], v[232:235], v[248:251], v[10:13]
	s_setprio 0
	s_movk_i32 s0, 0x100
	v_cmp_gt_u32_e32 vcc, s0, v138
	s_barrier
	s_and_saveexec_b64 s[0:1], vcc
	s_cbranch_execz .LBB0_169
	s_barrier

; __device__ __forceinline__ float frsq(float x) { return __builtin_amdgcn_rsqf(x); }
; #define STAGE_B(P, br, kt) do { const char* _gb = (const char*)(Bt + ((long)(br) * K + (long)(kt) * BK)); \
;     __builtin_amdgcn_global_load_lds((const unsigned*)(_gb + bofl0), (unsigned*)((char*)(P) + gtid_ * 16), 16, 0, 0); \
;     __builtin_amdgcn_global_load_lds((const unsigned*)(_gb + (long)K * 128 + bofl0), (unsigned*)((char*)(P) + gtid_ * 16 + 8192), 16, 0, 0); } while (0)
; #define WAIT_V(n) asm volatile("s_waitcnt vmcnt(" #n ")" ::: "memory")
; #define BAR __builtin_amdgcn_s_barrier()
; template <int EPI>
; __device__ __forceinline__ void gemm_tile(const GemmArgs& g, int brow, int bcol, int parity, bool first, bool nvalid, int nbrow, int nbcol) {
;     ...
;   if (first) { WAIT_V(4); } else { WAIT_V(0); }
;   BAR;
;   if constexpr (EPI != EPI_RES) {
;     if (gtid_ < 256) {
;       float s = ((ra0[0] + ra0[1]) + (ra0[2] + ra0[3])) + ((ra1[0] + ra1[1]) + (ra1[2] + ra1[3])) + ((ra2[0] + ra2[1]) + (ra2[2] + ra2[3])) + ((ra3[0] + ra3[1]) + (ra3[2] + ra3[3]));
;       rstd_s[gtid_] = frsq(s * (1.0f / 1024.0f) + 1e-6f);
;     }
;   }
;   STAGE_B(SB(1, 0), bcol, 1); STAGE_A(SA(1, 0), brow, 1); STAGE_B(SB(1, 1), bcol + HALF, 1);
;   WAIT_V(6); BAR;
.LBB0_186:
	s_or_b64 exec, exec, s[22:23]
	s_xor_b64 s[2:3], s[12:13], -1
	s_andn2_b64 vcc, exec, s[2:3]
	s_mov_b64 s[12:13], -1
	s_cbranch_vccnz .LBB0_188
	s_waitcnt vmcnt(2)
	s_mov_b64 s[12:13], 0

; #define STAGE_B(P, br, kt) do { const char* _gb = (const char*)(Bt + ((long)(br) * K + (long)(kt) * BK)); \
;     __builtin_amdgcn_global_load_lds((const unsigned*)(_gb + bofl0), (unsigned*)((char*)(P) + gtid_ * 16), 16, 0, 0); \
;     __builtin_amdgcn_global_load_lds((const unsigned*)(_gb + (long)K * 128 + bofl0), (unsigned*)((char*)(P) + gtid_ * 16 + 8192), 16, 0, 0); } while (0)
; #define LDA(dst, b, h) for (int m = 0; m < 4; ++m) for (int k = 0; k < 2; ++k) \
;     dst[m][k] = *reinterpret_cast<const bf16x8*>((char*)SA(b, h) + lds_byte(wr * 64 + m * 16 + fr, k * 32 + fq * 8))
; #define LDB(dst, b, h) for (int n = 0; n < 2; ++n) for (int k = 0; k < 2; ++k) \
;     dst[n][k] = *reinterpret_cast<const bf16x8*>((char*)SB(b, h) + lds_byte(wc * 32 + n * 16 + fr, k * 32 + fq * 8))
; #define MMA(ai, bj, At_, Bt_) do { __builtin_amdgcn_s_setprio(1); \
;     for (int m = 0; m < 4; ++m) for (int n = 0; n < 2; ++n) for (int k = 0; k < 2; ++k) \
;       acc[ai][bj][m][n] = __builtin_amdgcn_mfma_f32_16x16x32_bf16(At_[m][k], Bt_[n][k], acc[ai][bj][m][n], 0, 0, 0); \
;     __builtin_amdgcn_s_setprio(0); } while (0)
; #define WAIT_V(n) asm volatile("s_waitcnt vmcnt(" #n ")" ::: "memory")
; #define WAIT_L(n) asm volatile("s_waitcnt lgkmcnt(" #n ")" ::: "memory")
; #define BAR __builtin_amdgcn_s_barrier()
; #define SCHED __builtin_amdgcn_sched_barrier(0)
; template <int EPI>
; __device__ __forceinline__ void gemm_tile(const GemmArgs& g, int brow, int bcol, int parity, bool first, bool nvalid, int nbrow, int nbcol) {
;     ...
;   for (int t = 0; t < nt - 2; t += 2) {
;     LDB(B0, 0, 0); SCHED; LDA(At, 0, 0); STAGE_A(SA(1, 1), brow + HALF, t + 1);
;     WAIT_L(8); BAR; WAIT_L(0); MMA(0, 0, At, B0); BAR; SCHED;
;     LDB(B1, 0, 1); STAGE_B(SB(0, 0), bcol, t + 2);
;     BAR; WAIT_L(0); MMA(0, 1, At, B1); BAR; SCHED;
;     LDA(At, 0, 1); STAGE_A(SA(0, 0), brow, t + 2);
;     BAR; WAIT_L(0); MMA(1, 0, At, B0); BAR; SCHED;
;     STAGE_B(SB(0, 1), bcol + HALF, t + 2);
;     WAIT_V(6); BAR; MMA(1, 1, At, B1); BAR; SCHED;
.LBB0_191:
	ds_read_b128 v[166:169], v160
	ds_read_b128 v[170:173], v160 offset:1024
	ds_read_b128 v[174:177], v160 offset:2048
	ds_read_b128 v[178:181], v160 offset:3072
	ds_read_b128 v[182:185], v150
	ds_read_b128 v[186:189], v150 offset:1024
	ds_read_b128 v[190:193], v149
	ds_read_b128 v[194:197], v149 offset:1024
	ds_read_b128 v[202:205], v148
	ds_read_b128 v[206:209], v148 offset:1024
	ds_read_b128 v[216:219], v147
	ds_read_b128 v[222:225], v147 offset:1024
	s_waitcnt lgkmcnt(6)
	ds_read_b128 v[228:231], v159
	ds_read_b128 v[232:235], v159 offset:1024
	ds_read_b128 v[236:239], v159 offset:2048
	ds_read_b128 v[240:243], v159 offset:3072
	s_add_i32 s2, s61, 0xffffff80
	s_cmp_lt_u32 s2, s35
	s_cselect_b32 s3, s36, s57
	s_add_i32 s2, s2, s3
	s_ashr_i32 s3, s2, 31
	s_lshl_b64 s[2:3], s[2:3], 1
	s_add_u32 s2, s41, s2
	s_addc_u32 s3, s44, s3
	v_add_u32_e32 v165, 0xc000, v140
	v_lshl_add_u64 v[162:163], s[2:3], 0, v[130:131]
	v_readfirstlane_b32 s26, v165
	s_add_u32 s2, s2, s53
	s_mov_b32 m0, s26
	s_addc_u32 s3, s3, 0
	v_add_u32_e32 v164, 0xe000, v140
	global_load_lds_dwordx4 v[162:163], off
	v_lshl_add_u64 v[162:163], s[2:3], 0, v[130:131]
	v_readfirstlane_b32 s2, v164
	s_mov_b32 m0, s2
	s_nop 0
	global_load_lds_dwordx4 v[162:163], off
	s_waitcnt vmcnt(8)
	s_barrier
	s_waitcnt lgkmcnt(0)
	s_setprio 1
	v_mfma_f32_16x16x32_bf16 v[126:129], v[182:185], v[166:169], v[126:129]
	v_mfma_f32_16x16x32_bf16 v[122:125], v[182:185], v[174:177], v[122:125]
	v_mfma_f32_16x16x32_bf16 v[118:121], v[190:193], v[166:169], v[118:121]
	v_mfma_f32_16x16x32_bf16 v[114:117], v[190:193], v[174:177], v[114:117]
	v_mfma_f32_16x16x32_bf16 v[110:113], v[202:205], v[166:169], v[110:113]
	v_mfma_f32_16x16x32_bf16 v[106:109], v[202:205], v[174:177], v[106:109]
	v_mfma_f32_16x16x32_bf16 v[102:105], v[216:219], v[166:169], v[102:105]
	v_mfma_f32_16x16x32_bf16 v[98:101], v[216:219], v[174:177], v[98:101]
	v_mfma_f32_16x16x32_bf16 v[126:129], v[186:189], v[170:173], v[126:129]
	v_mfma_f32_16x16x32_bf16 v[122:125], v[186:189], v[178:181], v[122:125]
	v_mfma_f32_16x16x32_bf16 v[118:121], v[194:197], v[170:173], v[118:121]
	v_mfma_f32_16x16x32_bf16 v[114:117], v[194:197], v[178:181], v[114:117]
	v_mfma_f32_16x16x32_bf16 v[110:113], v[206:209], v[170:173], v[110:113]
	v_mfma_f32_16x16x32_bf16 v[106:109], v[206:209], v[178:181], v[106:109]
	v_mfma_f32_16x16x32_bf16 v[102:105], v[222:225], v[170:173], v[102:105]
	v_mfma_f32_16x16x32_bf16 v[98:101], v[222:225], v[178:181], v[98:101]
	v_mfma_f32_16x16x32_bf16 v[94:97], v[182:185], v[228:231], v[94:97]
	v_mfma_f32_16x16x32_bf16 v[90:93], v[182:185], v[236:239], v[90:93]
	v_mfma_f32_16x16x32_bf16 v[86:89], v[190:193], v[228:231], v[86:89]
	v_mfma_f32_16x16x32_bf16 v[82:85], v[190:193], v[236:239], v[82:85]
	v_mfma_f32_16x16x32_bf16 v[78:81], v[202:205], v[228:231], v[78:81]
	v_mfma_f32_16x16x32_bf16 v[74:77], v[202:205], v[236:239], v[74:77]
	v_mfma_f32_16x16x32_bf16 v[70:73], v[216:219], v[228:231], v[70:73]
	v_mfma_f32_16x16x32_bf16 v[66:69], v[216:219], v[236:239], v[66:69]
	v_mfma_f32_16x16x32_bf16 v[94:97], v[186:189], v[232:235], v[94:97]
	v_mfma_f32_16x16x32_bf16 v[90:93], v[186:189], v[240:243], v[90:93]
	v_mfma_f32_16x16x32_bf16 v[86:89], v[194:197], v[232:235], v[86:89]
	v_mfma_f32_16x16x32_bf16 v[82:85], v[194:197], v[240:243], v[82:85]
	v_mfma_f32_16x16x32_bf16 v[78:81], v[206:209], v[232:235], v[78:81]
	v_mfma_f32_16x16x32_bf16 v[74:77], v[206:209], v[240:243], v[74:77]
	v_mfma_f32_16x16x32_bf16 v[70:73], v[222:225], v[232:235], v[70:73]
	v_mfma_f32_16x16x32_bf16 v[66:69], v[222:225], v[240:243], v[66:69]
	s_setprio 0
	s_barrier
	ds_read_b128 v[182:185], v150 offset:16384
	ds_read_b128 v[186:189], v150 offset:17408
	ds_read_b128 v[190:193], v149 offset:16384
	ds_read_b128 v[194:197], v149 offset:17408
	ds_read_b128 v[202:205], v148 offset:16384
	ds_read_b128 v[206:209], v148 offset:17408
	ds_read_b128 v[216:219], v147 offset:16384
	ds_read_b128 v[222:225], v147 offset:17408
	v_add_u32_e32 v162, s40, v146
	v_lshl_add_u64 v[198:199], s[14:15], 0, v[132:133]
	v_readfirstlane_b32 s2, v162
	v_lshl_add_u64 v[210:211], v[198:199], 0, s[78:79]
	s_mov_b32 m0, s2
	v_add_u32_e32 v161, 0x2000, v162
	global_load_lds_dwordx4 v[210:211], off
	v_lshl_add_u64 v[210:211], s[18:19], 0, v[132:133]
	v_readfirstlane_b32 s2, v161
	v_lshl_add_u64 v[212:213], v[210:211], 0, s[78:79]
	s_mov_b32 m0, s2
	s_add_i32 s45, s45, 2
	global_load_lds_dwordx4 v[212:213], off
	s_sub_i32 s2, s61, 64
	s_cmp_lt_u32 s2, s35
	s_cselect_b32 s3, s36, s57
	s_add_i32 s2, s2, s3
	s_ashr_i32 s3, s2, 31
	s_lshl_b64 s[2:3], s[2:3], 1
	s_add_u32 s26, s25, s2
	s_addc_u32 s27, s39, s3
	v_lshl_add_u64 v[212:213], s[26:27], 0, v[130:131]
	v_readfirstlane_b32 s63, v140
	s_add_u32 s26, s26, s53
	s_mov_b32 m0, s63
	s_addc_u32 s27, s27, 0
	global_load_lds_dwordx4 v[212:213], off
	v_lshl_add_u64 v[212:213], s[26:27], 0, v[130:131]
	v_readfirstlane_b32 s26, v139
	s_mov_b32 m0, s26
	s_nop 0
	global_load_lds_dwordx4 v[212:213], off
	v_lshl_add_u64 v[212:213], s[20:21], 0, v[132:133]
	v_readfirstlane_b32 s26, v136
	v_add_u32_e32 v163, 0x2000, v136
	v_lshl_add_u64 v[246:247], v[212:213], 0, s[78:79]
	s_mov_b32 m0, s26
	v_lshl_add_u64 v[244:245], s[22:23], 0, v[132:133]
	v_readfirstlane_b32 s26, v163
	global_load_lds_dwordx4 v[246:247], off
	v_lshl_add_u64 v[246:247], v[244:245], 0, s[78:79]
	s_mov_b32 m0, s26
	s_nop 0
	global_load_lds_dwordx4 v[246:247], off
	s_waitcnt vmcnt(8)
	s_barrier
; #define STAGE_B(P, br, kt) do { const char* _gb = (const char*)(Bt + ((long)(br) * K + (long)(kt) * BK)); \
;     __builtin_amdgcn_global_load_lds((const unsigned*)(_gb + bofl0), (unsigned*)((char*)(P) + gtid_ * 16), 16, 0, 0); \
;     __builtin_amdgcn_global_load_lds((const unsigned*)(_gb + (long)K * 128 + bofl0), (unsigned*)((char*)(P) + gtid_ * 16 + 8192), 16, 0, 0); } while (0)
; #define LDA(dst, b, h) for (int m = 0; m < 4; ++m) for (int k = 0; k < 2; ++k) \
;     dst[m][k] = *reinterpret_cast<const bf16x8*>((char*)SA(b, h) + lds_byte(wr * 64 + m * 16 + fr, k * 32 + fq * 8))
; #define LDB(dst, b, h) for (int n = 0; n < 2; ++n) for (int k = 0; k < 2; ++k) \
;     dst[n][k] = *reinterpret_cast<const bf16x8*>((char*)SB(b, h) + lds_byte(wc * 32 + n * 16 + fr, k * 32 + fq * 8))
; #define MMA(ai, bj, At_, Bt_) do { __builtin_amdgcn_s_setprio(1); \
;     for (int m = 0; m < 4; ++m) for (int n = 0; n < 2; ++n) for (int k = 0; k < 2; ++k) \
;       acc[ai][bj][m][n] = __builtin_amdgcn_mfma_f32_16x16x32_bf16(At_[m][k], Bt_[n][k], acc[ai][bj][m][n], 0, 0, 0); \
;     __builtin_amdgcn_s_setprio(0); } while (0)
; #define WAIT_V(n) asm volatile("s_waitcnt vmcnt(" #n ")" ::: "memory")
; #define WAIT_L(n) asm volatile("s_waitcnt lgkmcnt(" #n ")" ::: "memory")
; template <int EPI>
; __device__ __forceinline__ void gemm_tile(const GemmArgs& g, int brow, int bcol, int parity, bool first, bool nvalid, int nbrow, int nbcol) {
;     ...
;   for (int t = 0; t < nt - 2; t += 2) {
;     LDB(B0, 0, 0); SCHED; LDA(At, 0, 0); STAGE_A(SA(1, 1), brow + HALF, t + 1);
;     WAIT_L(8); BAR; WAIT_L(0); MMA(0, 0, At, B0); BAR; SCHED;
;     LDB(B1, 0, 1); STAGE_B(SB(0, 0), bcol, t + 2);
;     BAR; WAIT_L(0); MMA(0, 1, At, B1); BAR; SCHED;
;     LDA(At, 0, 1); STAGE_A(SA(0, 0), brow, t + 2);
;     BAR; WAIT_L(0); MMA(1, 0, At, B0); BAR; SCHED;
;     STAGE_B(SB(0, 1), bcol + HALF, t + 2);
;     WAIT_V(6); BAR; MMA(1, 1, At, B1); BAR; SCHED;
;     LDB(B0, 1, 0); SCHED; LDA(At, 1, 0); STAGE_A(SA(0, 1), brow + HALF, t + 2);
;     WAIT_L(8); BAR; WAIT_L(0); MMA(0, 0, At, B0); BAR; SCHED;
;     LDB(B1, 1, 1); STAGE_B(SB(1, 0), bcol, t + 3);
;     BAR; WAIT_L(0); MMA(0, 1, At, B1); BAR; SCHED;
;     LDA(At, 1, 1); STAGE_A(SA(1, 0), brow, t + 3);
;     BAR; WAIT_L(0); MMA(1, 0, At, B0); BAR; SCHED;
;     STAGE_B(SB(1, 1), bcol + HALF, t + 3);
;     WAIT_V(6); BAR; MMA(1, 1, At, B1); BAR; SCHED;
	s_waitcnt lgkmcnt(0)
	s_setprio 1
	v_mfma_f32_16x16x32_bf16 v[62:65], v[182:185], v[166:169], v[62:65]
	v_mfma_f32_16x16x32_bf16 v[58:61], v[182:185], v[174:177], v[58:61]
	v_mfma_f32_16x16x32_bf16 v[54:57], v[190:193], v[166:169], v[54:57]
	v_mfma_f32_16x16x32_bf16 v[50:53], v[190:193], v[174:177], v[50:53]
	v_mfma_f32_16x16x32_bf16 v[46:49], v[202:205], v[166:169], v[46:49]
	v_mfma_f32_16x16x32_bf16 v[42:45], v[202:205], v[174:177], v[42:45]
	v_mfma_f32_16x16x32_bf16 v[38:41], v[216:219], v[166:169], v[38:41]
	v_mfma_f32_16x16x32_bf16 v[34:37], v[216:219], v[174:177], v[34:37]
	v_mfma_f32_16x16x32_bf16 v[62:65], v[186:189], v[170:173], v[62:65]
	v_mfma_f32_16x16x32_bf16 v[58:61], v[186:189], v[178:181], v[58:61]
	v_mfma_f32_16x16x32_bf16 v[54:57], v[194:197], v[170:173], v[54:57]
	v_mfma_f32_16x16x32_bf16 v[50:53], v[194:197], v[178:181], v[50:53]
	v_mfma_f32_16x16x32_bf16 v[46:49], v[206:209], v[170:173], v[46:49]
	v_mfma_f32_16x16x32_bf16 v[42:45], v[206:209], v[178:181], v[42:45]
	v_mfma_f32_16x16x32_bf16 v[38:41], v[222:225], v[170:173], v[38:41]
	v_mfma_f32_16x16x32_bf16 v[34:37], v[222:225], v[178:181], v[34:37]
	v_mfma_f32_16x16x32_bf16 v[30:33], v[182:185], v[228:231], v[30:33]
	v_mfma_f32_16x16x32_bf16 v[26:29], v[182:185], v[236:239], v[26:29]
	v_mfma_f32_16x16x32_bf16 v[22:25], v[190:193], v[228:231], v[22:25]
	v_mfma_f32_16x16x32_bf16 v[18:21], v[190:193], v[236:239], v[18:21]
	v_mfma_f32_16x16x32_bf16 v[14:17], v[202:205], v[228:231], v[14:17]
	v_mfma_f32_16x16x32_bf16 v[10:13], v[202:205], v[236:239], v[10:13]
	v_mfma_f32_16x16x32_bf16 v[6:9], v[216:219], v[228:231], v[6:9]
	v_mfma_f32_16x16x32_bf16 v[2:5], v[216:219], v[236:239], v[2:5]
	v_mfma_f32_16x16x32_bf16 v[30:33], v[186:189], v[232:235], v[30:33]
	v_mfma_f32_16x16x32_bf16 v[26:29], v[186:189], v[240:243], v[26:29]
	v_mfma_f32_16x16x32_bf16 v[22:25], v[194:197], v[232:235], v[22:25]
	v_mfma_f32_16x16x32_bf16 v[18:21], v[194:197], v[240:243], v[18:21]
	v_mfma_f32_16x16x32_bf16 v[14:17], v[206:209], v[232:235], v[14:17]
	v_mfma_f32_16x16x32_bf16 v[10:13], v[206:209], v[240:243], v[10:13]
	v_mfma_f32_16x16x32_bf16 v[6:9], v[222:225], v[232:235], v[6:9]
	v_mfma_f32_16x16x32_bf16 v[2:5], v[222:225], v[240:243], v[2:5]
	s_setprio 0
	s_barrier
	ds_read_b128 v[166:169], v154
	ds_read_b128 v[170:173], v154 offset:1024
	ds_read_b128 v[174:177], v154 offset:2048
	ds_read_b128 v[178:181], v154 offset:3072
	ds_read_b128 v[182:185], v150 offset:32768
	ds_read_b128 v[186:189], v150 offset:33792
	ds_read_b128 v[190:193], v149 offset:32768
	ds_read_b128 v[194:197], v149 offset:33792
	ds_read_b128 v[202:205], v148 offset:32768
	ds_read_b128 v[206:209], v148 offset:33792
	ds_read_b128 v[216:219], v147 offset:32768
	ds_read_b128 v[222:225], v147 offset:33792
	s_waitcnt lgkmcnt(6)
	ds_read_b128 v[228:231], v151
	ds_read_b128 v[232:235], v151 offset:1024
	ds_read_b128 v[236:239], v151 offset:2048
	ds_read_b128 v[240:243], v151 offset:3072
	s_add_u32 s2, s41, s2
	s_addc_u32 s3, s44, s3
	v_lshl_add_u64 v[248:249], s[2:3], 0, v[130:131]
	v_readfirstlane_b32 s26, v135
	s_add_u32 s2, s2, s53
	s_mov_b32 m0, s26
	s_addc_u32 s3, s3, 0
	global_load_lds_dwordx4 v[248:249], off
	v_lshl_add_u64 v[248:249], s[2:3], 0, v[130:131]
	v_readfirstlane_b32 s2, v134
	s_mov_b32 m0, s2
	s_nop 0
	global_load_lds_dwordx4 v[248:249], off
	s_waitcnt vmcnt(8)
	s_barrier
	s_waitcnt lgkmcnt(0)
	s_setprio 1
	v_mfma_f32_16x16x32_bf16 v[126:129], v[182:185], v[166:169], v[126:129]
	v_mfma_f32_16x16x32_bf16 v[122:125], v[182:185], v[174:177], v[122:125]
	v_mfma_f32_16x16x32_bf16 v[118:121], v[190:193], v[166:169], v[118:121]
	v_mfma_f32_16x16x32_bf16 v[114:117], v[190:193], v[174:177], v[114:117]
	v_mfma_f32_16x16x32_bf16 v[110:113], v[202:205], v[166:169], v[110:113]
	v_mfma_f32_16x16x32_bf16 v[106:109], v[202:205], v[174:177], v[106:109]
	v_mfma_f32_16x16x32_bf16 v[102:105], v[216:219], v[166:169], v[102:105]
	v_mfma_f32_16x16x32_bf16 v[98:101], v[216:219], v[174:177], v[98:101]
	v_mfma_f32_16x16x32_bf16 v[126:129], v[186:189], v[170:173], v[126:129]
	v_mfma_f32_16x16x32_bf16 v[122:125], v[186:189], v[178:181], v[122:125]
	v_mfma_f32_16x16x32_bf16 v[118:121], v[194:197], v[170:173], v[118:121]
	v_mfma_f32_16x16x32_bf16 v[114:117], v[194:197], v[178:181], v[114:117]
	v_mfma_f32_16x16x32_bf16 v[110:113], v[206:209], v[170:173], v[110:113]
	v_mfma_f32_16x16x32_bf16 v[106:109], v[206:209], v[178:181], v[106:109]
	v_mfma_f32_16x16x32_bf16 v[102:105], v[222:225], v[170:173], v[102:105]
	v_mfma_f32_16x16x32_bf16 v[98:101], v[222:225], v[178:181], v[98:101]
	v_mfma_f32_16x16x32_bf16 v[94:97], v[182:185], v[228:231], v[94:97]
	v_mfma_f32_16x16x32_bf16 v[90:93], v[182:185], v[236:239], v[90:93]
	v_mfma_f32_16x16x32_bf16 v[86:89], v[190:193], v[228:231], v[86:89]
	v_mfma_f32_16x16x32_bf16 v[82:85], v[190:193], v[236:239], v[82:85]
	v_mfma_f32_16x16x32_bf16 v[78:81], v[202:205], v[228:231], v[78:81]
	v_mfma_f32_16x16x32_bf16 v[74:77], v[202:205], v[236:239], v[74:77]
	v_mfma_f32_16x16x32_bf16 v[70:73], v[216:219], v[228:231], v[70:73]
	v_mfma_f32_16x16x32_bf16 v[66:69], v[216:219], v[236:239], v[66:69]
	v_mfma_f32_16x16x32_bf16 v[94:97], v[186:189], v[232:235], v[94:97]
	v_mfma_f32_16x16x32_bf16 v[90:93], v[186:189], v[240:243], v[90:93]
	v_mfma_f32_16x16x32_bf16 v[86:89], v[194:197], v[232:235], v[86:89]
	v_mfma_f32_16x16x32_bf16 v[82:85], v[194:197], v[240:243], v[82:85]
	v_mfma_f32_16x16x32_bf16 v[78:81], v[206:209], v[232:235], v[78:81]
	v_mfma_f32_16x16x32_bf16 v[74:77], v[206:209], v[240:243], v[74:77]
	v_mfma_f32_16x16x32_bf16 v[70:73], v[222:225], v[232:235], v[70:73]
	v_mfma_f32_16x16x32_bf16 v[66:69], v[222:225], v[240:243], v[66:69]
	s_setprio 0
	s_barrier
; #define STAGE_B(P, br, kt) do { const char* _gb = (const char*)(Bt + ((long)(br) * K + (long)(kt) * BK)); \
;     __builtin_amdgcn_global_load_lds((const unsigned*)(_gb + bofl0), (unsigned*)((char*)(P) + gtid_ * 16), 16, 0, 0); \
;     __builtin_amdgcn_global_load_lds((const unsigned*)(_gb + (long)K * 128 + bofl0), (unsigned*)((char*)(P) + gtid_ * 16 + 8192), 16, 0, 0); } while (0)
; #define LDA(dst, b, h) for (int m = 0; m < 4; ++m) for (int k = 0; k < 2; ++k) \
;     dst[m][k] = *reinterpret_cast<const bf16x8*>((char*)SA(b, h) + lds_byte(wr * 64 + m * 16 + fr, k * 32 + fq * 8))
; #define LDB(dst, b, h) for (int n = 0; n < 2; ++n) for (int k = 0; k < 2; ++k) \
;     dst[n][k] = *reinterpret_cast<const bf16x8*>((char*)SB(b, h) + lds_byte(wc * 32 + n * 16 + fr, k * 32 + fq * 8))
; #define MMA(ai, bj, At_, Bt_) do { __builtin_amdgcn_s_setprio(1); \
;     for (int m = 0; m < 4; ++m) for (int n = 0; n < 2; ++n) for (int k = 0; k < 2; ++k) \
;       acc[ai][bj][m][n] = __builtin_amdgcn_mfma_f32_16x16x32_bf16(At_[m][k], Bt_[n][k], acc[ai][bj][m][n], 0, 0, 0); \
;     __builtin_amdgcn_s_setprio(0); } while (0)
; #define WAIT_V(n) asm volatile("s_waitcnt vmcnt(" #n ")" ::: "memory")
; #define WAIT_L(n) asm volatile("s_waitcnt lgkmcnt(" #n ")" ::: "memory")
; #define BAR __builtin_amdgcn_s_barrier()
; #define SCHED __builtin_amdgcn_sched_barrier(0)
; template <int EPI>
; __device__ __forceinline__ void gemm_tile(const GemmArgs& g, int brow, int bcol, int parity, bool first, bool nvalid, int nbrow, int nbcol) {
;     ...
;     WAIT_V(6); BAR; MMA(1, 1, At, B1); BAR; SCHED;
;     LDB(B0, 1, 0); SCHED; LDA(At, 1, 0); STAGE_A(SA(0, 1), brow + HALF, t + 2);
;     WAIT_L(8); BAR; WAIT_L(0); MMA(0, 0, At, B0); BAR; SCHED;
;     LDB(B1, 1, 1); STAGE_B(SB(1, 0), bcol, t + 3);
;     BAR; WAIT_L(0); MMA(0, 1, At, B1); BAR; SCHED;
;     LDA(At, 1, 1); STAGE_A(SA(1, 0), brow, t + 3);
;     BAR; WAIT_L(0); MMA(1, 0, At, B0); BAR; SCHED;
;     STAGE_B(SB(1, 1), bcol + HALF, t + 3);
;     WAIT_V(6); BAR; MMA(1, 1, At, B1); BAR; SCHED;
;   }
;   { LDB(B0, 0, 0); LDA(At, 0, 0); STAGE_A(SA(1, 1), brow + HALF, nt - 1);
;     BAR; WAIT_L(0); MMA(0, 0, At, B0); BAR;
	ds_read_b128 v[182:185], v150 offset:49152
	ds_read_b128 v[186:189], v150 offset:50176
	ds_read_b128 v[190:193], v149 offset:49152
	ds_read_b128 v[194:197], v149 offset:50176
	ds_read_b128 v[202:205], v148 offset:49152
	ds_read_b128 v[206:209], v148 offset:50176
	ds_read_b128 v[216:219], v147 offset:49152
	ds_read_b128 v[222:225], v147 offset:50176
	v_readfirstlane_b32 s2, v152
	v_lshl_add_u64 v[198:199], v[198:199], 0, s[58:59]
	s_mov_b32 m0, s2
	v_readfirstlane_b32 s2, v153
	global_load_lds_dwordx4 v[198:199], off
	v_lshl_add_u64 v[198:199], v[210:211], 0, s[58:59]
	s_mov_b32 m0, s2
	s_nop 0
	global_load_lds_dwordx4 v[198:199], off
	s_cmp_lt_u32 s61, s35
	s_cselect_b32 s2, s36, s57
	s_add_i32 s2, s2, s61
	s_ashr_i32 s3, s2, 31
	s_lshl_b64 s[2:3], s[2:3], 1
	s_add_u32 s2, s25, s2
	s_addc_u32 s3, s39, s3
	v_lshl_add_u64 v[198:199], s[2:3], 0, v[130:131]
	v_readfirstlane_b32 s26, v155
	s_add_u32 s2, s2, s53
	s_mov_b32 m0, s26
	s_addc_u32 s3, s3, 0
	global_load_lds_dwordx4 v[198:199], off
	v_lshl_add_u64 v[198:199], s[2:3], 0, v[130:131]
	v_readfirstlane_b32 s2, v156
	s_mov_b32 m0, s2
	s_nop 0
	global_load_lds_dwordx4 v[198:199], off
	v_readfirstlane_b32 s2, v157
	v_lshl_add_u64 v[246:247], v[212:213], 0, s[58:59]
	s_mov_b32 m0, s2
	v_readfirstlane_b32 s2, v158
	global_load_lds_dwordx4 v[246:247], off
	v_lshl_add_u64 v[246:247], v[244:245], 0, s[58:59]
	s_mov_b32 m0, s2
	s_nop 0
	global_load_lds_dwordx4 v[246:247], off
	s_waitcnt vmcnt(8)
	s_barrier
	s_waitcnt lgkmcnt(0)
	s_setprio 1
	v_mfma_f32_16x16x32_bf16 v[62:65], v[182:185], v[166:169], v[62:65]
	v_mfma_f32_16x16x32_bf16 v[58:61], v[182:185], v[174:177], v[58:61]
	v_mfma_f32_16x16x32_bf16 v[54:57], v[190:193], v[166:169], v[54:57]
	v_mfma_f32_16x16x32_bf16 v[50:53], v[190:193], v[174:177], v[50:53]
	v_mfma_f32_16x16x32_bf16 v[46:49], v[202:205], v[166:169], v[46:49]
	v_mfma_f32_16x16x32_bf16 v[42:45], v[202:205], v[174:177], v[42:45]
	v_mfma_f32_16x16x32_bf16 v[38:41], v[216:219], v[166:169], v[38:41]
	v_mfma_f32_16x16x32_bf16 v[34:37], v[216:219], v[174:177], v[34:37]
	v_mfma_f32_16x16x32_bf16 v[62:65], v[186:189], v[170:173], v[62:65]
	v_mfma_f32_16x16x32_bf16 v[58:61], v[186:189], v[178:181], v[58:61]
	v_mfma_f32_16x16x32_bf16 v[54:57], v[194:197], v[170:173], v[54:57]
	v_mfma_f32_16x16x32_bf16 v[50:53], v[194:197], v[178:181], v[50:53]
	v_mfma_f32_16x16x32_bf16 v[46:49], v[206:209], v[170:173], v[46:49]
	v_mfma_f32_16x16x32_bf16 v[42:45], v[206:209], v[178:181], v[42:45]
	v_mfma_f32_16x16x32_bf16 v[38:41], v[222:225], v[170:173], v[38:41]
	v_mfma_f32_16x16x32_bf16 v[34:37], v[222:225], v[178:181], v[34:37]
	v_mfma_f32_16x16x32_bf16 v[30:33], v[182:185], v[228:231], v[30:33]
	v_mfma_f32_16x16x32_bf16 v[26:29], v[182:185], v[236:239], v[26:29]
	v_mfma_f32_16x16x32_bf16 v[22:25], v[190:193], v[228:231], v[22:25]
	v_mfma_f32_16x16x32_bf16 v[18:21], v[190:193], v[236:239], v[18:21]
	v_mfma_f32_16x16x32_bf16 v[14:17], v[202:205], v[228:231], v[14:17]
	v_mfma_f32_16x16x32_bf16 v[10:13], v[202:205], v[236:239], v[10:13]
	v_mfma_f32_16x16x32_bf16 v[6:9], v[216:219], v[228:231], v[6:9]
	v_mfma_f32_16x16x32_bf16 v[2:5], v[216:219], v[236:239], v[2:5]
	v_mfma_f32_16x16x32_bf16 v[30:33], v[186:189], v[232:235], v[30:33]
	v_mfma_f32_16x16x32_bf16 v[26:29], v[186:189], v[240:243], v[26:29]
	v_mfma_f32_16x16x32_bf16 v[22:25], v[194:197], v[232:235], v[22:25]
	v_mfma_f32_16x16x32_bf16 v[18:21], v[194:197], v[240:243], v[18:21]
	v_mfma_f32_16x16x32_bf16 v[14:17], v[206:209], v[232:235], v[14:17]
	v_mfma_f32_16x16x32_bf16 v[10:13], v[206:209], v[240:243], v[10:13]
	v_mfma_f32_16x16x32_bf16 v[6:9], v[222:225], v[232:235], v[6:9]
	v_mfma_f32_16x16x32_bf16 v[2:5], v[222:225], v[240:243], v[2:5]
	s_setprio 0
	s_barrier
	s_addk_i32 s61, 0x80
	s_add_u32 s14, s14, 0x100
	s_addc_u32 s15, s15, 0
	s_add_u32 s18, s18, 0x100
	s_addc_u32 s19, s19, 0
	s_add_u32 s20, s20, 0x100
	s_addc_u32 s21, s21, 0
	s_add_u32 s22, s22, 0x100
	s_addc_u32 s23, s23, 0
	s_cmp_lt_i32 s45, s56
	s_cbranch_scc1 .LBB0_191
	s_add_u32 s2, s76, s12
	s_addc_u32 s3, s77, s13
	s_movk_i32 s14, 0xff80
	v_lshl_add_u64 v[132:133], s[2:3], 0, v[130:131]
	s_mov_b32 s15, -1
	v_readfirstlane_b32 s12, v165
	s_add_u32 s2, s2, s53
	v_lshl_add_u64 v[132:133], v[132:133], 0, s[14:15]
	s_mov_b32 m0, s12
	s_addc_u32 s3, s3, 0
	ds_read_b128 v[166:169], v160
	ds_read_b128 v[170:173], v160 offset:1024
	ds_read_b128 v[174:177], v160 offset:2048
	ds_read_b128 v[178:181], v160 offset:3072
	ds_read_b128 v[182:185], v150
	ds_read_b128 v[186:189], v150 offset:1024
	ds_read_b128 v[190:193], v149
	ds_read_b128 v[194:197], v149 offset:1024
	ds_read_b128 v[202:205], v148
	ds_read_b128 v[206:209], v148 offset:1024
	ds_read_b128 v[216:219], v147
	ds_read_b128 v[222:225], v147 offset:1024
	global_load_lds_dwordx4 v[132:133], off
	v_lshl_add_u64 v[132:133], s[2:3], 0, v[130:131]
	v_readfirstlane_b32 s2, v164
	v_lshl_add_u64 v[132:133], v[132:133], 0, s[14:15]
	s_mov_b32 m0, s2
	s_nop 0
	global_load_lds_dwordx4 v[132:133], off
	s_waitcnt vmcnt(8)
	s_barrier
	s_waitcnt lgkmcnt(0)
	s_setprio 1
	s_waitcnt lgkmcnt(0)
	v_mfma_f32_16x16x32_bf16 v[126:129], v[182:185], v[166:169], v[126:129]
	v_mfma_f32_16x16x32_bf16 v[122:125], v[182:185], v[174:177], v[122:125]
	v_mfma_f32_16x16x32_bf16 v[118:121], v[190:193], v[166:169], v[118:121]
	v_mfma_f32_16x16x32_bf16 v[106:109], v[202:205], v[174:177], v[106:109]
	v_mfma_f32_16x16x32_bf16 v[126:129], v[186:189], v[170:173], v[126:129]
	v_mfma_f32_16x16x32_bf16 v[122:125], v[186:189], v[178:181], v[122:125]
	v_mfma_f32_16x16x32_bf16 v[118:121], v[194:197], v[170:173], v[118:121]
	v_mfma_f32_16x16x32_bf16 v[114:117], v[190:193], v[174:177], v[114:117]
	v_mfma_f32_16x16x32_bf16 v[110:113], v[202:205], v[166:169], v[110:113]
	v_mfma_f32_16x16x32_bf16 v[106:109], v[206:209], v[178:181], v[106:109]
	v_mfma_f32_16x16x32_bf16 v[102:105], v[216:219], v[166:169], v[102:105]
	v_mfma_f32_16x16x32_bf16 v[98:101], v[216:219], v[174:177], v[98:101]
	v_mfma_f32_16x16x32_bf16 v[228:231], v[194:197], v[178:181], v[114:117]
	v_mfma_f32_16x16x32_bf16 v[232:235], v[206:209], v[170:173], v[110:113]
	v_mfma_f32_16x16x32_bf16 v[236:239], v[222:225], v[170:173], v[102:105]
	v_mfma_f32_16x16x32_bf16 v[240:243], v[222:225], v[178:181], v[98:101]
	s_setprio 0
	s_barrier
; #define LDA(dst, b, h) for (int m = 0; m < 4; ++m) for (int k = 0; k < 2; ++k) \
;     dst[m][k] = *reinterpret_cast<const bf16x8*>((char*)SA(b, h) + lds_byte(wr * 64 + m * 16 + fr, k * 32 + fq * 8))
; #define LDB(dst, b, h) for (int n = 0; n < 2; ++n) for (int k = 0; k < 2; ++k) \
;     dst[n][k] = *reinterpret_cast<const bf16x8*>((char*)SB(b, h) + lds_byte(wc * 32 + n * 16 + fr, k * 32 + fq * 8))
; #define MMA(ai, bj, At_, Bt_) do { __builtin_amdgcn_s_setprio(1); \
;     for (int m = 0; m < 4; ++m) for (int n = 0; n < 2; ++n) for (int k = 0; k < 2; ++k) \
;       acc[ai][bj][m][n] = __builtin_amdgcn_mfma_f32_16x16x32_bf16(At_[m][k], Bt_[n][k], acc[ai][bj][m][n], 0, 0, 0); \
;     __builtin_amdgcn_s_setprio(0); } while (0)
; #define WAIT_V(n) asm volatile("s_waitcnt vmcnt(" #n ")" ::: "memory")
; #define WAIT_L(n) asm volatile("s_waitcnt lgkmcnt(" #n ")" ::: "memory")
; #define BAR __builtin_amdgcn_s_barrier()
; #define SCHED __builtin_amdgcn_sched_barrier(0)
; template <int EPI>
; __device__ __forceinline__ void gemm_tile(const GemmArgs& g, int brow, int bcol, int parity, bool first, bool nvalid, int nbrow, int nbcol) {
;     ...
;   { LDB(B0, 0, 0); LDA(At, 0, 0); STAGE_A(SA(1, 1), brow + HALF, nt - 1);
;     BAR; WAIT_L(0); MMA(0, 0, At, B0); BAR;
;     LDB(B1, 0, 1); BAR; WAIT_L(0); MMA(0, 1, At, B1); BAR; SCHED;
;     LDA(At, 0, 1); WAIT_V(4); BAR; WAIT_L(0); MMA(1, 0, At, B0); MMA(1, 1, At, B1); BAR; }
;   { LDB(B0, 1, 0); LDA(At, 1, 0); WAIT_V(2); BAR; WAIT_L(0); MMA(0, 0, At, B0); BAR;
	s_nop 1
	ds_read_b128 v[98:101], v159
	ds_read_b128 v[102:105], v159 offset:1024
	ds_read_b128 v[110:113], v159 offset:2048
	ds_read_b128 v[114:117], v159 offset:3072
	s_barrier
	s_waitcnt lgkmcnt(0)
	s_setprio 1
	s_waitcnt lgkmcnt(0)
	v_mfma_f32_16x16x32_bf16 v[94:97], v[182:185], v[98:101], v[94:97]
	v_mfma_f32_16x16x32_bf16 v[90:93], v[182:185], v[110:113], v[90:93]
	v_mfma_f32_16x16x32_bf16 v[86:89], v[190:193], v[98:101], v[86:89]
	v_mfma_f32_16x16x32_bf16 v[78:81], v[202:205], v[98:101], v[78:81]
	v_mfma_f32_16x16x32_bf16 v[94:97], v[186:189], v[102:105], v[94:97]
	v_mfma_f32_16x16x32_bf16 v[90:93], v[186:189], v[114:117], v[90:93]
	v_mfma_f32_16x16x32_bf16 v[86:89], v[194:197], v[102:105], v[86:89]
	v_mfma_f32_16x16x32_bf16 v[82:85], v[190:193], v[110:113], v[82:85]
	v_mfma_f32_16x16x32_bf16 v[78:81], v[206:209], v[102:105], v[78:81]
	v_mfma_f32_16x16x32_bf16 v[74:77], v[202:205], v[110:113], v[74:77]
	v_mfma_f32_16x16x32_bf16 v[70:73], v[216:219], v[98:101], v[70:73]
	v_mfma_f32_16x16x32_bf16 v[66:69], v[216:219], v[110:113], v[66:69]
	v_mfma_f32_16x16x32_bf16 v[156:159], v[194:197], v[114:117], v[82:85]
	v_mfma_f32_16x16x32_bf16 v[182:185], v[206:209], v[114:117], v[74:77]
	v_mfma_f32_16x16x32_bf16 v[186:189], v[222:225], v[102:105], v[70:73]
	v_mfma_f32_16x16x32_bf16 v[190:193], v[222:225], v[114:117], v[66:69]
	s_setprio 0
	s_barrier
	s_nop 1
	ds_read_b128 v[66:69], v150 offset:16384
	ds_read_b128 v[70:73], v150 offset:17408
	ds_read_b128 v[74:77], v149 offset:16384
	ds_read_b128 v[82:85], v149 offset:17408
	ds_read_b128 v[194:197], v148 offset:16384
	ds_read_b128 v[202:205], v148 offset:17408
	ds_read_b128 v[206:209], v147 offset:16384
	ds_read_b128 v[216:219], v147 offset:17408
	s_waitcnt vmcnt(4)
	s_barrier
	s_waitcnt lgkmcnt(0)
	s_setprio 1
	s_waitcnt lgkmcnt(0)
	v_mfma_f32_16x16x32_bf16 v[62:65], v[66:69], v[166:169], v[62:65]
	v_mfma_f32_16x16x32_bf16 v[58:61], v[66:69], v[174:177], v[58:61]
	v_mfma_f32_16x16x32_bf16 v[54:57], v[74:77], v[166:169], v[54:57]
	v_mfma_f32_16x16x32_bf16 v[46:49], v[194:197], v[166:169], v[46:49]
	v_mfma_f32_16x16x32_bf16 v[62:65], v[70:73], v[170:173], v[62:65]
	v_mfma_f32_16x16x32_bf16 v[58:61], v[70:73], v[178:181], v[58:61]
	v_mfma_f32_16x16x32_bf16 v[54:57], v[82:85], v[170:173], v[54:57]
	v_mfma_f32_16x16x32_bf16 v[50:53], v[74:77], v[174:177], v[50:53]
	v_mfma_f32_16x16x32_bf16 v[46:49], v[202:205], v[170:173], v[46:49]
	v_mfma_f32_16x16x32_bf16 v[42:45], v[194:197], v[174:177], v[42:45]
	v_mfma_f32_16x16x32_bf16 v[38:41], v[206:209], v[166:169], v[38:41]
	v_mfma_f32_16x16x32_bf16 v[34:37], v[206:209], v[174:177], v[34:37]
	v_mfma_f32_16x16x32_bf16 v[222:225], v[82:85], v[178:181], v[50:53]
	v_mfma_f32_16x16x32_bf16 v[244:247], v[202:205], v[178:181], v[42:45]
	v_mfma_f32_16x16x32_bf16 v[164:167], v[216:219], v[170:173], v[38:41]
	v_mfma_f32_16x16x32_bf16 v[168:171], v[216:219], v[178:181], v[34:37]
	s_setprio 0
	s_setprio 1
	v_mfma_f32_16x16x32_bf16 v[30:33], v[66:69], v[98:101], v[30:33]
	v_mfma_f32_16x16x32_bf16 v[26:29], v[66:69], v[110:113], v[26:29]
	v_mfma_f32_16x16x32_bf16 v[22:25], v[74:77], v[98:101], v[22:25]
	v_mfma_f32_16x16x32_bf16 v[14:17], v[194:197], v[98:101], v[14:17]
	v_mfma_f32_16x16x32_bf16 v[30:33], v[70:73], v[102:105], v[30:33]
	v_mfma_f32_16x16x32_bf16 v[26:29], v[70:73], v[114:117], v[26:29]
	v_mfma_f32_16x16x32_bf16 v[22:25], v[82:85], v[102:105], v[22:25]
	v_mfma_f32_16x16x32_bf16 v[18:21], v[74:77], v[110:113], v[18:21]
	v_mfma_f32_16x16x32_bf16 v[14:17], v[202:205], v[102:105], v[14:17]
	v_mfma_f32_16x16x32_bf16 v[10:13], v[194:197], v[110:113], v[10:13]
	v_mfma_f32_16x16x32_bf16 v[6:9], v[206:209], v[98:101], v[6:9]
	v_mfma_f32_16x16x32_bf16 v[2:5], v[206:209], v[110:113], v[2:5]
	v_mfma_f32_16x16x32_bf16 v[172:175], v[82:85], v[114:117], v[18:21]
	v_mfma_f32_16x16x32_bf16 v[176:179], v[202:205], v[114:117], v[10:13]
	v_mfma_f32_16x16x32_bf16 v[194:197], v[216:219], v[102:105], v[6:9]
	v_mfma_f32_16x16x32_bf16 v[202:205], v[216:219], v[114:117], v[2:5]
	s_setprio 0
	s_barrier
	s_nop 1
	ds_read_b128 v[2:5], v154
	ds_read_b128 v[6:9], v154 offset:1024
	ds_read_b128 v[10:13], v154 offset:2048
	ds_read_b128 v[18:21], v154 offset:3072
	ds_read_b128 v[34:37], v150 offset:32768
	ds_read_b128 v[38:41], v150 offset:33792
	ds_read_b128 v[42:45], v149 offset:32768
	ds_read_b128 v[50:53], v149 offset:33792
	ds_read_b128 v[152:155], v148 offset:32768
	ds_read_b128 v[206:209], v148 offset:33792
	ds_read_b128 v[216:219], v147 offset:32768
	ds_read_b128 v[248:251], v147 offset:33792
	s_waitcnt vmcnt(2)
	s_barrier
; #define LDA(dst, b, h) for (int m = 0; m < 4; ++m) for (int k = 0; k < 2; ++k) \
;     dst[m][k] = *reinterpret_cast<const bf16x8*>((char*)SA(b, h) + lds_byte(wr * 64 + m * 16 + fr, k * 32 + fq * 8))
; #define LDB(dst, b, h) for (int n = 0; n < 2; ++n) for (int k = 0; k < 2; ++k) \
;     dst[n][k] = *reinterpret_cast<const bf16x8*>((char*)SB(b, h) + lds_byte(wc * 32 + n * 16 + fr, k * 32 + fq * 8))
; #define MMA(ai, bj, At_, Bt_) do { __builtin_amdgcn_s_setprio(1); \
;     for (int m = 0; m < 4; ++m) for (int n = 0; n < 2; ++n) for (int k = 0; k < 2; ++k) \
;       acc[ai][bj][m][n] = __builtin_amdgcn_mfma_f32_16x16x32_bf16(At_[m][k], Bt_[n][k], acc[ai][bj][m][n], 0, 0, 0); \
;     __builtin_amdgcn_s_setprio(0); } while (0)
; #define WAIT_V(n) asm volatile("s_waitcnt vmcnt(" #n ")" ::: "memory")
; #define WAIT_L(n) asm volatile("s_waitcnt lgkmcnt(" #n ")" ::: "memory")
; #define BAR __builtin_amdgcn_s_barrier()
; #define SCHED __builtin_amdgcn_sched_barrier(0)
; template <int EPI>
; __device__ __forceinline__ void gemm_tile(const GemmArgs& g, int brow, int bcol, int parity, bool first, bool nvalid, int nbrow, int nbcol) {
;     ...
;     LDA(At, 0, 1); WAIT_V(4); BAR; WAIT_L(0); MMA(1, 0, At, B0); MMA(1, 1, At, B1); BAR; }
;   { LDB(B0, 1, 0); LDA(At, 1, 0); WAIT_V(2); BAR; WAIT_L(0); MMA(0, 0, At, B0); BAR;
;     LDB(B1, 1, 1); WAIT_V(0); BAR; WAIT_L(0); MMA(0, 1, At, B1); BAR; SCHED;
;     LDA(At, 1, 1); BAR; WAIT_L(0); MMA(1, 0, At, B0); MMA(1, 1, At, B1); BAR; }
;   if (wr == 0) BAR;
	s_waitcnt lgkmcnt(0)
	s_setprio 1
	s_waitcnt lgkmcnt(0)
	v_mfma_f32_16x16x32_bf16 v[66:69], v[34:37], v[2:5], v[126:129]
	v_mfma_f32_16x16x32_bf16 v[114:117], v[38:41], v[6:9], v[66:69]
	v_mfma_f32_16x16x32_bf16 v[66:69], v[34:37], v[10:13], v[122:125]
	v_mfma_f32_16x16x32_bf16 v[126:129], v[38:41], v[18:21], v[66:69]
	v_mfma_f32_16x16x32_bf16 v[66:69], v[42:45], v[2:5], v[118:121]
	v_mfma_f32_16x16x32_bf16 v[110:113], v[50:53], v[6:9], v[66:69]
	v_mfma_f32_16x16x32_bf16 v[66:69], v[42:45], v[10:13], v[228:231]
	v_mfma_f32_16x16x32_bf16 v[122:125], v[50:53], v[18:21], v[66:69]
	v_mfma_f32_16x16x32_bf16 v[66:69], v[152:155], v[2:5], v[232:235]
	v_mfma_f32_16x16x32_bf16 v[102:105], v[206:209], v[6:9], v[66:69]
	v_mfma_f32_16x16x32_bf16 v[66:69], v[152:155], v[10:13], v[106:109]
	v_mfma_f32_16x16x32_bf16 v[118:121], v[206:209], v[18:21], v[66:69]
	v_mfma_f32_16x16x32_bf16 v[66:69], v[216:219], v[2:5], v[236:239]
	v_mfma_f32_16x16x32_bf16 v[98:101], v[248:251], v[6:9], v[66:69]
	v_mfma_f32_16x16x32_bf16 v[66:69], v[216:219], v[10:13], v[240:243]
	v_mfma_f32_16x16x32_bf16 v[106:109], v[248:251], v[18:21], v[66:69]
	s_setprio 0
	s_barrier
	ds_read_b128 v[228:231], v151
	ds_read_b128 v[232:235], v151 offset:1024
	ds_read_b128 v[236:239], v151 offset:2048
	ds_read_b128 v[240:243], v151 offset:3072
	s_waitcnt vmcnt(0)
	s_barrier
	s_waitcnt lgkmcnt(0)
	s_setprio 1
	s_waitcnt lgkmcnt(0)
	v_mfma_f32_16x16x32_bf16 v[66:69], v[34:37], v[228:231], v[94:97]
	v_mfma_f32_16x16x32_bf16 v[34:37], v[34:37], v[236:239], v[90:93]
	v_mfma_f32_16x16x32_bf16 v[82:85], v[38:41], v[240:243], v[34:37]
	v_mfma_f32_16x16x32_bf16 v[34:37], v[42:45], v[228:231], v[86:89]
	v_mfma_f32_16x16x32_bf16 v[70:73], v[50:53], v[232:235], v[34:37]
	v_mfma_f32_16x16x32_bf16 v[34:37], v[42:45], v[236:239], v[156:159]
	v_mfma_f32_16x16x32_bf16 v[86:89], v[50:53], v[240:243], v[34:37]
	v_mfma_f32_16x16x32_bf16 v[34:37], v[152:155], v[228:231], v[78:81]
	v_mfma_f32_16x16x32_bf16 v[74:77], v[206:209], v[232:235], v[34:37]
	v_mfma_f32_16x16x32_bf16 v[34:37], v[152:155], v[236:239], v[182:185]
	v_mfma_f32_16x16x32_bf16 v[90:93], v[206:209], v[240:243], v[34:37]
	v_mfma_f32_16x16x32_bf16 v[34:37], v[216:219], v[228:231], v[186:189]
	v_mfma_f32_16x16x32_bf16 v[78:81], v[248:251], v[232:235], v[34:37]
	v_mfma_f32_16x16x32_bf16 v[34:37], v[216:219], v[236:239], v[190:193]
	v_mfma_f32_16x16x32_bf16 v[66:69], v[38:41], v[232:235], v[66:69]
	v_mfma_f32_16x16x32_bf16 v[94:97], v[248:251], v[240:243], v[34:37]
	s_setprio 0
	s_barrier
	ds_read_b128 v[152:155], v150 offset:49152
	ds_read_b128 v[156:159], v150 offset:50176
	ds_read_b128 v[180:183], v149 offset:49152
	ds_read_b128 v[184:187], v149 offset:50176
	ds_read_b128 v[188:191], v148 offset:49152
	ds_read_b128 v[148:151], v148 offset:50176
	ds_read_b128 v[206:209], v147 offset:49152
	ds_read_b128 v[216:219], v147 offset:50176
	s_barrier
	s_waitcnt lgkmcnt(0)
	s_setprio 1
	s_waitcnt lgkmcnt(0)
	v_mfma_f32_16x16x32_bf16 v[38:41], v[152:155], v[10:13], v[58:61]
	v_mfma_f32_16x16x32_bf16 v[42:45], v[180:183], v[10:13], v[222:225]
	v_mfma_f32_16x16x32_bf16 v[34:37], v[152:155], v[2:5], v[62:65]
	v_mfma_f32_16x16x32_bf16 v[50:53], v[156:159], v[18:21], v[38:41]
	v_mfma_f32_16x16x32_bf16 v[38:41], v[180:183], v[2:5], v[54:57]
	v_mfma_f32_16x16x32_bf16 v[54:57], v[184:187], v[18:21], v[42:45]
	v_mfma_f32_16x16x32_bf16 v[42:45], v[188:191], v[2:5], v[46:49]
	v_mfma_f32_16x16x32_bf16 v[46:49], v[188:191], v[10:13], v[244:247]
	v_mfma_f32_16x16x32_bf16 v[2:5], v[206:209], v[2:5], v[164:167]
	v_mfma_f32_16x16x32_bf16 v[58:61], v[148:151], v[18:21], v[46:49]
	v_mfma_f32_16x16x32_bf16 v[46:49], v[216:219], v[6:9], v[2:5]
	v_mfma_f32_16x16x32_bf16 v[2:5], v[206:209], v[10:13], v[168:171]
	v_mfma_f32_16x16x32_bf16 v[34:37], v[156:159], v[6:9], v[34:37]
	v_mfma_f32_16x16x32_bf16 v[38:41], v[184:187], v[6:9], v[38:41]
	v_mfma_f32_16x16x32_bf16 v[42:45], v[148:151], v[6:9], v[42:45]
	v_mfma_f32_16x16x32_bf16 v[62:65], v[216:219], v[18:21], v[2:5]
	s_setprio 0
	s_setprio 1
	v_mfma_f32_16x16x32_bf16 v[6:9], v[152:155], v[236:239], v[26:29]
	v_mfma_f32_16x16x32_bf16 v[10:13], v[180:183], v[236:239], v[172:175]
	v_mfma_f32_16x16x32_bf16 v[18:21], v[156:159], v[240:243], v[6:9]
	v_mfma_f32_16x16x32_bf16 v[6:9], v[180:183], v[228:231], v[22:25]
	v_mfma_f32_16x16x32_bf16 v[22:25], v[184:187], v[240:243], v[10:13]
	v_mfma_f32_16x16x32_bf16 v[10:13], v[188:191], v[228:231], v[14:17]
	v_mfma_f32_16x16x32_bf16 v[14:17], v[188:191], v[236:239], v[176:179]
	v_mfma_f32_16x16x32_bf16 v[2:5], v[152:155], v[228:231], v[30:33]
	v_mfma_f32_16x16x32_bf16 v[26:29], v[148:151], v[240:243], v[14:17]
	v_mfma_f32_16x16x32_bf16 v[14:17], v[206:209], v[228:231], v[194:197]
	v_mfma_f32_16x16x32_bf16 v[30:33], v[206:209], v[236:239], v[202:205]
	v_mfma_f32_16x16x32_bf16 v[2:5], v[156:159], v[232:235], v[2:5]
	v_mfma_f32_16x16x32_bf16 v[6:9], v[184:187], v[232:235], v[6:9]
	v_mfma_f32_16x16x32_bf16 v[10:13], v[148:151], v[232:235], v[10:13]
	v_mfma_f32_16x16x32_bf16 v[14:17], v[216:219], v[232:235], v[14:17]
	v_mfma_f32_16x16x32_bf16 v[30:33], v[216:219], v[240:243], v[30:33]
	s_setprio 0
	s_movk_i32 s2, 0x100
	v_cmp_gt_u32_e32 vcc, s2, v141
	s_barrier
	s_and_saveexec_b64 s[12:13], vcc
	s_cbranch_execz .LBB0_194
	s_barrier

; #define STAGE_B(P, br, kt) do { const char* _gb = (const char*)(Bt + ((long)(br) * K + (long)(kt) * BK)); \
;     __builtin_amdgcn_global_load_lds((const unsigned*)(_gb + bofl0), (unsigned*)((char*)(P) + gtid_ * 16), 16, 0, 0); \
;     __builtin_amdgcn_global_load_lds((const unsigned*)(_gb + (long)K * 128 + bofl0), (unsigned*)((char*)(P) + gtid_ * 16 + 8192), 16, 0, 0); } while (0)
; #define LDA(dst, b, h) for (int m = 0; m < 4; ++m) for (int k = 0; k < 2; ++k) \
;     dst[m][k] = *reinterpret_cast<const bf16x8*>((char*)SA(b, h) + lds_byte(wr * 64 + m * 16 + fr, k * 32 + fq * 8))
; #define LDB(dst, b, h) for (int n = 0; n < 2; ++n) for (int k = 0; k < 2; ++k) \
;     dst[n][k] = *reinterpret_cast<const bf16x8*>((char*)SB(b, h) + lds_byte(wc * 32 + n * 16 + fr, k * 32 + fq * 8))
; #define MMA(ai, bj, At_, Bt_) do { __builtin_amdgcn_s_setprio(1); \
;     for (int m = 0; m < 4; ++m) for (int n = 0; n < 2; ++n) for (int k = 0; k < 2; ++k) \
;       acc[ai][bj][m][n] = __builtin_amdgcn_mfma_f32_16x16x32_bf16(At_[m][k], Bt_[n][k], acc[ai][bj][m][n], 0, 0, 0); \
;     __builtin_amdgcn_s_setprio(0); } while (0)
; #define WAIT_V(n) asm volatile("s_waitcnt vmcnt(" #n ")" ::: "memory")
; #define WAIT_L(n) asm volatile("s_waitcnt lgkmcnt(" #n ")" ::: "memory")
; #define BAR __builtin_amdgcn_s_barrier()
; #define SCHED __builtin_amdgcn_sched_barrier(0)
; template <int EPI>
; __device__ __forceinline__ void gemm_tile(const GemmArgs& g, int brow, int bcol, int parity, bool first, bool nvalid, int nbrow, int nbcol) {
;     ...
;   for (int t = 0; t < nt - 2; t += 2) {
;     LDB(B0, 0, 0); SCHED; LDA(At, 0, 0); STAGE_A(SA(1, 1), brow + HALF, t + 1);
;     WAIT_L(8); BAR; WAIT_L(0); MMA(0, 0, At, B0); BAR; SCHED;
;     LDB(B1, 0, 1); STAGE_B(SB(0, 0), bcol, t + 2);
;     BAR; WAIT_L(0); MMA(0, 1, At, B1); BAR; SCHED;
;     LDA(At, 0, 1); STAGE_A(SA(0, 0), brow, t + 2);
;     BAR; WAIT_L(0); MMA(1, 0, At, B0); BAR; SCHED;
;     STAGE_B(SB(0, 1), bcol + HALF, t + 2);
;     WAIT_V(6); BAR; MMA(1, 1, At, B1); BAR; SCHED;
.LBB0_640:
	ds_read_b128 v[164:167], v157
	ds_read_b128 v[168:171], v157 offset:1024
	ds_read_b128 v[172:175], v157 offset:2048
	ds_read_b128 v[176:179], v157 offset:3072
	ds_read_b128 v[180:183], v147
	ds_read_b128 v[184:187], v147 offset:1024
	ds_read_b128 v[188:191], v146
	ds_read_b128 v[192:195], v146 offset:1024
	ds_read_b128 v[196:199], v145
	ds_read_b128 v[202:205], v145 offset:1024
	ds_read_b128 v[206:209], v144
	ds_read_b128 v[216:219], v144 offset:1024
	s_waitcnt lgkmcnt(6)
	ds_read_b128 v[228:231], v154
	ds_read_b128 v[232:235], v154 offset:1024
	ds_read_b128 v[236:239], v154 offset:2048
	ds_read_b128 v[240:243], v154 offset:3072
	v_add_u32_e32 v161, 0xc000, v137
	v_lshl_add_u64 v[210:211], s[12:13], 0, v[130:131]
	v_readfirstlane_b32 s2, v161
	v_add_u32_e32 v162, 0xe000, v137
	v_lshl_add_u64 v[158:159], v[210:211], 0, s[24:25]
	s_mov_b32 m0, s2
	v_readfirstlane_b32 s2, v162
	global_load_lds_dwordx4 v[158:159], off
	v_lshl_add_u64 v[158:159], v[210:211], 0, s[36:37]
	s_mov_b32 m0, s2
	s_nop 0
	global_load_lds_dwordx4 v[158:159], off
	s_waitcnt vmcnt(8)
	s_barrier
	s_waitcnt lgkmcnt(0)
	s_setprio 1
	v_mfma_f32_16x16x32_bf16 v[126:129], v[164:167], v[180:183], v[126:129]
	v_mfma_f32_16x16x32_bf16 v[122:125], v[172:175], v[180:183], v[122:125]
	v_mfma_f32_16x16x32_bf16 v[118:121], v[164:167], v[188:191], v[118:121]
	v_mfma_f32_16x16x32_bf16 v[114:117], v[172:175], v[188:191], v[114:117]
	v_mfma_f32_16x16x32_bf16 v[110:113], v[164:167], v[196:199], v[110:113]
	v_mfma_f32_16x16x32_bf16 v[106:109], v[172:175], v[196:199], v[106:109]
	v_mfma_f32_16x16x32_bf16 v[102:105], v[164:167], v[206:209], v[102:105]
	v_mfma_f32_16x16x32_bf16 v[98:101], v[172:175], v[206:209], v[98:101]
	v_mfma_f32_16x16x32_bf16 v[126:129], v[168:171], v[184:187], v[126:129]
	v_mfma_f32_16x16x32_bf16 v[122:125], v[176:179], v[184:187], v[122:125]
	v_mfma_f32_16x16x32_bf16 v[118:121], v[168:171], v[192:195], v[118:121]
	v_mfma_f32_16x16x32_bf16 v[114:117], v[176:179], v[192:195], v[114:117]
	v_mfma_f32_16x16x32_bf16 v[110:113], v[168:171], v[202:205], v[110:113]
	v_mfma_f32_16x16x32_bf16 v[106:109], v[176:179], v[202:205], v[106:109]
	v_mfma_f32_16x16x32_bf16 v[102:105], v[168:171], v[216:219], v[102:105]
	v_mfma_f32_16x16x32_bf16 v[98:101], v[176:179], v[216:219], v[98:101]
	v_mfma_f32_16x16x32_bf16 v[94:97], v[228:231], v[180:183], v[94:97]
	v_mfma_f32_16x16x32_bf16 v[90:93], v[236:239], v[180:183], v[90:93]
	v_mfma_f32_16x16x32_bf16 v[86:89], v[228:231], v[188:191], v[86:89]
	v_mfma_f32_16x16x32_bf16 v[82:85], v[236:239], v[188:191], v[82:85]
	v_mfma_f32_16x16x32_bf16 v[78:81], v[228:231], v[196:199], v[78:81]
	v_mfma_f32_16x16x32_bf16 v[74:77], v[236:239], v[196:199], v[74:77]
	v_mfma_f32_16x16x32_bf16 v[70:73], v[228:231], v[206:209], v[70:73]
	v_mfma_f32_16x16x32_bf16 v[66:69], v[236:239], v[206:209], v[66:69]
	v_mfma_f32_16x16x32_bf16 v[94:97], v[232:235], v[184:187], v[94:97]
	v_mfma_f32_16x16x32_bf16 v[90:93], v[240:243], v[184:187], v[90:93]
	v_mfma_f32_16x16x32_bf16 v[86:89], v[232:235], v[192:195], v[86:89]
	v_mfma_f32_16x16x32_bf16 v[82:85], v[240:243], v[192:195], v[82:85]
	v_mfma_f32_16x16x32_bf16 v[78:81], v[232:235], v[202:205], v[78:81]
	v_mfma_f32_16x16x32_bf16 v[74:77], v[240:243], v[202:205], v[74:77]
	v_mfma_f32_16x16x32_bf16 v[70:73], v[232:235], v[216:219], v[70:73]
	v_mfma_f32_16x16x32_bf16 v[66:69], v[240:243], v[216:219], v[66:69]
	s_setprio 0
	s_barrier
	ds_read_b128 v[180:183], v147 offset:16384
	ds_read_b128 v[184:187], v147 offset:17408
	ds_read_b128 v[188:191], v146 offset:16384
	ds_read_b128 v[192:195], v146 offset:17408
	ds_read_b128 v[196:199], v145 offset:16384
	ds_read_b128 v[202:205], v145 offset:17408
	ds_read_b128 v[206:209], v144 offset:16384
	ds_read_b128 v[216:219], v144 offset:17408
	v_add_u32_e32 v158, s15, v142
	v_lshl_add_u64 v[212:213], s[0:1], 0, v[130:131]
	v_readfirstlane_b32 s2, v158
	v_add_u32_e32 v159, 0x2000, v158
	v_lshl_add_u64 v[222:223], v[212:213], 0, s[78:79]
	s_mov_b32 m0, s2
	v_readfirstlane_b32 s2, v159
	global_load_lds_dwordx4 v[222:223], off
	v_lshl_add_u64 v[222:223], v[212:213], 0, s[66:67]
	s_mov_b32 m0, s2
	s_nop 0
	global_load_lds_dwordx4 v[222:223], off
	v_readfirstlane_b32 s2, v137
	v_lshl_add_u64 v[222:223], v[210:211], 0, s[38:39]
	s_mov_b32 m0, s2
	v_readfirstlane_b32 s2, v136
	global_load_lds_dwordx4 v[222:223], off
	v_lshl_add_u64 v[222:223], v[210:211], 0, s[42:43]
	s_mov_b32 m0, s2
	s_nop 0
	global_load_lds_dwordx4 v[222:223], off
	v_readfirstlane_b32 s2, v135
	v_add_u32_e32 v160, 0x2000, v135
	v_lshl_add_u64 v[244:245], v[212:213], 0, s[76:77]
	s_mov_b32 m0, s2
	v_readfirstlane_b32 s2, v160
	global_load_lds_dwordx4 v[244:245], off
	v_lshl_add_u64 v[244:245], v[212:213], 0, s[96:97]
	s_mov_b32 m0, s2
	s_nop 0
	global_load_lds_dwordx4 v[244:245], off
	s_waitcnt vmcnt(8)
	s_barrier
; #define STAGE_B(P, br, kt) do { const char* _gb = (const char*)(Bt + ((long)(br) * K + (long)(kt) * BK)); \
;     __builtin_amdgcn_global_load_lds((const unsigned*)(_gb + bofl0), (unsigned*)((char*)(P) + gtid_ * 16), 16, 0, 0); \
;     __builtin_amdgcn_global_load_lds((const unsigned*)(_gb + (long)K * 128 + bofl0), (unsigned*)((char*)(P) + gtid_ * 16 + 8192), 16, 0, 0); } while (0)
; #define LDA(dst, b, h) for (int m = 0; m < 4; ++m) for (int k = 0; k < 2; ++k) \
;     dst[m][k] = *reinterpret_cast<const bf16x8*>((char*)SA(b, h) + lds_byte(wr * 64 + m * 16 + fr, k * 32 + fq * 8))
; #define LDB(dst, b, h) for (int n = 0; n < 2; ++n) for (int k = 0; k < 2; ++k) \
;     dst[n][k] = *reinterpret_cast<const bf16x8*>((char*)SB(b, h) + lds_byte(wc * 32 + n * 16 + fr, k * 32 + fq * 8))
; #define MMA(ai, bj, At_, Bt_) do { __builtin_amdgcn_s_setprio(1); \
;     for (int m = 0; m < 4; ++m) for (int n = 0; n < 2; ++n) for (int k = 0; k < 2; ++k) \
;       acc[ai][bj][m][n] = __builtin_amdgcn_mfma_f32_16x16x32_bf16(At_[m][k], Bt_[n][k], acc[ai][bj][m][n], 0, 0, 0); \
;     __builtin_amdgcn_s_setprio(0); } while (0)
; #define WAIT_V(n) asm volatile("s_waitcnt vmcnt(" #n ")" ::: "memory")
; #define WAIT_L(n) asm volatile("s_waitcnt lgkmcnt(" #n ")" ::: "memory")
; template <int EPI>
; __device__ __forceinline__ void gemm_tile(const GemmArgs& g, int brow, int bcol, int parity, bool first, bool nvalid, int nbrow, int nbcol) {
;     ...
;   for (int t = 0; t < nt - 2; t += 2) {
;     LDB(B0, 0, 0); SCHED; LDA(At, 0, 0); STAGE_A(SA(1, 1), brow + HALF, t + 1);
;     WAIT_L(8); BAR; WAIT_L(0); MMA(0, 0, At, B0); BAR; SCHED;
;     LDB(B1, 0, 1); STAGE_B(SB(0, 0), bcol, t + 2);
;     BAR; WAIT_L(0); MMA(0, 1, At, B1); BAR; SCHED;
;     LDA(At, 0, 1); STAGE_A(SA(0, 0), brow, t + 2);
;     BAR; WAIT_L(0); MMA(1, 0, At, B0); BAR; SCHED;
;     STAGE_B(SB(0, 1), bcol + HALF, t + 2);
;     WAIT_V(6); BAR; MMA(1, 1, At, B1); BAR; SCHED;
;     LDB(B0, 1, 0); SCHED; LDA(At, 1, 0); STAGE_A(SA(0, 1), brow + HALF, t + 2);
;     WAIT_L(8); BAR; WAIT_L(0); MMA(0, 0, At, B0); BAR; SCHED;
;     LDB(B1, 1, 1); STAGE_B(SB(1, 0), bcol, t + 3);
;     BAR; WAIT_L(0); MMA(0, 1, At, B1); BAR; SCHED;
;     LDA(At, 1, 1); STAGE_A(SA(1, 0), brow, t + 3);
;     BAR; WAIT_L(0); MMA(1, 0, At, B0); BAR; SCHED;
;     STAGE_B(SB(1, 1), bcol + HALF, t + 3);
;     WAIT_V(6); BAR; MMA(1, 1, At, B1); BAR; SCHED;
	s_waitcnt lgkmcnt(0)
	s_setprio 1
	v_mfma_f32_16x16x32_bf16 v[62:65], v[164:167], v[180:183], v[62:65]
	v_mfma_f32_16x16x32_bf16 v[58:61], v[172:175], v[180:183], v[58:61]
	v_mfma_f32_16x16x32_bf16 v[54:57], v[164:167], v[188:191], v[54:57]
	v_mfma_f32_16x16x32_bf16 v[50:53], v[172:175], v[188:191], v[50:53]
	v_mfma_f32_16x16x32_bf16 v[46:49], v[164:167], v[196:199], v[46:49]
	v_mfma_f32_16x16x32_bf16 v[42:45], v[172:175], v[196:199], v[42:45]
	v_mfma_f32_16x16x32_bf16 v[38:41], v[164:167], v[206:209], v[38:41]
	v_mfma_f32_16x16x32_bf16 v[34:37], v[172:175], v[206:209], v[34:37]
	v_mfma_f32_16x16x32_bf16 v[62:65], v[168:171], v[184:187], v[62:65]
	v_mfma_f32_16x16x32_bf16 v[58:61], v[176:179], v[184:187], v[58:61]
	v_mfma_f32_16x16x32_bf16 v[54:57], v[168:171], v[192:195], v[54:57]
	v_mfma_f32_16x16x32_bf16 v[50:53], v[176:179], v[192:195], v[50:53]
	v_mfma_f32_16x16x32_bf16 v[46:49], v[168:171], v[202:205], v[46:49]
	v_mfma_f32_16x16x32_bf16 v[42:45], v[176:179], v[202:205], v[42:45]
	v_mfma_f32_16x16x32_bf16 v[38:41], v[168:171], v[216:219], v[38:41]
	v_mfma_f32_16x16x32_bf16 v[34:37], v[176:179], v[216:219], v[34:37]
	v_mfma_f32_16x16x32_bf16 v[30:33], v[228:231], v[180:183], v[30:33]
	v_mfma_f32_16x16x32_bf16 v[26:29], v[236:239], v[180:183], v[26:29]
	v_mfma_f32_16x16x32_bf16 v[22:25], v[228:231], v[188:191], v[22:25]
	v_mfma_f32_16x16x32_bf16 v[18:21], v[236:239], v[188:191], v[18:21]
	v_mfma_f32_16x16x32_bf16 v[14:17], v[228:231], v[196:199], v[14:17]
	v_mfma_f32_16x16x32_bf16 v[10:13], v[236:239], v[196:199], v[10:13]
	v_mfma_f32_16x16x32_bf16 v[6:9], v[228:231], v[206:209], v[6:9]
	v_mfma_f32_16x16x32_bf16 v[2:5], v[236:239], v[206:209], v[2:5]
	v_mfma_f32_16x16x32_bf16 v[30:33], v[232:235], v[184:187], v[30:33]
	v_mfma_f32_16x16x32_bf16 v[26:29], v[240:243], v[184:187], v[26:29]
	v_mfma_f32_16x16x32_bf16 v[22:25], v[232:235], v[192:195], v[22:25]
	v_mfma_f32_16x16x32_bf16 v[18:21], v[240:243], v[192:195], v[18:21]
	v_mfma_f32_16x16x32_bf16 v[14:17], v[232:235], v[202:205], v[14:17]
	v_mfma_f32_16x16x32_bf16 v[10:13], v[240:243], v[202:205], v[10:13]
	v_mfma_f32_16x16x32_bf16 v[6:9], v[232:235], v[216:219], v[6:9]
	v_mfma_f32_16x16x32_bf16 v[2:5], v[240:243], v[216:219], v[2:5]
	s_setprio 0
	s_barrier
	ds_read_b128 v[164:167], v149
	ds_read_b128 v[168:171], v149 offset:1024
	ds_read_b128 v[172:175], v149 offset:2048
	ds_read_b128 v[176:179], v149 offset:3072
	ds_read_b128 v[180:183], v147 offset:32768
	ds_read_b128 v[184:187], v147 offset:33792
	ds_read_b128 v[188:191], v146 offset:32768
	ds_read_b128 v[192:195], v146 offset:33792
	ds_read_b128 v[196:199], v145 offset:32768
	ds_read_b128 v[202:205], v145 offset:33792
	ds_read_b128 v[206:209], v144 offset:32768
	ds_read_b128 v[216:219], v144 offset:33792
	s_waitcnt lgkmcnt(6)
	ds_read_b128 v[228:231], v148
	ds_read_b128 v[232:235], v148 offset:1024
	ds_read_b128 v[236:239], v148 offset:2048
	ds_read_b128 v[240:243], v148 offset:3072
	v_readfirstlane_b32 s2, v134
	v_lshl_add_u64 v[222:223], v[210:211], 0, s[44:45]
	s_mov_b32 m0, s2
	v_readfirstlane_b32 s2, v133
	global_load_lds_dwordx4 v[222:223], off
	v_lshl_add_u64 v[222:223], v[210:211], 0, s[46:47]
	s_mov_b32 m0, s2
	s_nop 0
	global_load_lds_dwordx4 v[222:223], off
	s_waitcnt vmcnt(8)
	s_barrier
	s_waitcnt lgkmcnt(0)
	s_setprio 1
	v_mfma_f32_16x16x32_bf16 v[126:129], v[164:167], v[180:183], v[126:129]
	v_mfma_f32_16x16x32_bf16 v[122:125], v[172:175], v[180:183], v[122:125]
	v_mfma_f32_16x16x32_bf16 v[118:121], v[164:167], v[188:191], v[118:121]
	v_mfma_f32_16x16x32_bf16 v[114:117], v[172:175], v[188:191], v[114:117]
	v_mfma_f32_16x16x32_bf16 v[110:113], v[164:167], v[196:199], v[110:113]
	v_mfma_f32_16x16x32_bf16 v[106:109], v[172:175], v[196:199], v[106:109]
	v_mfma_f32_16x16x32_bf16 v[102:105], v[164:167], v[206:209], v[102:105]
	v_mfma_f32_16x16x32_bf16 v[98:101], v[172:175], v[206:209], v[98:101]
	v_mfma_f32_16x16x32_bf16 v[126:129], v[168:171], v[184:187], v[126:129]
	v_mfma_f32_16x16x32_bf16 v[122:125], v[176:179], v[184:187], v[122:125]
	v_mfma_f32_16x16x32_bf16 v[118:121], v[168:171], v[192:195], v[118:121]
	v_mfma_f32_16x16x32_bf16 v[114:117], v[176:179], v[192:195], v[114:117]
	v_mfma_f32_16x16x32_bf16 v[110:113], v[168:171], v[202:205], v[110:113]
	v_mfma_f32_16x16x32_bf16 v[106:109], v[176:179], v[202:205], v[106:109]
	v_mfma_f32_16x16x32_bf16 v[102:105], v[168:171], v[216:219], v[102:105]
	v_mfma_f32_16x16x32_bf16 v[98:101], v[176:179], v[216:219], v[98:101]
	v_mfma_f32_16x16x32_bf16 v[94:97], v[228:231], v[180:183], v[94:97]
	v_mfma_f32_16x16x32_bf16 v[90:93], v[236:239], v[180:183], v[90:93]
	v_mfma_f32_16x16x32_bf16 v[86:89], v[228:231], v[188:191], v[86:89]
	v_mfma_f32_16x16x32_bf16 v[82:85], v[236:239], v[188:191], v[82:85]
	v_mfma_f32_16x16x32_bf16 v[78:81], v[228:231], v[196:199], v[78:81]
	v_mfma_f32_16x16x32_bf16 v[74:77], v[236:239], v[196:199], v[74:77]
	v_mfma_f32_16x16x32_bf16 v[70:73], v[228:231], v[206:209], v[70:73]
	v_mfma_f32_16x16x32_bf16 v[66:69], v[236:239], v[206:209], v[66:69]
	v_mfma_f32_16x16x32_bf16 v[94:97], v[232:235], v[184:187], v[94:97]
	v_mfma_f32_16x16x32_bf16 v[90:93], v[240:243], v[184:187], v[90:93]
	v_mfma_f32_16x16x32_bf16 v[86:89], v[232:235], v[192:195], v[86:89]
	v_mfma_f32_16x16x32_bf16 v[82:85], v[240:243], v[192:195], v[82:85]
	v_mfma_f32_16x16x32_bf16 v[78:81], v[232:235], v[202:205], v[78:81]
	v_mfma_f32_16x16x32_bf16 v[74:77], v[240:243], v[202:205], v[74:77]
	v_mfma_f32_16x16x32_bf16 v[70:73], v[232:235], v[216:219], v[70:73]
	v_mfma_f32_16x16x32_bf16 v[66:69], v[240:243], v[216:219], v[66:69]
	s_setprio 0
	s_barrier
; #define STAGE_B(P, br, kt) do { const char* _gb = (const char*)(Bt + ((long)(br) * K + (long)(kt) * BK)); \
;     __builtin_amdgcn_global_load_lds((const unsigned*)(_gb + bofl0), (unsigned*)((char*)(P) + gtid_ * 16), 16, 0, 0); \
;     __builtin_amdgcn_global_load_lds((const unsigned*)(_gb + (long)K * 128 + bofl0), (unsigned*)((char*)(P) + gtid_ * 16 + 8192), 16, 0, 0); } while (0)
; #define LDA(dst, b, h) for (int m = 0; m < 4; ++m) for (int k = 0; k < 2; ++k) \
;     dst[m][k] = *reinterpret_cast<const bf16x8*>((char*)SA(b, h) + lds_byte(wr * 64 + m * 16 + fr, k * 32 + fq * 8))
; #define LDB(dst, b, h) for (int n = 0; n < 2; ++n) for (int k = 0; k < 2; ++k) \
;     dst[n][k] = *reinterpret_cast<const bf16x8*>((char*)SB(b, h) + lds_byte(wc * 32 + n * 16 + fr, k * 32 + fq * 8))
; #define MMA(ai, bj, At_, Bt_) do { __builtin_amdgcn_s_setprio(1); \
;     for (int m = 0; m < 4; ++m) for (int n = 0; n < 2; ++n) for (int k = 0; k < 2; ++k) \
;       acc[ai][bj][m][n] = __builtin_amdgcn_mfma_f32_16x16x32_bf16(At_[m][k], Bt_[n][k], acc[ai][bj][m][n], 0, 0, 0); \
;     __builtin_amdgcn_s_setprio(0); } while (0)
; #define WAIT_V(n) asm volatile("s_waitcnt vmcnt(" #n ")" ::: "memory")
; #define WAIT_L(n) asm volatile("s_waitcnt lgkmcnt(" #n ")" ::: "memory")
; #define BAR __builtin_amdgcn_s_barrier()
; #define SCHED __builtin_amdgcn_sched_barrier(0)
; template <int EPI>
; __device__ __forceinline__ void gemm_tile(const GemmArgs& g, int brow, int bcol, int parity, bool first, bool nvalid, int nbrow, int nbcol) {
;     ...
;     WAIT_V(6); BAR; MMA(1, 1, At, B1); BAR; SCHED;
;     LDB(B0, 1, 0); SCHED; LDA(At, 1, 0); STAGE_A(SA(0, 1), brow + HALF, t + 2);
;     WAIT_L(8); BAR; WAIT_L(0); MMA(0, 0, At, B0); BAR; SCHED;
;     LDB(B1, 1, 1); STAGE_B(SB(1, 0), bcol, t + 3);
;     BAR; WAIT_L(0); MMA(0, 1, At, B1); BAR; SCHED;
;     LDA(At, 1, 1); STAGE_A(SA(1, 0), brow, t + 3);
;     BAR; WAIT_L(0); MMA(1, 0, At, B0); BAR; SCHED;
;     STAGE_B(SB(1, 1), bcol + HALF, t + 3);
;     WAIT_V(6); BAR; MMA(1, 1, At, B1); BAR; SCHED;
;   }
;   { LDB(B0, 0, 0); LDA(At, 0, 0); STAGE_A(SA(1, 1), brow + HALF, nt - 1);
;     BAR; WAIT_L(0); MMA(0, 0, At, B0); BAR;
	ds_read_b128 v[180:183], v147 offset:49152
	ds_read_b128 v[184:187], v147 offset:50176
	ds_read_b128 v[188:191], v146 offset:49152
	ds_read_b128 v[192:195], v146 offset:50176
	ds_read_b128 v[196:199], v145 offset:49152
	ds_read_b128 v[202:205], v145 offset:50176
	ds_read_b128 v[206:209], v144 offset:49152
	ds_read_b128 v[216:219], v144 offset:50176
	v_readfirstlane_b32 s2, v150
	v_lshl_add_u64 v[222:223], v[212:213], 0, s[58:59]
	s_mov_b32 m0, s2
	v_readfirstlane_b32 s2, v151
	global_load_lds_dwordx4 v[222:223], off
	v_lshl_add_u64 v[222:223], v[212:213], 0, vcc
	s_mov_b32 m0, s2
	s_nop 0
	global_load_lds_dwordx4 v[222:223], off
	v_readfirstlane_b32 s2, v152
	v_lshl_add_u64 v[222:223], v[210:211], 0, s[48:49]
	s_mov_b32 m0, s2
	v_readfirstlane_b32 s2, v153
	global_load_lds_dwordx4 v[222:223], off
	v_lshl_add_u64 v[210:211], v[210:211], 0, s[50:51]
	s_mov_b32 m0, s2
	s_nop 0
	global_load_lds_dwordx4 v[210:211], off
	v_readfirstlane_b32 s2, v155
	v_lshl_add_u64 v[244:245], v[212:213], 0, s[60:61]
	s_mov_b32 m0, s2
	v_readfirstlane_b32 s2, v156
	global_load_lds_dwordx4 v[244:245], off
	v_lshl_add_u64 v[244:245], v[212:213], 0, s[94:95]
	s_mov_b32 m0, s2
	s_nop 0
	global_load_lds_dwordx4 v[244:245], off
	s_waitcnt vmcnt(8)
	s_barrier
	s_waitcnt lgkmcnt(0)
	s_setprio 1
	v_mfma_f32_16x16x32_bf16 v[62:65], v[164:167], v[180:183], v[62:65]
	v_mfma_f32_16x16x32_bf16 v[58:61], v[172:175], v[180:183], v[58:61]
	v_mfma_f32_16x16x32_bf16 v[54:57], v[164:167], v[188:191], v[54:57]
	v_mfma_f32_16x16x32_bf16 v[50:53], v[172:175], v[188:191], v[50:53]
	v_mfma_f32_16x16x32_bf16 v[46:49], v[164:167], v[196:199], v[46:49]
	v_mfma_f32_16x16x32_bf16 v[42:45], v[172:175], v[196:199], v[42:45]
	v_mfma_f32_16x16x32_bf16 v[38:41], v[164:167], v[206:209], v[38:41]
	v_mfma_f32_16x16x32_bf16 v[34:37], v[172:175], v[206:209], v[34:37]
	v_mfma_f32_16x16x32_bf16 v[62:65], v[168:171], v[184:187], v[62:65]
	v_mfma_f32_16x16x32_bf16 v[58:61], v[176:179], v[184:187], v[58:61]
	v_mfma_f32_16x16x32_bf16 v[54:57], v[168:171], v[192:195], v[54:57]
	v_mfma_f32_16x16x32_bf16 v[50:53], v[176:179], v[192:195], v[50:53]
	v_mfma_f32_16x16x32_bf16 v[46:49], v[168:171], v[202:205], v[46:49]
	v_mfma_f32_16x16x32_bf16 v[42:45], v[176:179], v[202:205], v[42:45]
	v_mfma_f32_16x16x32_bf16 v[38:41], v[168:171], v[216:219], v[38:41]
	v_mfma_f32_16x16x32_bf16 v[34:37], v[176:179], v[216:219], v[34:37]
	v_mfma_f32_16x16x32_bf16 v[30:33], v[228:231], v[180:183], v[30:33]
	v_mfma_f32_16x16x32_bf16 v[26:29], v[236:239], v[180:183], v[26:29]
	v_mfma_f32_16x16x32_bf16 v[22:25], v[228:231], v[188:191], v[22:25]
	v_mfma_f32_16x16x32_bf16 v[18:21], v[236:239], v[188:191], v[18:21]
	v_mfma_f32_16x16x32_bf16 v[14:17], v[228:231], v[196:199], v[14:17]
	v_mfma_f32_16x16x32_bf16 v[10:13], v[236:239], v[196:199], v[10:13]
	v_mfma_f32_16x16x32_bf16 v[6:9], v[228:231], v[206:209], v[6:9]
	v_mfma_f32_16x16x32_bf16 v[2:5], v[236:239], v[206:209], v[2:5]
	v_mfma_f32_16x16x32_bf16 v[30:33], v[232:235], v[184:187], v[30:33]
	v_mfma_f32_16x16x32_bf16 v[26:29], v[240:243], v[184:187], v[26:29]
	v_mfma_f32_16x16x32_bf16 v[22:25], v[232:235], v[192:195], v[22:25]
	v_mfma_f32_16x16x32_bf16 v[18:21], v[240:243], v[192:195], v[18:21]
	v_mfma_f32_16x16x32_bf16 v[14:17], v[232:235], v[202:205], v[14:17]
	v_mfma_f32_16x16x32_bf16 v[10:13], v[240:243], v[202:205], v[10:13]
	v_mfma_f32_16x16x32_bf16 v[6:9], v[232:235], v[216:219], v[6:9]
	v_mfma_f32_16x16x32_bf16 v[2:5], v[240:243], v[216:219], v[2:5]
	s_setprio 0
	s_barrier
	s_add_i32 s23, s23, 2
	s_add_u32 s12, s12, 0x100
	s_addc_u32 s13, s13, 0
	s_add_u32 s0, s0, 0x100
	s_addc_u32 s1, s1, 0
	s_cmp_lt_u32 s23, 12
	s_cbranch_scc1 .LBB0_640
	s_or_b32 s0, s40, 0x80
	s_ashr_i32 s1, s0, 31
	s_lshl_b64 s[0:1], s[0:1], 11
	s_add_u32 s0, s80, s0
	s_addc_u32 s1, s81, s1
	v_lshl_add_u64 v[130:131], s[0:1], 0, v[0:1]
	s_mov_b64 s[0:1], 0x780
	ds_read_b128 v[150:153], v157
	ds_read_b128 v[164:167], v157 offset:1024
	ds_read_b128 v[168:171], v157 offset:2048
	ds_read_b128 v[172:175], v157 offset:3072
	ds_read_b128 v[176:179], v147
	ds_read_b128 v[180:183], v147 offset:1024
	ds_read_b128 v[184:187], v146
	ds_read_b128 v[188:191], v146 offset:1024
	ds_read_b128 v[192:195], v145
	ds_read_b128 v[196:199], v145 offset:1024
	ds_read_b128 v[202:205], v144
	ds_read_b128 v[206:209], v144 offset:1024
	v_lshl_add_u64 v[156:157], v[130:131], 0, s[0:1]
	v_readfirstlane_b32 s0, v161
	s_mov_b32 m0, s0
	s_mov_b64 s[0:1], 0x20780
	v_lshl_add_u64 v[130:131], v[130:131], 0, s[0:1]
	v_readfirstlane_b32 s0, v162
	global_load_lds_dwordx4 v[156:157], off
	s_mov_b32 m0, s0
	s_nop 0
	global_load_lds_dwordx4 v[130:131], off
	s_waitcnt vmcnt(8)
	s_barrier
	s_waitcnt lgkmcnt(0)
	s_setprio 1
	s_waitcnt lgkmcnt(0)
	v_mfma_f32_16x16x32_bf16 v[126:129], v[150:153], v[176:179], v[126:129]
	v_mfma_f32_16x16x32_bf16 v[118:121], v[150:153], v[184:187], v[118:121]
	v_mfma_f32_16x16x32_bf16 v[110:113], v[150:153], v[192:195], v[110:113]
	v_mfma_f32_16x16x32_bf16 v[102:105], v[150:153], v[202:205], v[102:105]
	v_mfma_f32_16x16x32_bf16 v[126:129], v[164:167], v[180:183], v[126:129]
	v_mfma_f32_16x16x32_bf16 v[122:125], v[168:171], v[176:179], v[122:125]
	v_mfma_f32_16x16x32_bf16 v[118:121], v[164:167], v[188:191], v[118:121]
	v_mfma_f32_16x16x32_bf16 v[114:117], v[168:171], v[184:187], v[114:117]
	v_mfma_f32_16x16x32_bf16 v[110:113], v[164:167], v[196:199], v[110:113]
	v_mfma_f32_16x16x32_bf16 v[106:109], v[168:171], v[192:195], v[106:109]
	v_mfma_f32_16x16x32_bf16 v[102:105], v[164:167], v[206:209], v[102:105]
	v_mfma_f32_16x16x32_bf16 v[98:101], v[168:171], v[202:205], v[98:101]
	v_mfma_f32_16x16x32_bf16 v[216:219], v[172:175], v[180:183], v[122:125]
	v_mfma_f32_16x16x32_bf16 v[228:231], v[172:175], v[188:191], v[114:117]
	v_mfma_f32_16x16x32_bf16 v[232:235], v[172:175], v[196:199], v[106:109]
	v_mfma_f32_16x16x32_bf16 v[236:239], v[172:175], v[206:209], v[98:101]
	s_setprio 0
	s_barrier
; #define LDA(dst, b, h) for (int m = 0; m < 4; ++m) for (int k = 0; k < 2; ++k) \
;     dst[m][k] = *reinterpret_cast<const bf16x8*>((char*)SA(b, h) + lds_byte(wr * 64 + m * 16 + fr, k * 32 + fq * 8))
; #define LDB(dst, b, h) for (int n = 0; n < 2; ++n) for (int k = 0; k < 2; ++k) \
;     dst[n][k] = *reinterpret_cast<const bf16x8*>((char*)SB(b, h) + lds_byte(wc * 32 + n * 16 + fr, k * 32 + fq * 8))
; #define MMA(ai, bj, At_, Bt_) do { __builtin_amdgcn_s_setprio(1); \
;     for (int m = 0; m < 4; ++m) for (int n = 0; n < 2; ++n) for (int k = 0; k < 2; ++k) \
;       acc[ai][bj][m][n] = __builtin_amdgcn_mfma_f32_16x16x32_bf16(At_[m][k], Bt_[n][k], acc[ai][bj][m][n], 0, 0, 0); \
;     __builtin_amdgcn_s_setprio(0); } while (0)
; #define WAIT_V(n) asm volatile("s_waitcnt vmcnt(" #n ")" ::: "memory")
; #define WAIT_L(n) asm volatile("s_waitcnt lgkmcnt(" #n ")" ::: "memory")
; #define BAR __builtin_amdgcn_s_barrier()
; #define SCHED __builtin_amdgcn_sched_barrier(0)
; template <int EPI>
; __device__ __forceinline__ void gemm_tile(const GemmArgs& g, int brow, int bcol, int parity, bool first, bool nvalid, int nbrow, int nbcol) {
;     ...
;   { LDB(B0, 0, 0); LDA(At, 0, 0); STAGE_A(SA(1, 1), brow + HALF, nt - 1);
;     BAR; WAIT_L(0); MMA(0, 0, At, B0); BAR;
;     LDB(B1, 0, 1); BAR; WAIT_L(0); MMA(0, 1, At, B1); BAR; SCHED;
;     LDA(At, 0, 1); WAIT_V(4); BAR; WAIT_L(0); MMA(1, 0, At, B0); MMA(1, 1, At, B1); BAR; }
;   { LDB(B0, 1, 0); LDA(At, 1, 0); WAIT_V(2); BAR; WAIT_L(0); MMA(0, 0, At, B0); BAR;
	s_nop 1
	ds_read_b128 v[98:101], v154
	ds_read_b128 v[106:109], v154 offset:1024
	ds_read_b128 v[114:117], v154 offset:2048
	ds_read_b128 v[122:125], v154 offset:3072
	s_barrier
	s_waitcnt lgkmcnt(0)
	s_setprio 1
	s_waitcnt lgkmcnt(0)
	v_mfma_f32_16x16x32_bf16 v[94:97], v[98:101], v[176:179], v[94:97]
	v_mfma_f32_16x16x32_bf16 v[86:89], v[98:101], v[184:187], v[86:89]
	v_mfma_f32_16x16x32_bf16 v[78:81], v[98:101], v[192:195], v[78:81]
	v_mfma_f32_16x16x32_bf16 v[70:73], v[98:101], v[202:205], v[70:73]
	v_mfma_f32_16x16x32_bf16 v[94:97], v[106:109], v[180:183], v[94:97]
	v_mfma_f32_16x16x32_bf16 v[90:93], v[114:117], v[176:179], v[90:93]
	v_mfma_f32_16x16x32_bf16 v[86:89], v[106:109], v[188:191], v[86:89]
	v_mfma_f32_16x16x32_bf16 v[82:85], v[114:117], v[184:187], v[82:85]
	v_mfma_f32_16x16x32_bf16 v[78:81], v[106:109], v[196:199], v[78:81]
	v_mfma_f32_16x16x32_bf16 v[74:77], v[114:117], v[192:195], v[74:77]
	v_mfma_f32_16x16x32_bf16 v[70:73], v[106:109], v[206:209], v[70:73]
	v_mfma_f32_16x16x32_bf16 v[66:69], v[114:117], v[202:205], v[66:69]
	v_mfma_f32_16x16x32_bf16 v[154:157], v[122:125], v[180:183], v[90:93]
	v_mfma_f32_16x16x32_bf16 v[176:179], v[122:125], v[188:191], v[82:85]
	v_mfma_f32_16x16x32_bf16 v[180:183], v[122:125], v[196:199], v[74:77]
	v_mfma_f32_16x16x32_bf16 v[184:187], v[122:125], v[206:209], v[66:69]
	s_setprio 0
	s_barrier
	s_nop 1
	ds_read_b128 v[66:69], v147 offset:16384
	ds_read_b128 v[74:77], v147 offset:17408
	ds_read_b128 v[82:85], v146 offset:16384
	ds_read_b128 v[90:93], v146 offset:17408
	ds_read_b128 v[188:191], v145 offset:16384
	ds_read_b128 v[192:195], v145 offset:17408
	ds_read_b128 v[196:199], v144 offset:16384
	ds_read_b128 v[202:205], v144 offset:17408
	s_waitcnt vmcnt(4)
	s_barrier
	s_waitcnt lgkmcnt(0)
	s_setprio 1
	s_waitcnt lgkmcnt(0)
	v_mfma_f32_16x16x32_bf16 v[62:65], v[150:153], v[66:69], v[62:65]
	v_mfma_f32_16x16x32_bf16 v[54:57], v[150:153], v[82:85], v[54:57]
	v_mfma_f32_16x16x32_bf16 v[46:49], v[150:153], v[188:191], v[46:49]
	v_mfma_f32_16x16x32_bf16 v[38:41], v[150:153], v[196:199], v[38:41]
	v_mfma_f32_16x16x32_bf16 v[62:65], v[164:167], v[74:77], v[62:65]
	v_mfma_f32_16x16x32_bf16 v[58:61], v[168:171], v[66:69], v[58:61]
	v_mfma_f32_16x16x32_bf16 v[54:57], v[164:167], v[90:93], v[54:57]
	v_mfma_f32_16x16x32_bf16 v[50:53], v[168:171], v[82:85], v[50:53]
	v_mfma_f32_16x16x32_bf16 v[46:49], v[164:167], v[192:195], v[46:49]
	v_mfma_f32_16x16x32_bf16 v[42:45], v[168:171], v[188:191], v[42:45]
	v_mfma_f32_16x16x32_bf16 v[38:41], v[164:167], v[202:205], v[38:41]
	v_mfma_f32_16x16x32_bf16 v[34:37], v[168:171], v[196:199], v[34:37]
	v_mfma_f32_16x16x32_bf16 v[206:209], v[172:175], v[74:77], v[58:61]
	v_mfma_f32_16x16x32_bf16 v[240:243], v[172:175], v[90:93], v[50:53]
	v_mfma_f32_16x16x32_bf16 v[244:247], v[172:175], v[192:195], v[42:45]
	v_mfma_f32_16x16x32_bf16 v[150:153], v[172:175], v[202:205], v[34:37]
	s_setprio 0
	s_setprio 1
	v_mfma_f32_16x16x32_bf16 v[30:33], v[98:101], v[66:69], v[30:33]
	v_mfma_f32_16x16x32_bf16 v[22:25], v[98:101], v[82:85], v[22:25]
	v_mfma_f32_16x16x32_bf16 v[14:17], v[98:101], v[188:191], v[14:17]
	v_mfma_f32_16x16x32_bf16 v[6:9], v[98:101], v[196:199], v[6:9]
	v_mfma_f32_16x16x32_bf16 v[30:33], v[106:109], v[74:77], v[30:33]
	v_mfma_f32_16x16x32_bf16 v[26:29], v[114:117], v[66:69], v[26:29]
	v_mfma_f32_16x16x32_bf16 v[22:25], v[106:109], v[90:93], v[22:25]
	v_mfma_f32_16x16x32_bf16 v[18:21], v[114:117], v[82:85], v[18:21]
	v_mfma_f32_16x16x32_bf16 v[14:17], v[106:109], v[192:195], v[14:17]
	v_mfma_f32_16x16x32_bf16 v[10:13], v[114:117], v[188:191], v[10:13]
	v_mfma_f32_16x16x32_bf16 v[6:9], v[106:109], v[202:205], v[6:9]
	v_mfma_f32_16x16x32_bf16 v[2:5], v[114:117], v[196:199], v[2:5]
	v_mfma_f32_16x16x32_bf16 v[162:165], v[122:125], v[74:77], v[26:29]
	v_mfma_f32_16x16x32_bf16 v[166:169], v[122:125], v[90:93], v[18:21]
	v_mfma_f32_16x16x32_bf16 v[170:173], v[122:125], v[192:195], v[10:13]
	v_mfma_f32_16x16x32_bf16 v[188:191], v[122:125], v[202:205], v[2:5]
	s_setprio 0
	s_barrier
	s_nop 1
	ds_read_b128 v[2:5], v149
	ds_read_b128 v[10:13], v149 offset:1024
	ds_read_b128 v[18:21], v149 offset:2048
	ds_read_b128 v[26:29], v149 offset:3072
	ds_read_b128 v[34:37], v147 offset:32768
	ds_read_b128 v[42:45], v147 offset:33792
	ds_read_b128 v[50:53], v146 offset:32768
	ds_read_b128 v[58:61], v146 offset:33792
	ds_read_b128 v[66:69], v145 offset:32768
	ds_read_b128 v[192:195], v145 offset:33792
	ds_read_b128 v[196:199], v144 offset:32768
	ds_read_b128 v[202:205], v144 offset:33792
	s_waitcnt vmcnt(2)
	s_barrier
; #define LDA(dst, b, h) for (int m = 0; m < 4; ++m) for (int k = 0; k < 2; ++k) \
;     dst[m][k] = *reinterpret_cast<const bf16x8*>((char*)SA(b, h) + lds_byte(wr * 64 + m * 16 + fr, k * 32 + fq * 8))
; #define LDB(dst, b, h) for (int n = 0; n < 2; ++n) for (int k = 0; k < 2; ++k) \
;     dst[n][k] = *reinterpret_cast<const bf16x8*>((char*)SB(b, h) + lds_byte(wc * 32 + n * 16 + fr, k * 32 + fq * 8))
; #define MMA(ai, bj, At_, Bt_) do { __builtin_amdgcn_s_setprio(1); \
;     for (int m = 0; m < 4; ++m) for (int n = 0; n < 2; ++n) for (int k = 0; k < 2; ++k) \
;       acc[ai][bj][m][n] = __builtin_amdgcn_mfma_f32_16x16x32_bf16(At_[m][k], Bt_[n][k], acc[ai][bj][m][n], 0, 0, 0); \
;     __builtin_amdgcn_s_setprio(0); } while (0)
; #define WAIT_V(n) asm volatile("s_waitcnt vmcnt(" #n ")" ::: "memory")
; #define WAIT_L(n) asm volatile("s_waitcnt lgkmcnt(" #n ")" ::: "memory")
; #define BAR __builtin_amdgcn_s_barrier()
; #define SCHED __builtin_amdgcn_sched_barrier(0)
; template <int EPI>
; __device__ __forceinline__ void gemm_tile(const GemmArgs& g, int brow, int bcol, int parity, bool first, bool nvalid, int nbrow, int nbcol) {
;     ...
;     LDA(At, 0, 1); WAIT_V(4); BAR; WAIT_L(0); MMA(1, 0, At, B0); MMA(1, 1, At, B1); BAR; }
;   { LDB(B0, 1, 0); LDA(At, 1, 0); WAIT_V(2); BAR; WAIT_L(0); MMA(0, 0, At, B0); BAR;
;     LDB(B1, 1, 1); WAIT_V(0); BAR; WAIT_L(0); MMA(0, 1, At, B1); BAR; SCHED;
;     LDA(At, 1, 1); BAR; WAIT_L(0); MMA(1, 0, At, B0); MMA(1, 1, At, B1); BAR; }
;   if (wr == 0) BAR;
	s_waitcnt lgkmcnt(0)
	s_setprio 1
	s_waitcnt lgkmcnt(0)
	v_mfma_f32_16x16x32_bf16 v[74:77], v[2:5], v[34:37], v[126:129]
	v_mfma_f32_16x16x32_bf16 v[122:125], v[10:13], v[42:45], v[74:77]
	v_mfma_f32_16x16x32_bf16 v[74:77], v[18:21], v[34:37], v[216:219]
	v_mfma_f32_16x16x32_bf16 v[126:129], v[26:29], v[42:45], v[74:77]
	v_mfma_f32_16x16x32_bf16 v[74:77], v[2:5], v[50:53], v[118:121]
	v_mfma_f32_16x16x32_bf16 v[114:117], v[10:13], v[58:61], v[74:77]
	v_mfma_f32_16x16x32_bf16 v[74:77], v[18:21], v[50:53], v[228:231]
	v_mfma_f32_16x16x32_bf16 v[118:121], v[26:29], v[58:61], v[74:77]
	v_mfma_f32_16x16x32_bf16 v[74:77], v[2:5], v[66:69], v[110:113]
	v_mfma_f32_16x16x32_bf16 v[106:109], v[10:13], v[192:195], v[74:77]
	v_mfma_f32_16x16x32_bf16 v[74:77], v[18:21], v[66:69], v[232:235]
	v_mfma_f32_16x16x32_bf16 v[110:113], v[26:29], v[192:195], v[74:77]
	v_mfma_f32_16x16x32_bf16 v[74:77], v[2:5], v[196:199], v[102:105]
	v_mfma_f32_16x16x32_bf16 v[98:101], v[10:13], v[202:205], v[74:77]
	v_mfma_f32_16x16x32_bf16 v[74:77], v[18:21], v[196:199], v[236:239]
	v_mfma_f32_16x16x32_bf16 v[102:105], v[26:29], v[202:205], v[74:77]
	s_setprio 0
	s_barrier
	ds_read_b128 v[216:219], v148
	ds_read_b128 v[228:231], v148 offset:1024
	ds_read_b128 v[232:235], v148 offset:2048
	ds_read_b128 v[236:239], v148 offset:3072
	s_waitcnt vmcnt(0)
	s_barrier
	s_waitcnt lgkmcnt(0)
	s_setprio 1
	s_waitcnt lgkmcnt(0)
	v_mfma_f32_16x16x32_bf16 v[74:77], v[216:219], v[34:37], v[94:97]
	v_mfma_f32_16x16x32_bf16 v[34:37], v[232:235], v[34:37], v[154:157]
	v_mfma_f32_16x16x32_bf16 v[94:97], v[236:239], v[42:45], v[34:37]
	v_mfma_f32_16x16x32_bf16 v[34:37], v[216:219], v[50:53], v[86:89]
	v_mfma_f32_16x16x32_bf16 v[82:85], v[228:231], v[58:61], v[34:37]
	v_mfma_f32_16x16x32_bf16 v[34:37], v[232:235], v[50:53], v[176:179]
	v_mfma_f32_16x16x32_bf16 v[86:89], v[236:239], v[58:61], v[34:37]
	v_mfma_f32_16x16x32_bf16 v[34:37], v[216:219], v[66:69], v[78:81]
	v_mfma_f32_16x16x32_bf16 v[90:93], v[228:231], v[42:45], v[74:77]
	v_mfma_f32_16x16x32_bf16 v[74:77], v[228:231], v[192:195], v[34:37]
	v_mfma_f32_16x16x32_bf16 v[34:37], v[232:235], v[66:69], v[180:183]
	v_mfma_f32_16x16x32_bf16 v[78:81], v[236:239], v[192:195], v[34:37]
	v_mfma_f32_16x16x32_bf16 v[34:37], v[216:219], v[196:199], v[70:73]
	v_mfma_f32_16x16x32_bf16 v[66:69], v[228:231], v[202:205], v[34:37]
	v_mfma_f32_16x16x32_bf16 v[34:37], v[232:235], v[196:199], v[184:187]
	v_mfma_f32_16x16x32_bf16 v[70:73], v[236:239], v[202:205], v[34:37]
	s_setprio 0
	s_barrier
	ds_read_b128 v[154:157], v147 offset:49152
	ds_read_b128 v[174:177], v147 offset:50176
	ds_read_b128 v[178:181], v146 offset:49152
	ds_read_b128 v[146:149], v146 offset:50176
	ds_read_b128 v[182:185], v145 offset:49152
	ds_read_b128 v[192:195], v145 offset:50176
	ds_read_b128 v[196:199], v144 offset:49152
	ds_read_b128 v[202:205], v144 offset:50176
	s_barrier
	s_waitcnt lgkmcnt(0)
	s_setprio 1
	s_waitcnt lgkmcnt(0)
	v_mfma_f32_16x16x32_bf16 v[34:37], v[2:5], v[154:157], v[62:65]
	v_mfma_f32_16x16x32_bf16 v[58:61], v[10:13], v[174:177], v[34:37]
	v_mfma_f32_16x16x32_bf16 v[34:37], v[18:21], v[154:157], v[206:209]
	v_mfma_f32_16x16x32_bf16 v[62:65], v[26:29], v[174:177], v[34:37]
	v_mfma_f32_16x16x32_bf16 v[34:37], v[2:5], v[178:181], v[54:57]
	v_mfma_f32_16x16x32_bf16 v[50:53], v[10:13], v[146:149], v[34:37]
	v_mfma_f32_16x16x32_bf16 v[34:37], v[18:21], v[178:181], v[240:243]
	v_mfma_f32_16x16x32_bf16 v[54:57], v[26:29], v[146:149], v[34:37]
	v_mfma_f32_16x16x32_bf16 v[34:37], v[2:5], v[182:185], v[46:49]
	v_mfma_f32_16x16x32_bf16 v[42:45], v[10:13], v[192:195], v[34:37]
	v_mfma_f32_16x16x32_bf16 v[34:37], v[18:21], v[182:185], v[244:247]
	v_mfma_f32_16x16x32_bf16 v[2:5], v[2:5], v[196:199], v[38:41]
	v_mfma_f32_16x16x32_bf16 v[46:49], v[26:29], v[192:195], v[34:37]
	v_mfma_f32_16x16x32_bf16 v[34:37], v[10:13], v[202:205], v[2:5]
	v_mfma_f32_16x16x32_bf16 v[2:5], v[18:21], v[196:199], v[150:153]
	v_mfma_f32_16x16x32_bf16 v[38:41], v[26:29], v[202:205], v[2:5]
	s_setprio 0
	s_setprio 1
	v_mfma_f32_16x16x32_bf16 v[2:5], v[216:219], v[154:157], v[30:33]
	v_mfma_f32_16x16x32_bf16 v[26:29], v[228:231], v[174:177], v[2:5]
	v_mfma_f32_16x16x32_bf16 v[2:5], v[232:235], v[154:157], v[162:165]
	v_mfma_f32_16x16x32_bf16 v[30:33], v[236:239], v[174:177], v[2:5]
	v_mfma_f32_16x16x32_bf16 v[2:5], v[216:219], v[178:181], v[22:25]
	v_mfma_f32_16x16x32_bf16 v[18:21], v[228:231], v[146:149], v[2:5]
	v_mfma_f32_16x16x32_bf16 v[2:5], v[232:235], v[178:181], v[166:169]
	v_mfma_f32_16x16x32_bf16 v[22:25], v[236:239], v[146:149], v[2:5]
	v_mfma_f32_16x16x32_bf16 v[2:5], v[216:219], v[182:185], v[14:17]
	v_mfma_f32_16x16x32_bf16 v[10:13], v[228:231], v[192:195], v[2:5]
	v_mfma_f32_16x16x32_bf16 v[2:5], v[232:235], v[182:185], v[170:173]
	v_mfma_f32_16x16x32_bf16 v[14:17], v[236:239], v[192:195], v[2:5]
	v_mfma_f32_16x16x32_bf16 v[2:5], v[216:219], v[196:199], v[6:9]
	v_mfma_f32_16x16x32_bf16 v[6:9], v[232:235], v[196:199], v[188:191]
	v_mfma_f32_16x16x32_bf16 v[2:5], v[228:231], v[202:205], v[2:5]
	v_mfma_f32_16x16x32_bf16 v[6:9], v[236:239], v[202:205], v[6:9]
	s_setprio 0
	s_movk_i32 s0, 0x100
	v_cmp_gt_u32_e32 vcc, s0, v138
	s_barrier
	s_and_saveexec_b64 s[0:1], vcc
	s_cbranch_execz .LBB0_643
	s_barrier

; #define WAIT_V(n) asm volatile("s_waitcnt vmcnt(" #n ")" ::: "memory")
; template <int EPI>
; __device__ __forceinline__ void gemm_tile(const GemmArgs& g, int brow, int bcol, int parity, bool first, bool nvalid, int nbrow, int nbcol) {
;     ...
;   if (first) { WAIT_V(4); } else { WAIT_V(0); }
.LBB0_647:
	s_waitcnt vmcnt(2)
	s_cbranch_execz .LBB0_636
	s_branch .LBB0_637
